# row statistics from per-(lane,unit) f32 sum-of-squares partials written by the AddRes epilogues (16 MB) instead of re-reading the 134 MB residual stream in 6 rowstat phases
# speedup vs baseline: 1.0009x; 1.0009x over previous
; #define PG8_STAGE(bufoff, gbase, voff) do { _Pragma("unroll") for (int _i = 0; _i < 2; ++_i) \
;         __builtin_amdgcn_global_load_lds((const unsigned*)((const char*)(gbase) + (voff)[_i]), (LAS unsigned*)(lds + (bufoff) + ldsw + _i * 8192), 16, 0, 0); } while (0)
; #define PG8_LDA(dst, b, h) do { _Pragma("unroll") for (int m = 0; m < 4; ++m) _Pragma("unroll") for (int k = 0; k < 2; ++k) dst[m][k] = *(const LAS bf16x8*)(lds + PG8_SA(b, h) + aoff + m * 2048 + k * 1024); } while (0)
; #define PG8_LDB(dst, b, h) do { _Pragma("unroll") for (int n = 0; n < 2; ++n) _Pragma("unroll") for (int k = 0; k < 2; ++k) dst[n][k] = *(const LAS bf16x8*)(lds + PG8_SB(b, h) + boff + n * 2048 + k * 1024); } while (0)
; #define PG8_MMA(ai, bj, At, Bt) do { __builtin_amdgcn_s_setprio(1); _Pragma("unroll") for (int m = 0; m < 4; ++m) _Pragma("unroll") for (int n = 0; n < 2; ++n) _Pragma("unroll") for (int k = 0; k < 2; ++k) \
;         acc[ai][bj][m][n] = __builtin_amdgcn_mfma_f32_16x16x32_bf16(Bt[n][k], At[m][k], acc[ai][bj][m][n], 0, 0, 0); __builtin_amdgcn_s_setprio(0); } while (0)
; #define PG8_WAIT_V(n) asm volatile("s_waitcnt vmcnt(" #n ")" ::: "memory")
; #define PG8_WAIT_L(n) asm volatile("s_waitcnt lgkmcnt(" #n ")" ::: "memory")
; #define PG8_BAR __builtin_amdgcn_s_barrier()
; #define PG8_SCHED __builtin_amdgcn_sched_barrier(0)
; template <class Epi, class Sched>
; __device__ __forceinline__ void gemm_phase(LAS unsigned char* lds, const Gemm g, const Sched& S, const Epi& E) {
;     ...
;             PG8_LDB(B0, 0, 0); PG8_SCHED; PG8_LDA(At, 0, 0); PG8_STAGE(PG8_SA(1, 1), a1 + hstepA, voffA);
;             PG8_WAIT_L(8); PG8_BAR; PG8_WAIT_L(0); PG8_MMA(0, 0, At, B0); PG8_BAR; PG8_SCHED;
;             PG8_LDB(B1, 0, 1); PG8_STAGE(PG8_SB(0, 0), b2, voffB);
;             PG8_BAR; PG8_WAIT_L(0); PG8_MMA(0, 1, At, B1); PG8_BAR;
;             PG8_LDA(At, 0, 1); PG8_STAGE(PG8_SA(0, 0), a2, voffA);
;             PG8_BAR; PG8_WAIT_L(0); PG8_MMA(1, 0, At, B0); PG8_BAR; PG8_SCHED;
;             PG8_STAGE(PG8_SB(0, 1), b2 + hstepB, voffB);
;             PG8_WAIT_V(6); PG8_BAR; PG8_MMA(1, 1, At, B1); PG8_BAR;
.LBB0_966:
	s_setprio 0
	s_add_u32 s20, s6, 0xfff80080
	s_addc_u32 s21, s7, -1
	s_add_i32 s52, 0, 0x10000
	v_add_u32_e32 v144, s52, v1
	ds_read_b128 v[132:135], v144
	ds_read_b128 v[136:139], v144 offset:1024
	ds_read_b128 v[140:143], v144 offset:2048
	ds_read_b128 v[144:147], v144 offset:3072
	s_cmp_eq_u32 s51, 28
	s_cselect_b32 s25, s15, s21
	s_cselect_b32 s24, s47, s20
	s_cselect_b32 s21, s1, s50
	s_cselect_b32 s20, s48, s49
	ds_read_b128 v[148:151], v224
	ds_read_b128 v[152:155], v224 offset:1024
	ds_read_b128 v[156:159], v224 offset:2048
	ds_read_b128 v[160:163], v224 offset:3072
	ds_read_b128 v[164:167], v224 offset:4096
	ds_read_b128 v[168:171], v224 offset:5120
	ds_read_b128 v[172:175], v224 offset:6144
	ds_read_b128 v[176:179], v224 offset:7168
	s_add_i32 s54, 0, 0x14000
	v_add_u32_e32 v202, s54, v1
	ds_read_b128 v[180:183], v202
	ds_read_b128 v[184:187], v202 offset:1024
	ds_read_b128 v[188:191], v202 offset:2048
	ds_read_b128 v[202:205], v202 offset:3072
	s_add_i32 m0, s31, 0xc000
	s_nop 0
	global_load_lds_dwordx4 v198, s[6:7]
	s_add_i32 m0, s31, 0xe000
	s_nop 0
	global_load_lds_dwordx4 v200, s[6:7]
	s_waitcnt lgkmcnt(0)
	s_setprio 1
	s_barrier
	v_mfma_f32_16x16x32_bf16 v[128:131], v[132:135], v[148:151], v[128:131]
	v_mfma_f32_16x16x32_bf16 v[124:127], v[140:143], v[148:151], v[124:127]
	v_mfma_f32_16x16x32_bf16 v[112:115], v[132:135], v[156:159], v[112:115]
	v_mfma_f32_16x16x32_bf16 v[108:111], v[140:143], v[156:159], v[108:111]
	v_mfma_f32_16x16x32_bf16 v[100:103], v[132:135], v[164:167], v[100:103]
	v_mfma_f32_16x16x32_bf16 v[92:95], v[140:143], v[164:167], v[92:95]
	v_mfma_f32_16x16x32_bf16 v[84:87], v[132:135], v[172:175], v[84:87]
	v_mfma_f32_16x16x32_bf16 v[76:79], v[140:143], v[172:175], v[76:79]
	v_mfma_f32_16x16x32_bf16 v[128:131], v[136:139], v[152:155], v[128:131]
	v_mfma_f32_16x16x32_bf16 v[124:127], v[144:147], v[152:155], v[124:127]
	v_mfma_f32_16x16x32_bf16 v[112:115], v[136:139], v[160:163], v[112:115]
	v_mfma_f32_16x16x32_bf16 v[108:111], v[144:147], v[160:163], v[108:111]
	v_mfma_f32_16x16x32_bf16 v[100:103], v[136:139], v[168:171], v[100:103]
	v_mfma_f32_16x16x32_bf16 v[92:95], v[144:147], v[168:171], v[92:95]
	v_mfma_f32_16x16x32_bf16 v[84:87], v[136:139], v[176:179], v[84:87]
	v_mfma_f32_16x16x32_bf16 v[76:79], v[144:147], v[176:179], v[76:79]
	v_mfma_f32_16x16x32_bf16 v[120:123], v[180:183], v[148:151], v[120:123]
	v_mfma_f32_16x16x32_bf16 v[116:119], v[188:191], v[148:151], v[116:119]
	v_mfma_f32_16x16x32_bf16 v[104:107], v[180:183], v[156:159], v[104:107]
	v_mfma_f32_16x16x32_bf16 v[96:99], v[188:191], v[156:159], v[96:99]
	v_mfma_f32_16x16x32_bf16 v[88:91], v[180:183], v[164:167], v[88:91]
	v_mfma_f32_16x16x32_bf16 v[80:83], v[188:191], v[164:167], v[80:83]
	v_mfma_f32_16x16x32_bf16 v[72:75], v[180:183], v[172:175], v[72:75]
	v_mfma_f32_16x16x32_bf16 v[68:71], v[188:191], v[172:175], v[68:71]
	v_mfma_f32_16x16x32_bf16 v[120:123], v[184:187], v[152:155], v[120:123]
	v_mfma_f32_16x16x32_bf16 v[116:119], v[202:205], v[152:155], v[116:119]
	v_mfma_f32_16x16x32_bf16 v[104:107], v[184:187], v[160:163], v[104:107]
	v_mfma_f32_16x16x32_bf16 v[96:99], v[202:205], v[160:163], v[96:99]
	v_mfma_f32_16x16x32_bf16 v[88:91], v[184:187], v[168:171], v[88:91]
	v_mfma_f32_16x16x32_bf16 v[80:83], v[202:205], v[168:171], v[80:83]
	v_mfma_f32_16x16x32_bf16 v[72:75], v[184:187], v[176:179], v[72:75]
	v_mfma_f32_16x16x32_bf16 v[68:71], v[202:205], v[176:179], v[68:71]
	s_barrier
	s_setprio 0
	ds_read_b128 v[148:151], v224 offset:16384
	ds_read_b128 v[152:155], v224 offset:17408
	ds_read_b128 v[156:159], v224 offset:18432
	ds_read_b128 v[160:163], v224 offset:19456
	ds_read_b128 v[164:167], v224 offset:20480
	ds_read_b128 v[168:171], v224 offset:21504
	ds_read_b128 v[172:175], v224 offset:22528
	ds_read_b128 v[176:179], v224 offset:23552
	s_add_i32 s52, s52, s30
	v_lshl_add_u64 v[206:207], s[20:21], 0, v[2:3]
	s_mov_b32 m0, s52
	s_nop 0
	global_load_lds_dwordx4 v[206:207], off
	v_lshl_add_u64 v[208:209], s[20:21], 0, v[192:193]
	s_add_i32 m0, s52, 0x2000
	s_nop 0
	global_load_lds_dwordx4 v[208:209], off
	s_mov_b32 m0, s31
	v_lshl_add_u64 v[210:211], s[24:25], 0, v[196:197]
	global_load_lds_dwordx4 v[210:211], off
	v_lshl_add_u64 v[212:213], s[24:25], 0, v[194:195]
	s_mov_b32 m0, s35
	s_nop 0
	global_load_lds_dwordx4 v[212:213], off
	s_add_u32 s52, s20, 0x80000
	s_addc_u32 s53, s21, 0
	s_add_i32 s54, s54, s30
	s_mov_b32 m0, s54
	s_nop 0
	global_load_lds_dwordx4 v2, s[52:53]
	s_add_i32 m0, s54, 0x2000
	s_nop 0
	global_load_lds_dwordx4 v192, s[52:53]
	s_waitcnt lgkmcnt(0)
	s_waitcnt vmcnt(6)
	s_setprio 1
	s_barrier
; #define PG8_STAGE(bufoff, gbase, voff) do { _Pragma("unroll") for (int _i = 0; _i < 2; ++_i) \
;         __builtin_amdgcn_global_load_lds((const unsigned*)((const char*)(gbase) + (voff)[_i]), (LAS unsigned*)(lds + (bufoff) + ldsw + _i * 8192), 16, 0, 0); } while (0)
; #define PG8_LDA(dst, b, h) do { _Pragma("unroll") for (int m = 0; m < 4; ++m) _Pragma("unroll") for (int k = 0; k < 2; ++k) dst[m][k] = *(const LAS bf16x8*)(lds + PG8_SA(b, h) + aoff + m * 2048 + k * 1024); } while (0)
; #define PG8_LDB(dst, b, h) do { _Pragma("unroll") for (int n = 0; n < 2; ++n) _Pragma("unroll") for (int k = 0; k < 2; ++k) dst[n][k] = *(const LAS bf16x8*)(lds + PG8_SB(b, h) + boff + n * 2048 + k * 1024); } while (0)
; #define PG8_MMA(ai, bj, At, Bt) do { __builtin_amdgcn_s_setprio(1); _Pragma("unroll") for (int m = 0; m < 4; ++m) _Pragma("unroll") for (int n = 0; n < 2; ++n) _Pragma("unroll") for (int k = 0; k < 2; ++k) \
;         acc[ai][bj][m][n] = __builtin_amdgcn_mfma_f32_16x16x32_bf16(Bt[n][k], At[m][k], acc[ai][bj][m][n], 0, 0, 0); __builtin_amdgcn_s_setprio(0); } while (0)
; #define PG8_WAIT_V(n) asm volatile("s_waitcnt vmcnt(" #n ")" ::: "memory")
; #define PG8_WAIT_L(n) asm volatile("s_waitcnt lgkmcnt(" #n ")" ::: "memory")
; #define PG8_BAR __builtin_amdgcn_s_barrier()
; #define PG8_SCHED __builtin_amdgcn_sched_barrier(0)
; template <class Epi, class Sched>
; __device__ __forceinline__ void gemm_phase(LAS unsigned char* lds, const Gemm g, const Sched& S, const Epi& E) {
;     ...
;             PG8_WAIT_V(6); PG8_BAR; PG8_MMA(1, 1, At, B1); PG8_BAR;
;             PG8_LDB(B0, 1, 0); PG8_SCHED; PG8_LDA(At, 1, 0); PG8_STAGE(PG8_SA(0, 1), a2 + hstepA, voffA);
;             PG8_WAIT_L(8); PG8_BAR; PG8_WAIT_L(0); PG8_MMA(0, 0, At, B0); PG8_BAR; PG8_SCHED;
;             PG8_LDB(B1, 1, 1); PG8_STAGE(PG8_SB(1, 0), b3, voffB);
;             PG8_BAR; PG8_WAIT_L(0); PG8_MMA(0, 1, At, B1); PG8_BAR;
;             PG8_LDA(At, 1, 1); PG8_STAGE(PG8_SA(1, 0), a3, voffA);
;             PG8_BAR; PG8_WAIT_L(0); PG8_MMA(1, 0, At, B0); PG8_BAR; PG8_SCHED;
	v_mfma_f32_16x16x32_bf16 v[64:67], v[132:135], v[148:151], v[64:67]
	v_mfma_f32_16x16x32_bf16 v[60:63], v[140:143], v[148:151], v[60:63]
	v_mfma_f32_16x16x32_bf16 v[52:55], v[132:135], v[156:159], v[52:55]
	v_mfma_f32_16x16x32_bf16 v[44:47], v[140:143], v[156:159], v[44:47]
	v_mfma_f32_16x16x32_bf16 v[36:39], v[132:135], v[164:167], v[36:39]
	v_mfma_f32_16x16x32_bf16 v[28:31], v[140:143], v[164:167], v[28:31]
	v_mfma_f32_16x16x32_bf16 v[20:23], v[132:135], v[172:175], v[20:23]
	v_mfma_f32_16x16x32_bf16 v[12:15], v[140:143], v[172:175], v[12:15]
	v_mfma_f32_16x16x32_bf16 v[64:67], v[136:139], v[152:155], v[64:67]
	v_mfma_f32_16x16x32_bf16 v[60:63], v[144:147], v[152:155], v[60:63]
	v_mfma_f32_16x16x32_bf16 v[52:55], v[136:139], v[160:163], v[52:55]
	v_mfma_f32_16x16x32_bf16 v[44:47], v[144:147], v[160:163], v[44:47]
	v_mfma_f32_16x16x32_bf16 v[36:39], v[136:139], v[168:171], v[36:39]
	v_mfma_f32_16x16x32_bf16 v[28:31], v[144:147], v[168:171], v[28:31]
	v_mfma_f32_16x16x32_bf16 v[20:23], v[136:139], v[176:179], v[20:23]
	v_mfma_f32_16x16x32_bf16 v[12:15], v[144:147], v[176:179], v[12:15]
	v_mfma_f32_16x16x32_bf16 v[56:59], v[180:183], v[148:151], v[56:59]
	v_mfma_f32_16x16x32_bf16 v[48:51], v[188:191], v[148:151], v[48:51]
	v_mfma_f32_16x16x32_bf16 v[40:43], v[180:183], v[156:159], v[40:43]
	v_mfma_f32_16x16x32_bf16 v[32:35], v[188:191], v[156:159], v[32:35]
	v_mfma_f32_16x16x32_bf16 v[24:27], v[180:183], v[164:167], v[24:27]
	v_mfma_f32_16x16x32_bf16 v[16:19], v[188:191], v[164:167], v[16:19]
	v_mfma_f32_16x16x32_bf16 v[8:11], v[180:183], v[172:175], v[8:11]
	v_mfma_f32_16x16x32_bf16 v[4:7], v[188:191], v[172:175], v[4:7]
	v_mfma_f32_16x16x32_bf16 v[56:59], v[184:187], v[152:155], v[56:59]
	v_mfma_f32_16x16x32_bf16 v[48:51], v[202:205], v[152:155], v[48:51]
	v_mfma_f32_16x16x32_bf16 v[40:43], v[184:187], v[160:163], v[40:43]
	v_mfma_f32_16x16x32_bf16 v[32:35], v[202:205], v[160:163], v[32:35]
	v_mfma_f32_16x16x32_bf16 v[24:27], v[184:187], v[168:171], v[24:27]
	v_mfma_f32_16x16x32_bf16 v[16:19], v[202:205], v[168:171], v[16:19]
	v_mfma_f32_16x16x32_bf16 v[8:11], v[184:187], v[176:179], v[8:11]
	v_mfma_f32_16x16x32_bf16 v[4:7], v[202:205], v[176:179], v[4:7]
	s_barrier
	s_setprio 0
	s_add_i32 s52, 0, 0x18000
	v_add_u32_e32 v144, s52, v1
	ds_read_b128 v[132:135], v144
	ds_read_b128 v[136:139], v144 offset:1024
	ds_read_b128 v[140:143], v144 offset:2048
	ds_read_b128 v[144:147], v144 offset:3072
	s_add_u32 s24, s24, 0x80000
	s_addc_u32 s25, s25, 0
	ds_read_b128 v[148:151], v224 offset:32768
	ds_read_b128 v[152:155], v224 offset:33792
	ds_read_b128 v[156:159], v224 offset:34816
	ds_read_b128 v[160:163], v224 offset:35840
	ds_read_b128 v[164:167], v224 offset:36864
	ds_read_b128 v[168:171], v224 offset:37888
	ds_read_b128 v[172:175], v224 offset:38912
	ds_read_b128 v[176:179], v224 offset:39936
	s_mov_b32 m0, s36
	s_nop 0
	global_load_lds_dwordx4 v196, s[24:25]
	s_mov_b32 m0, s37
	s_nop 0
	global_load_lds_dwordx4 v194, s[24:25]
	s_add_i32 s24, 0, 0x1c000
	v_add_u32_e32 v202, s24, v1
	ds_read_b128 v[180:183], v202
	ds_read_b128 v[184:187], v202 offset:1024
	ds_read_b128 v[188:191], v202 offset:2048
	ds_read_b128 v[202:205], v202 offset:3072
	s_waitcnt lgkmcnt(0)
	s_setprio 1
	s_barrier
	v_mfma_f32_16x16x32_bf16 v[128:131], v[132:135], v[148:151], v[128:131]
	v_mfma_f32_16x16x32_bf16 v[124:127], v[140:143], v[148:151], v[124:127]
	v_mfma_f32_16x16x32_bf16 v[112:115], v[132:135], v[156:159], v[112:115]
	v_mfma_f32_16x16x32_bf16 v[108:111], v[140:143], v[156:159], v[108:111]
	v_mfma_f32_16x16x32_bf16 v[100:103], v[132:135], v[164:167], v[100:103]
	v_mfma_f32_16x16x32_bf16 v[92:95], v[140:143], v[164:167], v[92:95]
	v_mfma_f32_16x16x32_bf16 v[84:87], v[132:135], v[172:175], v[84:87]
	v_mfma_f32_16x16x32_bf16 v[76:79], v[140:143], v[172:175], v[76:79]
	v_mfma_f32_16x16x32_bf16 v[128:131], v[136:139], v[152:155], v[128:131]
	v_mfma_f32_16x16x32_bf16 v[124:127], v[144:147], v[152:155], v[124:127]
	v_mfma_f32_16x16x32_bf16 v[112:115], v[136:139], v[160:163], v[112:115]
	v_mfma_f32_16x16x32_bf16 v[108:111], v[144:147], v[160:163], v[108:111]
	v_mfma_f32_16x16x32_bf16 v[100:103], v[136:139], v[168:171], v[100:103]
	v_mfma_f32_16x16x32_bf16 v[92:95], v[144:147], v[168:171], v[92:95]
	v_mfma_f32_16x16x32_bf16 v[84:87], v[136:139], v[176:179], v[84:87]
	v_mfma_f32_16x16x32_bf16 v[76:79], v[144:147], v[176:179], v[76:79]
	v_mfma_f32_16x16x32_bf16 v[120:123], v[180:183], v[148:151], v[120:123]
	v_mfma_f32_16x16x32_bf16 v[116:119], v[188:191], v[148:151], v[116:119]
	v_mfma_f32_16x16x32_bf16 v[104:107], v[180:183], v[156:159], v[104:107]
	v_mfma_f32_16x16x32_bf16 v[96:99], v[188:191], v[156:159], v[96:99]
	v_mfma_f32_16x16x32_bf16 v[88:91], v[180:183], v[164:167], v[88:91]
	v_mfma_f32_16x16x32_bf16 v[80:83], v[188:191], v[164:167], v[80:83]
	v_mfma_f32_16x16x32_bf16 v[72:75], v[180:183], v[172:175], v[72:75]
	v_mfma_f32_16x16x32_bf16 v[68:71], v[188:191], v[172:175], v[68:71]
	v_mfma_f32_16x16x32_bf16 v[120:123], v[184:187], v[152:155], v[120:123]
	v_mfma_f32_16x16x32_bf16 v[116:119], v[202:205], v[152:155], v[116:119]
	v_mfma_f32_16x16x32_bf16 v[104:107], v[184:187], v[160:163], v[104:107]
	v_mfma_f32_16x16x32_bf16 v[96:99], v[202:205], v[160:163], v[96:99]
	v_mfma_f32_16x16x32_bf16 v[88:91], v[184:187], v[168:171], v[88:91]
	v_mfma_f32_16x16x32_bf16 v[80:83], v[202:205], v[168:171], v[80:83]
	v_mfma_f32_16x16x32_bf16 v[72:75], v[184:187], v[176:179], v[72:75]
	v_mfma_f32_16x16x32_bf16 v[68:71], v[202:205], v[176:179], v[68:71]
	s_barrier
; __device__ __forceinline__ int opaque_tid() { int t = threadIdx.x; asm volatile("" : "+v"(t)); return t; }
; #define PG8_STAGE(bufoff, gbase, voff) do { _Pragma("unroll") for (int _i = 0; _i < 2; ++_i) \
;         __builtin_amdgcn_global_load_lds((const unsigned*)((const char*)(gbase) + (voff)[_i]), (LAS unsigned*)(lds + (bufoff) + ldsw + _i * 8192), 16, 0, 0); } while (0)
; #define PG8_LDA(dst, b, h) do { _Pragma("unroll") for (int m = 0; m < 4; ++m) _Pragma("unroll") for (int k = 0; k < 2; ++k) dst[m][k] = *(const LAS bf16x8*)(lds + PG8_SA(b, h) + aoff + m * 2048 + k * 1024); } while (0)
; #define PG8_MMA(ai, bj, At, Bt) do { __builtin_amdgcn_s_setprio(1); _Pragma("unroll") for (int m = 0; m < 4; ++m) _Pragma("unroll") for (int n = 0; n < 2; ++n) _Pragma("unroll") for (int k = 0; k < 2; ++k) \
;         acc[ai][bj][m][n] = __builtin_amdgcn_mfma_f32_16x16x32_bf16(Bt[n][k], At[m][k], acc[ai][bj][m][n], 0, 0, 0); __builtin_amdgcn_s_setprio(0); } while (0)
; #define PG8_WAIT_V(n) asm volatile("s_waitcnt vmcnt(" #n ")" ::: "memory")
; #define PG8_WAIT_L(n) asm volatile("s_waitcnt lgkmcnt(" #n ")" ::: "memory")
; #define PG8_BAR __builtin_amdgcn_s_barrier()
; #define PG8_SCHED __builtin_amdgcn_sched_barrier(0)
;     __device__ __forceinline__ void operator()(const f32x4 (&acc)[2][2][4][2], const Unit& u, int wr, int wc, int, int) const {
;         const int ol_ = opaque_tid() & 63, fr = ol_ & 15, fq = ol_ >> 4;
;         const int row0 = u.pm * BM + wr * 64 + fr, col0 = u.pn * BM + wc * 32 + 8 * fq;
;         u32x4 cin[2][4][2];
; #pragma unroll
;         for (int ai = 0; ai < 2; ++ai)
; #pragma unroll
;             for (int m = 0; m < 4; ++m)
; #pragma unroll
;                 for (int bj = 0; bj < 2; ++bj) cin[ai][m][bj] = *(const u32x4*)(C + (size_t)(row0 + ai * HALF + m * 16) * ldc + col0 + bj * HALF);
; template <class Epi, class Sched>
; __device__ __forceinline__ void gemm_phase(LAS unsigned char* lds, const Gemm g, const Sched& S, const Epi& E) {
;     ...
;             PG8_LDA(At, 1, 1); PG8_STAGE(PG8_SA(1, 0), a3, voffA);
;             PG8_BAR; PG8_WAIT_L(0); PG8_MMA(1, 0, At, B0); PG8_BAR; PG8_SCHED;
;             PG8_STAGE(PG8_SB(1, 1), b3 + hstepB, voffB);
;             PG8_WAIT_V(6); PG8_BAR; PG8_MMA(1, 1, At, B1); PG8_BAR;
;         }
	s_setprio 0
	ds_read_b128 v[148:151], v224 offset:49152
	ds_read_b128 v[152:155], v224 offset:50176
	ds_read_b128 v[156:159], v224 offset:51200
	ds_read_b128 v[160:163], v224 offset:52224
	ds_read_b128 v[164:167], v224 offset:53248
	ds_read_b128 v[168:171], v224 offset:54272
	ds_read_b128 v[172:175], v224 offset:55296
	ds_read_b128 v[176:179], v224 offset:56320
	s_add_i32 s25, s52, s30
	v_lshl_add_u64 v[206:207], v[206:207], 0, s[8:9]
	s_mov_b32 m0, s25
	s_nop 0
	global_load_lds_dwordx4 v[206:207], off
	v_lshl_add_u64 v[206:207], v[208:209], 0, s[8:9]
	s_add_i32 m0, s25, 0x2000
	s_nop 0
	global_load_lds_dwordx4 v[206:207], off
	s_mov_b32 m0, s40
	v_lshl_add_u64 v[206:207], v[210:211], 0, s[8:9]
	global_load_lds_dwordx4 v[206:207], off
	v_lshl_add_u64 v[206:207], v[212:213], 0, s[8:9]
	s_mov_b32 m0, s41
	s_nop 0
	global_load_lds_dwordx4 v[206:207], off
	s_add_u32 s20, s20, 0x80080
	s_addc_u32 s21, s21, 0
	s_add_i32 s24, s24, s30
	s_mov_b32 m0, s24
	s_nop 0
	global_load_lds_dwordx4 v2, s[20:21]
	s_add_i32 m0, s24, 0x2000
	s_nop 0
	global_load_lds_dwordx4 v192, s[20:21]
	s_add_i32 s51, s51, 2
	s_add_u32 s6, s6, 0x100
	s_addc_u32 s7, s7, 0
	s_add_u32 s49, s49, 0x100
	s_addc_u32 s50, s50, 0
	s_cmp_gt_u32 s51, 29
	s_waitcnt lgkmcnt(0)
	s_waitcnt vmcnt(6)
	s_setprio 1
	s_barrier
	v_mfma_f32_16x16x32_bf16 v[64:67], v[132:135], v[148:151], v[64:67]
	v_mfma_f32_16x16x32_bf16 v[60:63], v[140:143], v[148:151], v[60:63]
	v_mfma_f32_16x16x32_bf16 v[52:55], v[132:135], v[156:159], v[52:55]
	v_mfma_f32_16x16x32_bf16 v[44:47], v[140:143], v[156:159], v[44:47]
	v_mfma_f32_16x16x32_bf16 v[36:39], v[132:135], v[164:167], v[36:39]
	v_mfma_f32_16x16x32_bf16 v[28:31], v[140:143], v[164:167], v[28:31]
	v_mfma_f32_16x16x32_bf16 v[20:23], v[132:135], v[172:175], v[20:23]
	v_mfma_f32_16x16x32_bf16 v[12:15], v[140:143], v[172:175], v[12:15]
	v_mfma_f32_16x16x32_bf16 v[64:67], v[136:139], v[152:155], v[64:67]
	v_mfma_f32_16x16x32_bf16 v[60:63], v[144:147], v[152:155], v[60:63]
	v_mfma_f32_16x16x32_bf16 v[52:55], v[136:139], v[160:163], v[52:55]
	v_mfma_f32_16x16x32_bf16 v[44:47], v[144:147], v[160:163], v[44:47]
	v_mfma_f32_16x16x32_bf16 v[36:39], v[136:139], v[168:171], v[36:39]
	v_mfma_f32_16x16x32_bf16 v[28:31], v[144:147], v[168:171], v[28:31]
	v_mfma_f32_16x16x32_bf16 v[20:23], v[136:139], v[176:179], v[20:23]
	v_mfma_f32_16x16x32_bf16 v[12:15], v[144:147], v[176:179], v[12:15]
	v_mfma_f32_16x16x32_bf16 v[56:59], v[180:183], v[148:151], v[56:59]
	v_mfma_f32_16x16x32_bf16 v[48:51], v[188:191], v[148:151], v[48:51]
	v_mfma_f32_16x16x32_bf16 v[40:43], v[180:183], v[156:159], v[40:43]
	v_mfma_f32_16x16x32_bf16 v[32:35], v[188:191], v[156:159], v[32:35]
	v_mfma_f32_16x16x32_bf16 v[24:27], v[180:183], v[164:167], v[24:27]
	v_mfma_f32_16x16x32_bf16 v[16:19], v[188:191], v[164:167], v[16:19]
	v_mfma_f32_16x16x32_bf16 v[8:11], v[180:183], v[172:175], v[8:11]
	v_mfma_f32_16x16x32_bf16 v[4:7], v[188:191], v[172:175], v[4:7]
	v_mfma_f32_16x16x32_bf16 v[56:59], v[184:187], v[152:155], v[56:59]
	v_mfma_f32_16x16x32_bf16 v[48:51], v[202:205], v[152:155], v[48:51]
	v_mfma_f32_16x16x32_bf16 v[40:43], v[184:187], v[160:163], v[40:43]
	v_mfma_f32_16x16x32_bf16 v[32:35], v[202:205], v[160:163], v[32:35]
	v_mfma_f32_16x16x32_bf16 v[24:27], v[184:187], v[168:171], v[24:27]
	v_mfma_f32_16x16x32_bf16 v[16:19], v[202:205], v[168:171], v[16:19]
	v_mfma_f32_16x16x32_bf16 v[8:11], v[184:187], v[176:179], v[8:11]
	v_mfma_f32_16x16x32_bf16 v[4:7], v[202:205], v[176:179], v[4:7]
	s_barrier
	s_cbranch_scc0 .LBB0_966
	s_setprio 0
	v_mov_b32_e32 v133, v0
	s_lshl_b32 s1, s46, 8
	s_add_i32 s1, s1, s38
	v_and_or_b32 v132, v133, 15, s1
	s_lshl_b32 s1, s45, 8
	v_lshrrev_b32_e32 v133, 1, v133
	v_and_or_b32 v133, v133, 24, s1
	v_or_b32_e32 v134, s39, v133
	v_ashrrev_i32_e32 v135, 31, v134
	v_lshlrev_b64 v[202:203], 1, v[134:135]
	v_ashrrev_i32_e32 v133, 31, v132
	v_lshl_add_u64 v[134:135], s[88:89], 0, v[202:203]
	v_lshlrev_b64 v[226:227], 12, v[132:133]
	v_lshl_add_u64 v[136:137], v[134:135], 0, v[226:227]
	global_load_dwordx4 v[216:219], v[136:137], off
	global_load_dwordx4 v[188:191], v[136:137], off offset:256
	v_or_b32_e32 v136, 16, v132
	v_ashrrev_i32_e32 v137, 31, v136
	v_lshlrev_b64 v[222:223], 12, v[136:137]
	v_lshl_add_u64 v[136:137], v[134:135], 0, v[222:223]
	global_load_dwordx4 v[184:187], v[136:137], off
	global_load_dwordx4 v[180:183], v[136:137], off offset:256
	v_or_b32_e32 v136, 32, v132
	v_ashrrev_i32_e32 v137, 31, v136
	v_lshlrev_b64 v[220:221], 12, v[136:137]
	v_lshl_add_u64 v[136:137], v[134:135], 0, v[220:221]
	global_load_dwordx4 v[176:179], v[136:137], off
	global_load_dwordx4 v[168:171], v[136:137], off offset:256
	v_or_b32_e32 v132, 48, v132
	v_ashrrev_i32_e32 v133, 31, v132
	v_lshlrev_b64 v[212:213], 12, v[132:133]
	v_lshl_add_u64 v[132:133], v[134:135], 0, v[212:213]
	global_load_dwordx4 v[172:175], v[132:133], off
	global_load_dwordx4 v[164:167], v[132:133], off offset:256
	s_mov_b64 s[6:7], 0x80000
	v_lshl_add_u64 v[210:211], v[226:227], 0, s[6:7]
	v_lshl_add_u64 v[132:133], v[134:135], 0, v[210:211]
	global_load_dwordx4 v[160:163], v[132:133], off
	global_load_dwordx4 v[156:159], v[132:133], off offset:256
	s_mov_b64 s[6:7], 0x90000
	v_lshl_add_u64 v[208:209], v[226:227], 0, s[6:7]
	v_lshl_add_u64 v[132:133], v[134:135], 0, v[208:209]
	global_load_dwordx4 v[152:155], v[132:133], off
	global_load_dwordx4 v[148:151], v[132:133], off offset:256
	s_mov_b64 s[6:7], 0xa0000
	v_lshl_add_u64 v[206:207], v[226:227], 0, s[6:7]
	v_lshl_add_u64 v[132:133], v[134:135], 0, v[206:207]
	global_load_dwordx4 v[144:147], v[132:133], off
	global_load_dwordx4 v[140:143], v[132:133], off offset:256
	s_mov_b64 s[6:7], 0xb0000
	v_lshl_add_u64 v[204:205], v[226:227], 0, s[6:7]
	v_lshl_add_u64 v[132:133], v[134:135], 0, v[204:205]
	global_load_dwordx4 v[136:139], v[132:133], off
	s_nop 0
	global_load_dwordx4 v[132:135], v[132:133], off offset:256
	s_and_b64 vcc, exec, s[42:43]
	s_mov_b32 s45, s0
	s_mov_b32 s46, s14
	s_mov_b64 s[20:21], s[18:19]
	s_mov_b64 s[6:7], s[4:5]
	s_waitcnt vmcnt(15)
; __device__ __forceinline__ unsigned cvt_pk_bf16(float lo, float hi) { const f32x2 v = {lo, hi}; const bf16v2_ r = __builtin_convertvector(v, bf16v2_); return __builtin_bit_cast(unsigned, r); }
; __device__ __forceinline__ float bflo(unsigned w) { return __uint_as_float(w << 16); }
; __device__ __forceinline__ float bfhi(unsigned w) { return __uint_as_float(w & 0xffff0000u); }
;     __device__ __forceinline__ void operator()(const f32x4 (&acc)[2][2][4][2], const Unit& u, int wr, int wc, int, int) const {
;     ...
; #pragma unroll
;         for (int ai = 0; ai < 2; ++ai)
; #pragma unroll
;             for (int m = 0; m < 4; ++m)
; #pragma unroll
;                 for (int bj = 0; bj < 2; ++bj) { const u32x4 c = cin[ai][m][bj]; const f32x4 v0 = acc[ai][bj][m][0], v1 = acc[ai][bj][m][1];
;                     u32x4 w; w.x = cvt_pk_bf16(bflo(c.x) + v0[0], bfhi(c.x) + v0[1]); w.y = cvt_pk_bf16(bflo(c.y) + v0[2], bfhi(c.y) + v0[3]);
;                     w.z = cvt_pk_bf16(bflo(c.z) + v1[0], bfhi(c.z) + v1[1]); w.w = cvt_pk_bf16(bflo(c.w) + v1[2], bfhi(c.w) + v1[3]);
;                     *(u32x4*)(C + (size_t)(row0 + ai * HALF + m * 16) * ldc + col0 + bj * HALF) = w; }
	v_lshlrev_b32_e32 v228, 16, v216
	v_and_b32_e32 v229, 0xffff0000, v216
	v_lshlrev_b32_e32 v216, 16, v217
	v_and_b32_e32 v217, 0xffff0000, v217
	v_pk_add_f32 v[128:129], v[128:129], v[228:229]
	v_pk_add_f32 v[130:131], v[130:131], v[216:217]
	v_cvt_pk_bf16_f32 v128, v128, v129
	v_cvt_pk_bf16_f32 v129, v130, v131
	v_lshlrev_b32_e32 v130, 16, v218
	v_and_b32_e32 v131, 0xffff0000, v218
	v_pk_add_f32 v[124:125], v[124:125], v[130:131]
	s_nop 0
	v_cvt_pk_bf16_f32 v130, v124, v125
	v_lshlrev_b32_e32 v124, 16, v219
	v_and_b32_e32 v125, 0xffff0000, v219
	v_pk_add_f32 v[124:125], v[126:127], v[124:125]
	s_waitcnt vmcnt(14)
	v_lshlrev_b32_e32 v126, 16, v188
	v_and_b32_e32 v127, 0xffff0000, v188
	v_pk_add_f32 v[120:121], v[120:121], v[126:127]
	v_lshlrev_b32_e32 v126, 16, v189
	v_and_b32_e32 v127, 0xffff0000, v189
	v_pk_add_f32 v[122:123], v[122:123], v[126:127]
	v_cvt_pk_bf16_f32 v120, v120, v121
	v_cvt_pk_bf16_f32 v121, v122, v123
	v_lshlrev_b32_e32 v122, 16, v190
	v_and_b32_e32 v123, 0xffff0000, v190
	v_pk_add_f32 v[116:117], v[116:117], v[122:123]
	v_cvt_pk_bf16_f32 v131, v124, v125
	v_cvt_pk_bf16_f32 v122, v116, v117
	v_lshlrev_b32_e32 v116, 16, v191
	v_and_b32_e32 v117, 0xffff0000, v191
	v_pk_add_f32 v[116:117], v[118:119], v[116:117]
	v_lshl_add_u64 v[124:125], s[88:89], 0, v[226:227]
	v_cvt_pk_bf16_f32 v123, v116, v117
	s_waitcnt vmcnt(13)
	v_lshlrev_b32_e32 v116, 16, v184
	v_and_b32_e32 v117, 0xffff0000, v184
	v_pk_add_f32 v[112:113], v[112:113], v[116:117]
	v_lshlrev_b32_e32 v116, 16, v185
	v_and_b32_e32 v117, 0xffff0000, v185
	v_pk_add_f32 v[114:115], v[114:115], v[116:117]
	v_cvt_pk_bf16_f32 v112, v112, v113
	v_cvt_pk_bf16_f32 v113, v114, v115
	v_lshlrev_b32_e32 v114, 16, v186
	v_and_b32_e32 v115, 0xffff0000, v186
	v_pk_add_f32 v[108:109], v[108:109], v[114:115]
	v_lshl_add_u64 v[124:125], v[124:125], 0, v[202:203]
	v_cvt_pk_bf16_f32 v114, v108, v109
	v_lshlrev_b32_e32 v108, 16, v187
	v_and_b32_e32 v109, 0xffff0000, v187
	v_pk_add_f32 v[108:109], v[110:111], v[108:109]
	s_waitcnt vmcnt(12)
	v_lshlrev_b32_e32 v110, 16, v180
	v_and_b32_e32 v111, 0xffff0000, v180
	v_pk_add_f32 v[104:105], v[104:105], v[110:111]
	v_lshlrev_b32_e32 v110, 16, v181
	v_and_b32_e32 v111, 0xffff0000, v181
	v_pk_add_f32 v[106:107], v[106:107], v[110:111]
	v_cvt_pk_bf16_f32 v104, v104, v105
	v_cvt_pk_bf16_f32 v105, v106, v107
	v_lshlrev_b32_e32 v106, 16, v182
	v_and_b32_e32 v107, 0xffff0000, v182
	v_pk_add_f32 v[96:97], v[96:97], v[106:107]
	v_cvt_pk_bf16_f32 v115, v108, v109
	v_cvt_pk_bf16_f32 v106, v96, v97
	v_lshlrev_b32_e32 v96, 16, v183
	v_and_b32_e32 v97, 0xffff0000, v183
	v_pk_add_f32 v[96:97], v[98:99], v[96:97]
	s_waitcnt vmcnt(11)
	v_lshlrev_b32_e32 v98, 16, v177
	v_cvt_pk_bf16_f32 v107, v96, v97
	v_lshlrev_b32_e32 v96, 16, v176
	v_and_b32_e32 v97, 0xffff0000, v176
	v_and_b32_e32 v99, 0xffff0000, v177
	v_pk_add_f32 v[96:97], v[100:101], v[96:97]
	v_pk_add_f32 v[98:99], v[102:103], v[98:99]
	v_cvt_pk_bf16_f32 v96, v96, v97
	v_cvt_pk_bf16_f32 v97, v98, v99
	v_lshlrev_b32_e32 v98, 16, v178
	v_and_b32_e32 v99, 0xffff0000, v178
	v_pk_add_f32 v[92:93], v[92:93], v[98:99]
	v_lshl_add_u64 v[108:109], s[88:89], 0, v[222:223]
	v_cvt_pk_bf16_f32 v98, v92, v93
	v_lshlrev_b32_e32 v92, 16, v179
	v_and_b32_e32 v93, 0xffff0000, v179
	v_pk_add_f32 v[92:93], v[94:95], v[92:93]
	s_waitcnt vmcnt(10)
	v_lshlrev_b32_e32 v94, 16, v168
	v_and_b32_e32 v95, 0xffff0000, v168
	v_pk_add_f32 v[88:89], v[88:89], v[94:95]
	v_lshlrev_b32_e32 v94, 16, v169
	v_and_b32_e32 v95, 0xffff0000, v169
	v_pk_add_f32 v[90:91], v[90:91], v[94:95]
	v_cvt_pk_bf16_f32 v88, v88, v89
	v_cvt_pk_bf16_f32 v89, v90, v91
	v_lshlrev_b32_e32 v90, 16, v170
	v_and_b32_e32 v91, 0xffff0000, v170
	v_pk_add_f32 v[80:81], v[80:81], v[90:91]
	v_cvt_pk_bf16_f32 v99, v92, v93
	v_cvt_pk_bf16_f32 v90, v80, v81
	v_lshlrev_b32_e32 v80, 16, v171
	v_and_b32_e32 v81, 0xffff0000, v171
	v_pk_add_f32 v[80:81], v[82:83], v[80:81]
	s_waitcnt vmcnt(9)
	v_lshlrev_b32_e32 v82, 16, v173
	v_cvt_pk_bf16_f32 v91, v80, v81
	v_lshlrev_b32_e32 v80, 16, v172
	v_and_b32_e32 v81, 0xffff0000, v172
	v_and_b32_e32 v83, 0xffff0000, v173
	v_pk_add_f32 v[80:81], v[84:85], v[80:81]
	v_pk_add_f32 v[82:83], v[86:87], v[82:83]
	v_cvt_pk_bf16_f32 v80, v80, v81
	v_cvt_pk_bf16_f32 v81, v82, v83
	v_lshlrev_b32_e32 v82, 16, v174
	v_and_b32_e32 v83, 0xffff0000, v174
	v_pk_add_f32 v[76:77], v[76:77], v[82:83]
	v_lshl_add_u64 v[92:93], s[88:89], 0, v[220:221]
	v_cvt_pk_bf16_f32 v82, v76, v77
	v_lshlrev_b32_e32 v76, 16, v175
	v_and_b32_e32 v77, 0xffff0000, v175
	v_pk_add_f32 v[76:77], v[78:79], v[76:77]
	s_waitcnt vmcnt(8)
	v_lshlrev_b32_e32 v78, 16, v164
	v_and_b32_e32 v79, 0xffff0000, v164
	v_pk_add_f32 v[72:73], v[72:73], v[78:79]
	v_lshlrev_b32_e32 v78, 16, v165
	v_and_b32_e32 v79, 0xffff0000, v165
	v_pk_add_f32 v[74:75], v[74:75], v[78:79]
	v_cvt_pk_bf16_f32 v72, v72, v73
	v_cvt_pk_bf16_f32 v73, v74, v75
	v_lshlrev_b32_e32 v74, 16, v166
	v_and_b32_e32 v75, 0xffff0000, v166
	v_pk_add_f32 v[68:69], v[68:69], v[74:75]
	v_cvt_pk_bf16_f32 v83, v76, v77
	v_cvt_pk_bf16_f32 v74, v68, v69
	v_lshlrev_b32_e32 v68, 16, v167
	v_and_b32_e32 v69, 0xffff0000, v167
	v_pk_add_f32 v[68:69], v[70:71], v[68:69]
	v_lshl_add_u64 v[76:77], s[88:89], 0, v[212:213]
	v_cvt_pk_bf16_f32 v75, v68, v69
	s_waitcnt vmcnt(7)
	v_lshlrev_b32_e32 v68, 16, v160
	v_and_b32_e32 v69, 0xffff0000, v160
	v_pk_add_f32 v[64:65], v[64:65], v[68:69]
	v_lshlrev_b32_e32 v68, 16, v161
	v_and_b32_e32 v69, 0xffff0000, v161
	v_pk_add_f32 v[66:67], v[66:67], v[68:69]
	v_cvt_pk_bf16_f32 v64, v64, v65
	v_cvt_pk_bf16_f32 v65, v66, v67
	v_lshlrev_b32_e32 v66, 16, v162
	v_and_b32_e32 v67, 0xffff0000, v162
	v_pk_add_f32 v[60:61], v[60:61], v[66:67]
	v_lshl_add_u64 v[108:109], v[108:109], 0, v[202:203]
	v_cvt_pk_bf16_f32 v66, v60, v61
	v_lshlrev_b32_e32 v60, 16, v163
	v_and_b32_e32 v61, 0xffff0000, v163
	v_pk_add_f32 v[60:61], v[62:63], v[60:61]
	s_waitcnt vmcnt(6)
; __device__ __forceinline__ unsigned cvt_pk_bf16(float lo, float hi) { const f32x2 v = {lo, hi}; const bf16v2_ r = __builtin_convertvector(v, bf16v2_); return __builtin_bit_cast(unsigned, r); }
; __device__ __forceinline__ float bflo(unsigned w) { return __uint_as_float(w << 16); }
; __device__ __forceinline__ float bfhi(unsigned w) { return __uint_as_float(w & 0xffff0000u); }
;     __device__ __forceinline__ void operator()(const f32x4 (&acc)[2][2][4][2], const Unit& u, int wr, int wc, int, int) const {
;     ...
;                 for (int bj = 0; bj < 2; ++bj) { const u32x4 c = cin[ai][m][bj]; const f32x4 v0 = acc[ai][bj][m][0], v1 = acc[ai][bj][m][1];
;                     u32x4 w; w.x = cvt_pk_bf16(bflo(c.x) + v0[0], bfhi(c.x) + v0[1]); w.y = cvt_pk_bf16(bflo(c.y) + v0[2], bfhi(c.y) + v0[3]);
;                     w.z = cvt_pk_bf16(bflo(c.z) + v1[0], bfhi(c.z) + v1[1]); w.w = cvt_pk_bf16(bflo(c.w) + v1[2], bfhi(c.w) + v1[3]);
;                     *(u32x4*)(C + (size_t)(row0 + ai * HALF + m * 16) * ldc + col0 + bj * HALF) = w; }
	v_lshlrev_b32_e32 v62, 16, v156
	v_and_b32_e32 v63, 0xffff0000, v156
	v_pk_add_f32 v[56:57], v[56:57], v[62:63]
	v_lshlrev_b32_e32 v62, 16, v157
	v_and_b32_e32 v63, 0xffff0000, v157
	v_pk_add_f32 v[58:59], v[58:59], v[62:63]
	v_cvt_pk_bf16_f32 v56, v56, v57
	v_cvt_pk_bf16_f32 v57, v58, v59
	v_lshlrev_b32_e32 v58, 16, v158
	v_and_b32_e32 v59, 0xffff0000, v158
	v_pk_add_f32 v[48:49], v[48:49], v[58:59]
	v_cvt_pk_bf16_f32 v67, v60, v61
	v_cvt_pk_bf16_f32 v58, v48, v49
	v_lshlrev_b32_e32 v48, 16, v159
	v_and_b32_e32 v49, 0xffff0000, v159
	v_pk_add_f32 v[48:49], v[50:51], v[48:49]
	s_waitcnt vmcnt(5)
	v_lshlrev_b32_e32 v50, 16, v153
	v_cvt_pk_bf16_f32 v59, v48, v49
	v_lshlrev_b32_e32 v48, 16, v152
	v_and_b32_e32 v49, 0xffff0000, v152
	v_and_b32_e32 v51, 0xffff0000, v153
	v_pk_add_f32 v[48:49], v[52:53], v[48:49]
	v_pk_add_f32 v[50:51], v[54:55], v[50:51]
	v_cvt_pk_bf16_f32 v48, v48, v49
	v_cvt_pk_bf16_f32 v49, v50, v51
	v_lshlrev_b32_e32 v50, 16, v154
	v_and_b32_e32 v51, 0xffff0000, v154
	v_pk_add_f32 v[44:45], v[44:45], v[50:51]
	v_lshl_add_u64 v[60:61], s[88:89], 0, v[210:211]
	v_cvt_pk_bf16_f32 v50, v44, v45
	v_lshlrev_b32_e32 v44, 16, v155
	v_and_b32_e32 v45, 0xffff0000, v155
	v_pk_add_f32 v[44:45], v[46:47], v[44:45]
	s_waitcnt vmcnt(4)
	v_lshlrev_b32_e32 v46, 16, v148
	v_and_b32_e32 v47, 0xffff0000, v148
	v_pk_add_f32 v[40:41], v[40:41], v[46:47]
	v_lshlrev_b32_e32 v46, 16, v149
	v_and_b32_e32 v47, 0xffff0000, v149
	v_pk_add_f32 v[42:43], v[42:43], v[46:47]
	v_cvt_pk_bf16_f32 v40, v40, v41
	v_cvt_pk_bf16_f32 v41, v42, v43
	v_lshlrev_b32_e32 v42, 16, v150
	v_and_b32_e32 v43, 0xffff0000, v150
	v_pk_add_f32 v[32:33], v[32:33], v[42:43]
	v_cvt_pk_bf16_f32 v51, v44, v45
	v_cvt_pk_bf16_f32 v42, v32, v33
	v_lshlrev_b32_e32 v32, 16, v151
	v_and_b32_e32 v33, 0xffff0000, v151
	v_pk_add_f32 v[32:33], v[34:35], v[32:33]
	s_waitcnt vmcnt(3)
	v_lshlrev_b32_e32 v34, 16, v145
	v_cvt_pk_bf16_f32 v43, v32, v33
	v_lshlrev_b32_e32 v32, 16, v144
	v_and_b32_e32 v33, 0xffff0000, v144
	v_and_b32_e32 v35, 0xffff0000, v145
	v_pk_add_f32 v[32:33], v[36:37], v[32:33]
	v_pk_add_f32 v[34:35], v[38:39], v[34:35]
	v_cvt_pk_bf16_f32 v32, v32, v33
	v_cvt_pk_bf16_f32 v33, v34, v35
	v_lshlrev_b32_e32 v34, 16, v146
	v_and_b32_e32 v35, 0xffff0000, v146
	v_pk_add_f32 v[28:29], v[28:29], v[34:35]
	v_lshl_add_u64 v[44:45], s[88:89], 0, v[208:209]
	v_cvt_pk_bf16_f32 v34, v28, v29
	v_lshlrev_b32_e32 v28, 16, v147
	v_and_b32_e32 v29, 0xffff0000, v147
	v_pk_add_f32 v[28:29], v[30:31], v[28:29]
	s_waitcnt vmcnt(2)
	v_lshlrev_b32_e32 v30, 16, v140
	v_and_b32_e32 v31, 0xffff0000, v140
	v_pk_add_f32 v[24:25], v[24:25], v[30:31]
	v_lshlrev_b32_e32 v30, 16, v141
	v_and_b32_e32 v31, 0xffff0000, v141
	v_pk_add_f32 v[26:27], v[26:27], v[30:31]
	v_cvt_pk_bf16_f32 v24, v24, v25
	v_cvt_pk_bf16_f32 v25, v26, v27
	v_lshlrev_b32_e32 v26, 16, v142
	v_and_b32_e32 v27, 0xffff0000, v142
	v_pk_add_f32 v[16:17], v[16:17], v[26:27]
	v_cvt_pk_bf16_f32 v35, v28, v29
	v_cvt_pk_bf16_f32 v26, v16, v17
	v_lshlrev_b32_e32 v16, 16, v143
	v_and_b32_e32 v17, 0xffff0000, v143
	v_pk_add_f32 v[16:17], v[18:19], v[16:17]
	s_waitcnt vmcnt(1)
	v_lshlrev_b32_e32 v18, 16, v137
	v_cvt_pk_bf16_f32 v27, v16, v17
	v_lshlrev_b32_e32 v16, 16, v136
	v_and_b32_e32 v17, 0xffff0000, v136
	v_and_b32_e32 v19, 0xffff0000, v137
	v_pk_add_f32 v[16:17], v[20:21], v[16:17]
	v_pk_add_f32 v[18:19], v[22:23], v[18:19]
	v_cvt_pk_bf16_f32 v16, v16, v17
	v_cvt_pk_bf16_f32 v17, v18, v19
	v_lshlrev_b32_e32 v18, 16, v138
	v_and_b32_e32 v19, 0xffff0000, v138
	v_pk_add_f32 v[12:13], v[12:13], v[18:19]
	v_lshl_add_u64 v[28:29], s[88:89], 0, v[206:207]
	v_cvt_pk_bf16_f32 v18, v12, v13
	v_lshlrev_b32_e32 v12, 16, v139
	v_and_b32_e32 v13, 0xffff0000, v139
	v_pk_add_f32 v[12:13], v[14:15], v[12:13]
	s_waitcnt vmcnt(0)
	v_lshlrev_b32_e32 v14, 16, v132
	v_and_b32_e32 v15, 0xffff0000, v132
	v_pk_add_f32 v[8:9], v[8:9], v[14:15]
	v_lshlrev_b32_e32 v14, 16, v133
	v_and_b32_e32 v15, 0xffff0000, v133
	v_pk_add_f32 v[10:11], v[10:11], v[14:15]
	v_cvt_pk_bf16_f32 v8, v8, v9
	v_cvt_pk_bf16_f32 v9, v10, v11
	v_lshlrev_b32_e32 v10, 16, v134
	v_and_b32_e32 v11, 0xffff0000, v134
	v_pk_add_f32 v[4:5], v[4:5], v[10:11]
	v_cvt_pk_bf16_f32 v19, v12, v13
	v_cvt_pk_bf16_f32 v10, v4, v5
	v_lshlrev_b32_e32 v4, 16, v135
	v_and_b32_e32 v5, 0xffff0000, v135
	v_lshl_add_u64 v[12:13], s[88:89], 0, v[204:205]
	v_pk_add_f32 v[4:5], v[6:7], v[4:5]
	v_lshl_add_u64 v[92:93], v[92:93], 0, v[202:203]
	v_lshl_add_u64 v[76:77], v[76:77], 0, v[202:203]
	v_lshl_add_u64 v[60:61], v[60:61], 0, v[202:203]
	v_lshl_add_u64 v[44:45], v[44:45], 0, v[202:203]
	v_lshl_add_u64 v[28:29], v[28:29], 0, v[202:203]
	v_lshl_add_u64 v[12:13], v[12:13], 0, v[202:203]
	v_cvt_pk_bf16_f32 v11, v4, v5
	global_store_dwordx4 v[124:125], v[128:131], off
	global_store_dwordx4 v[124:125], v[120:123], off offset:256
	global_store_dwordx4 v[108:109], v[112:115], off
	global_store_dwordx4 v[108:109], v[104:107], off offset:256
	global_store_dwordx4 v[92:93], v[96:99], off
	global_store_dwordx4 v[92:93], v[88:91], off offset:256
	global_store_dwordx4 v[76:77], v[80:83], off
	global_store_dwordx4 v[76:77], v[72:75], off offset:256
	global_store_dwordx4 v[60:61], v[64:67], off
	global_store_dwordx4 v[60:61], v[56:59], off offset:256
	global_store_dwordx4 v[44:45], v[48:51], off
	global_store_dwordx4 v[44:45], v[40:43], off offset:256
	global_store_dwordx4 v[28:29], v[32:35], off
	global_store_dwordx4 v[28:29], v[24:27], off offset:256
	global_store_dwordx4 v[12:13], v[16:19], off
	global_store_dwordx4 v[12:13], v[8:11], off offset:256
	v_subrev_u32_e32 v216, s88, v124
	v_bfe_u32 v217, v216, 4, 8
	v_lshrrev_b32_e32 v216, 12, v216
; __device__ __forceinline__ unsigned cvt_pk_bf16(float lo, float hi) { const f32x2 v = {lo, hi}; const bf16v2_ r = __builtin_convertvector(v, bf16v2_); return __builtin_bit_cast(unsigned, r); }
; __device__ __forceinline__ float bflo(unsigned w) { return __uint_as_float(w << 16); }
; __device__ __forceinline__ float bfhi(unsigned w) { return __uint_as_float(w & 0xffff0000u); }
; __device__ __forceinline__ float wave_sum(float v) { v = row16_sum(v); v += shx(v, 16); v += shx(v, 32); return v; }
;     __device__ __forceinline__ void operator()(const f32x4 (&acc)[2][2][4][2], const Unit& u, int wr, int wc, int, int) const {
;     ...
;                 for (int bj = 0; bj < 2; ++bj) { const u32x4 c = cin[ai][m][bj]; const f32x4 v0 = acc[ai][bj][m][0], v1 = acc[ai][bj][m][1];
;                     u32x4 w; w.x = cvt_pk_bf16(bflo(c.x) + v0[0], bfhi(c.x) + v0[1]); w.y = cvt_pk_bf16(bflo(c.y) + v0[2], bfhi(c.y) + v0[3]);
;                     w.z = cvt_pk_bf16(bflo(c.z) + v1[0], bfhi(c.z) + v1[1]); w.w = cvt_pk_bf16(bflo(c.w) + v1[2], bfhi(c.w) + v1[3]);
;                     *(u32x4*)(C + (size_t)(row0 + ai * HALF + m * 16) * ldc + col0 + bj * HALF) = w; }
; __device__ __forceinline__ void rowstat_phase(const Frame& F, const bf16_t* __restrict__ res, float* __restrict__ rstd_out) {
;     ...
;         for (int r = 0; r < 4; ++r) { ss[r] = 0.f;
; #pragma unroll
;             for (int i = 0; i < 4; ++i) { const u32x4 x = v[r][i];
;                 ss[r] += bflo(x.x) * bflo(x.x) + bfhi(x.x) * bfhi(x.x) + bflo(x.y) * bflo(x.y) + bfhi(x.y) * bfhi(x.y) + bflo(x.z) * bflo(x.z) + bfhi(x.z) * bfhi(x.z) + bflo(x.w) * bflo(x.w) + bfhi(x.w) * bfhi(x.w); }
;             ss[r] = wave_sum(ss[r]); }
	v_and_b32_e32 v218, 15, v217
	v_lshrrev_b32_e32 v217, 5, v217
	v_lshl_or_b32 v217, v217, 4, v218
	v_lshlrev_b32_e32 v217, 17, v217
	v_lshl_add_u32 v216, v216, 2, v217
	v_add_u32_e32 v216, 0x1e000000, v216
	v_lshlrev_b32_e32 v218, 16, v128
	v_and_b32_e32 v219, 0xffff0000, v128
	v_mul_f32_e32 v188, v218, v218
	v_fmac_f32_e32 v188, v219, v219
	v_lshlrev_b32_e32 v218, 16, v129
	v_and_b32_e32 v219, 0xffff0000, v129
	v_fmac_f32_e32 v188, v218, v218
	v_fmac_f32_e32 v188, v219, v219
	v_lshlrev_b32_e32 v218, 16, v130
	v_and_b32_e32 v219, 0xffff0000, v130
	v_fmac_f32_e32 v188, v218, v218
	v_fmac_f32_e32 v188, v219, v219
	v_lshlrev_b32_e32 v218, 16, v131
	v_and_b32_e32 v219, 0xffff0000, v131
	v_fmac_f32_e32 v188, v218, v218
	v_fmac_f32_e32 v188, v219, v219
	v_lshlrev_b32_e32 v218, 16, v120
	v_and_b32_e32 v219, 0xffff0000, v120
	v_fmac_f32_e32 v188, v218, v218
	v_fmac_f32_e32 v188, v219, v219
	v_lshlrev_b32_e32 v218, 16, v121
	v_and_b32_e32 v219, 0xffff0000, v121
	v_fmac_f32_e32 v188, v218, v218
	v_fmac_f32_e32 v188, v219, v219
	v_lshlrev_b32_e32 v218, 16, v122
	v_and_b32_e32 v219, 0xffff0000, v122
	v_fmac_f32_e32 v188, v218, v218
	v_fmac_f32_e32 v188, v219, v219
	v_lshlrev_b32_e32 v218, 16, v123
	v_and_b32_e32 v219, 0xffff0000, v123
	v_fmac_f32_e32 v188, v218, v218
	v_fmac_f32_e32 v188, v219, v219
	global_store_dword v216, v188, s[88:89]
	v_lshlrev_b32_e32 v218, 16, v112
	v_and_b32_e32 v219, 0xffff0000, v112
	v_mul_f32_e32 v189, v218, v218
	v_fmac_f32_e32 v189, v219, v219
	v_lshlrev_b32_e32 v218, 16, v113
	v_and_b32_e32 v219, 0xffff0000, v113
	v_fmac_f32_e32 v189, v218, v218
	v_fmac_f32_e32 v189, v219, v219
	v_lshlrev_b32_e32 v218, 16, v114
	v_and_b32_e32 v219, 0xffff0000, v114
	v_fmac_f32_e32 v189, v218, v218
	v_fmac_f32_e32 v189, v219, v219
	v_lshlrev_b32_e32 v218, 16, v115
	v_and_b32_e32 v219, 0xffff0000, v115
	v_fmac_f32_e32 v189, v218, v218
	v_fmac_f32_e32 v189, v219, v219
	v_lshlrev_b32_e32 v218, 16, v104
	v_and_b32_e32 v219, 0xffff0000, v104
	v_fmac_f32_e32 v189, v218, v218
	v_fmac_f32_e32 v189, v219, v219
	v_lshlrev_b32_e32 v218, 16, v105
	v_and_b32_e32 v219, 0xffff0000, v105
	v_fmac_f32_e32 v189, v218, v218
	v_fmac_f32_e32 v189, v219, v219
	v_lshlrev_b32_e32 v218, 16, v106
	v_and_b32_e32 v219, 0xffff0000, v106
	v_fmac_f32_e32 v189, v218, v218
	v_fmac_f32_e32 v189, v219, v219
	v_lshlrev_b32_e32 v218, 16, v107
	v_and_b32_e32 v219, 0xffff0000, v107
	v_fmac_f32_e32 v189, v218, v218
	v_fmac_f32_e32 v189, v219, v219
	global_store_dword v216, v189, s[88:89] offset:64
	v_lshlrev_b32_e32 v218, 16, v96
	v_and_b32_e32 v219, 0xffff0000, v96
	v_mul_f32_e32 v188, v218, v218
	v_fmac_f32_e32 v188, v219, v219
	v_lshlrev_b32_e32 v218, 16, v97
	v_and_b32_e32 v219, 0xffff0000, v97
	v_fmac_f32_e32 v188, v218, v218
	v_fmac_f32_e32 v188, v219, v219
	v_lshlrev_b32_e32 v218, 16, v98
	v_and_b32_e32 v219, 0xffff0000, v98
	v_fmac_f32_e32 v188, v218, v218
	v_fmac_f32_e32 v188, v219, v219
	v_lshlrev_b32_e32 v218, 16, v99
	v_and_b32_e32 v219, 0xffff0000, v99
	v_fmac_f32_e32 v188, v218, v218
	v_fmac_f32_e32 v188, v219, v219
	v_lshlrev_b32_e32 v218, 16, v88
	v_and_b32_e32 v219, 0xffff0000, v88
	v_fmac_f32_e32 v188, v218, v218
	v_fmac_f32_e32 v188, v219, v219
	v_lshlrev_b32_e32 v218, 16, v89
	v_and_b32_e32 v219, 0xffff0000, v89
	v_fmac_f32_e32 v188, v218, v218
	v_fmac_f32_e32 v188, v219, v219
	v_lshlrev_b32_e32 v218, 16, v90
	v_and_b32_e32 v219, 0xffff0000, v90
	v_fmac_f32_e32 v188, v218, v218
	v_fmac_f32_e32 v188, v219, v219
	v_lshlrev_b32_e32 v218, 16, v91
	v_and_b32_e32 v219, 0xffff0000, v91
	v_fmac_f32_e32 v188, v218, v218
	v_fmac_f32_e32 v188, v219, v219
	global_store_dword v216, v188, s[88:89] offset:128
	v_lshlrev_b32_e32 v218, 16, v80
	v_and_b32_e32 v219, 0xffff0000, v80
	v_mul_f32_e32 v189, v218, v218
	v_fmac_f32_e32 v189, v219, v219
	v_lshlrev_b32_e32 v218, 16, v81
	v_and_b32_e32 v219, 0xffff0000, v81
	v_fmac_f32_e32 v189, v218, v218
	v_fmac_f32_e32 v189, v219, v219
	v_lshlrev_b32_e32 v218, 16, v82
	v_and_b32_e32 v219, 0xffff0000, v82
	v_fmac_f32_e32 v189, v218, v218
	v_fmac_f32_e32 v189, v219, v219
	v_lshlrev_b32_e32 v218, 16, v83
	v_and_b32_e32 v219, 0xffff0000, v83
	v_fmac_f32_e32 v189, v218, v218
	v_fmac_f32_e32 v189, v219, v219
	v_lshlrev_b32_e32 v218, 16, v72
	v_and_b32_e32 v219, 0xffff0000, v72
	v_fmac_f32_e32 v189, v218, v218
	v_fmac_f32_e32 v189, v219, v219
	v_lshlrev_b32_e32 v218, 16, v73
	v_and_b32_e32 v219, 0xffff0000, v73
	v_fmac_f32_e32 v189, v218, v218
	v_fmac_f32_e32 v189, v219, v219
	v_lshlrev_b32_e32 v218, 16, v74
	v_and_b32_e32 v219, 0xffff0000, v74
	v_fmac_f32_e32 v189, v218, v218
	v_fmac_f32_e32 v189, v219, v219
	v_lshlrev_b32_e32 v218, 16, v75
	v_and_b32_e32 v219, 0xffff0000, v75
	v_fmac_f32_e32 v189, v218, v218
	v_fmac_f32_e32 v189, v219, v219
; __device__ __forceinline__ unsigned cvt_pk_bf16(float lo, float hi) { const f32x2 v = {lo, hi}; const bf16v2_ r = __builtin_convertvector(v, bf16v2_); return __builtin_bit_cast(unsigned, r); }
; __device__ __forceinline__ float bflo(unsigned w) { return __uint_as_float(w << 16); }
; __device__ __forceinline__ float bfhi(unsigned w) { return __uint_as_float(w & 0xffff0000u); }
; __device__ __forceinline__ float wave_sum(float v) { v = row16_sum(v); v += shx(v, 16); v += shx(v, 32); return v; }
;     __device__ __forceinline__ void operator()(const f32x4 (&acc)[2][2][4][2], const Unit& u, int wr, int wc, int, int) const {
;     ...
;                 for (int bj = 0; bj < 2; ++bj) { const u32x4 c = cin[ai][m][bj]; const f32x4 v0 = acc[ai][bj][m][0], v1 = acc[ai][bj][m][1];
;                     u32x4 w; w.x = cvt_pk_bf16(bflo(c.x) + v0[0], bfhi(c.x) + v0[1]); w.y = cvt_pk_bf16(bflo(c.y) + v0[2], bfhi(c.y) + v0[3]);
;                     w.z = cvt_pk_bf16(bflo(c.z) + v1[0], bfhi(c.z) + v1[1]); w.w = cvt_pk_bf16(bflo(c.w) + v1[2], bfhi(c.w) + v1[3]);
;                     *(u32x4*)(C + (size_t)(row0 + ai * HALF + m * 16) * ldc + col0 + bj * HALF) = w; }
; __device__ __forceinline__ void rowstat_phase(const Frame& F, const bf16_t* __restrict__ res, float* __restrict__ rstd_out) {
;     ...
;         for (int r = 0; r < 4; ++r) { ss[r] = 0.f;
; #pragma unroll
;             for (int i = 0; i < 4; ++i) { const u32x4 x = v[r][i];
;                 ss[r] += bflo(x.x) * bflo(x.x) + bfhi(x.x) * bfhi(x.x) + bflo(x.y) * bflo(x.y) + bfhi(x.y) * bfhi(x.y) + bflo(x.z) * bflo(x.z) + bfhi(x.z) * bfhi(x.z) + bflo(x.w) * bflo(x.w) + bfhi(x.w) * bfhi(x.w); }
;             ss[r] = wave_sum(ss[r]); }
	global_store_dword v216, v189, s[88:89] offset:192
	v_lshlrev_b32_e32 v218, 16, v64
	v_and_b32_e32 v219, 0xffff0000, v64
	v_mul_f32_e32 v188, v218, v218
	v_fmac_f32_e32 v188, v219, v219
	v_lshlrev_b32_e32 v218, 16, v65
	v_and_b32_e32 v219, 0xffff0000, v65
	v_fmac_f32_e32 v188, v218, v218
	v_fmac_f32_e32 v188, v219, v219
	v_lshlrev_b32_e32 v218, 16, v66
	v_and_b32_e32 v219, 0xffff0000, v66
	v_fmac_f32_e32 v188, v218, v218
	v_fmac_f32_e32 v188, v219, v219
	v_lshlrev_b32_e32 v218, 16, v67
	v_and_b32_e32 v219, 0xffff0000, v67
	v_fmac_f32_e32 v188, v218, v218
	v_fmac_f32_e32 v188, v219, v219
	v_lshlrev_b32_e32 v218, 16, v56
	v_and_b32_e32 v219, 0xffff0000, v56
	v_fmac_f32_e32 v188, v218, v218
	v_fmac_f32_e32 v188, v219, v219
	v_lshlrev_b32_e32 v218, 16, v57
	v_and_b32_e32 v219, 0xffff0000, v57
	v_fmac_f32_e32 v188, v218, v218
	v_fmac_f32_e32 v188, v219, v219
	v_lshlrev_b32_e32 v218, 16, v58
	v_and_b32_e32 v219, 0xffff0000, v58
	v_fmac_f32_e32 v188, v218, v218
	v_fmac_f32_e32 v188, v219, v219
	v_lshlrev_b32_e32 v218, 16, v59
	v_and_b32_e32 v219, 0xffff0000, v59
	v_fmac_f32_e32 v188, v218, v218
	v_fmac_f32_e32 v188, v219, v219
	global_store_dword v216, v188, s[88:89] offset:512
	v_lshlrev_b32_e32 v218, 16, v48
	v_and_b32_e32 v219, 0xffff0000, v48
	v_mul_f32_e32 v189, v218, v218
	v_fmac_f32_e32 v189, v219, v219
	v_lshlrev_b32_e32 v218, 16, v49
	v_and_b32_e32 v219, 0xffff0000, v49
	v_fmac_f32_e32 v189, v218, v218
	v_fmac_f32_e32 v189, v219, v219
	v_lshlrev_b32_e32 v218, 16, v50
	v_and_b32_e32 v219, 0xffff0000, v50
	v_fmac_f32_e32 v189, v218, v218
	v_fmac_f32_e32 v189, v219, v219
	v_lshlrev_b32_e32 v218, 16, v51
	v_and_b32_e32 v219, 0xffff0000, v51
	v_fmac_f32_e32 v189, v218, v218
	v_fmac_f32_e32 v189, v219, v219
	v_lshlrev_b32_e32 v218, 16, v40
	v_and_b32_e32 v219, 0xffff0000, v40
	v_fmac_f32_e32 v189, v218, v218
	v_fmac_f32_e32 v189, v219, v219
	v_lshlrev_b32_e32 v218, 16, v41
	v_and_b32_e32 v219, 0xffff0000, v41
	v_fmac_f32_e32 v189, v218, v218
	v_fmac_f32_e32 v189, v219, v219
	v_lshlrev_b32_e32 v218, 16, v42
	v_and_b32_e32 v219, 0xffff0000, v42
	v_fmac_f32_e32 v189, v218, v218
	v_fmac_f32_e32 v189, v219, v219
	v_lshlrev_b32_e32 v218, 16, v43
	v_and_b32_e32 v219, 0xffff0000, v43
	v_fmac_f32_e32 v189, v218, v218
	v_fmac_f32_e32 v189, v219, v219
	global_store_dword v216, v189, s[88:89] offset:576
	v_lshlrev_b32_e32 v218, 16, v32
	v_and_b32_e32 v219, 0xffff0000, v32
	v_mul_f32_e32 v188, v218, v218
	v_fmac_f32_e32 v188, v219, v219
	v_lshlrev_b32_e32 v218, 16, v33
	v_and_b32_e32 v219, 0xffff0000, v33
	v_fmac_f32_e32 v188, v218, v218
	v_fmac_f32_e32 v188, v219, v219
	v_lshlrev_b32_e32 v218, 16, v34
	v_and_b32_e32 v219, 0xffff0000, v34
	v_fmac_f32_e32 v188, v218, v218
	v_fmac_f32_e32 v188, v219, v219
	v_lshlrev_b32_e32 v218, 16, v35
	v_and_b32_e32 v219, 0xffff0000, v35
	v_fmac_f32_e32 v188, v218, v218
	v_fmac_f32_e32 v188, v219, v219
	v_lshlrev_b32_e32 v218, 16, v24
	v_and_b32_e32 v219, 0xffff0000, v24
	v_fmac_f32_e32 v188, v218, v218
	v_fmac_f32_e32 v188, v219, v219
	v_lshlrev_b32_e32 v218, 16, v25
	v_and_b32_e32 v219, 0xffff0000, v25
	v_fmac_f32_e32 v188, v218, v218
	v_fmac_f32_e32 v188, v219, v219
	v_lshlrev_b32_e32 v218, 16, v26
	v_and_b32_e32 v219, 0xffff0000, v26
	v_fmac_f32_e32 v188, v218, v218
	v_fmac_f32_e32 v188, v219, v219
	v_lshlrev_b32_e32 v218, 16, v27
	v_and_b32_e32 v219, 0xffff0000, v27
	v_fmac_f32_e32 v188, v218, v218
	v_fmac_f32_e32 v188, v219, v219
	global_store_dword v216, v188, s[88:89] offset:640
	v_lshlrev_b32_e32 v218, 16, v16
	v_and_b32_e32 v219, 0xffff0000, v16
	v_mul_f32_e32 v189, v218, v218
	v_fmac_f32_e32 v189, v219, v219
	v_lshlrev_b32_e32 v218, 16, v17
	v_and_b32_e32 v219, 0xffff0000, v17
	v_fmac_f32_e32 v189, v218, v218
	v_fmac_f32_e32 v189, v219, v219
	v_lshlrev_b32_e32 v218, 16, v18
	v_and_b32_e32 v219, 0xffff0000, v18
	v_fmac_f32_e32 v189, v218, v218
	v_fmac_f32_e32 v189, v219, v219
	v_lshlrev_b32_e32 v218, 16, v19
	v_and_b32_e32 v219, 0xffff0000, v19
	v_fmac_f32_e32 v189, v218, v218
	v_fmac_f32_e32 v189, v219, v219
	v_lshlrev_b32_e32 v218, 16, v8
	v_and_b32_e32 v219, 0xffff0000, v8
	v_fmac_f32_e32 v189, v218, v218
	v_fmac_f32_e32 v189, v219, v219
	v_lshlrev_b32_e32 v218, 16, v9
	v_and_b32_e32 v219, 0xffff0000, v9
	v_fmac_f32_e32 v189, v218, v218
	v_fmac_f32_e32 v189, v219, v219
	v_lshlrev_b32_e32 v218, 16, v10
	v_and_b32_e32 v219, 0xffff0000, v10
	v_fmac_f32_e32 v189, v218, v218
	v_fmac_f32_e32 v189, v219, v219
	v_lshlrev_b32_e32 v218, 16, v11
	v_and_b32_e32 v219, 0xffff0000, v11
	v_fmac_f32_e32 v189, v218, v218
	v_fmac_f32_e32 v189, v219, v219
	global_store_dword v216, v189, s[88:89] offset:704
	s_cbranch_vccz .LBB0_959
	s_waitcnt vmcnt(0)
	s_cmpk_gt_u32 s2, 0xff
	s_cbranch_scc1 .LBB0_970
	s_barrier

; __device__ __forceinline__ float bflo(unsigned w) { return __uint_as_float(w << 16); }
; __device__ __forceinline__ float bfhi(unsigned w) { return __uint_as_float(w & 0xffff0000u); }
; __device__ __forceinline__ float wave_sum(float v) { v = row16_sum(v); v += shx(v, 16); v += shx(v, 32); return v; }
; #define WAVE (__builtin_amdgcn_readfirstlane(opaque_tid() >> 6))
; __device__ __forceinline__ void xcd_barrier(const XcdBarrier& b) {
;     asm volatile("s_waitcnt vmcnt(0)" ::: "memory");
;     __syncthreads();
;     if (threadIdx.x == 0) {
;         unsigned* bar = b.bar;
;         __builtin_amdgcn_s_waitcnt(0);
;         unsigned nloc = b.st[0], nx = b.st[1];
;         if (nloc == 0u) { xcd_barrier_complete(bar, b.x, nloc, nx); b.st[0] = nloc; b.st[1] = nx; }
; __device__ __forceinline__ void rowstat_phase(const Frame& F, const bf16_t* __restrict__ res, float* __restrict__ rstd_out) {
;     for (int row0 = (F.bid * NWAVE + WAVE) * 4; row0 < M; row0 += F.G * NWAVE * 4) {
;         u32x4 v[4][4];
; #pragma unroll
;         for (int r = 0; r < 4; ++r)
; #pragma unroll
;             for (int i = 0; i < 4; ++i) v[r][i] = *(const u32x4*)(res + (size_t)(row0 + r) * D + LANE * 8 + i * 512);
;         float ss[4];
; #pragma unroll
;         for (int r = 0; r < 4; ++r) { ss[r] = 0.f;
; #pragma unroll
;             for (int i = 0; i < 4; ++i) { const u32x4 x = v[r][i];
;                 ss[r] += bflo(x.x) * bflo(x.x) + bfhi(x.x) * bfhi(x.x) + bflo(x.y) * bflo(x.y) + bfhi(x.y) * bfhi(x.y) + bflo(x.z) * bflo(x.z) + bfhi(x.z) * bfhi(x.z) + bflo(x.w) * bflo(x.w) + bfhi(x.w) * bfhi(x.w); }
;             ss[r] = wave_sum(ss[r]); }
;         if (LANE < 4) rstd_out[row0 + LANE] = rsqrtf((LANE == 0 ? ss[0] : LANE == 1 ? ss[1] : LANE == 2 ? ss[2] : ss[3]) * (1.f / D) + EPS);
;     }
; }
.LBB0_1021:
	v_readlane_b32 s4, v252, 4
	v_readlane_b32 s5, v252, 5
	s_cmp_le_i32 s4, s2
	s_cselect_b64 s[0:1], -1, 0
	s_cmp_lt_i32 s2, s5
	s_cselect_b64 s[4:5], -1, 0
	s_and_b64 s[4:5], s[0:1], s[4:5]
	s_mov_b64 s[0:1], 0
	s_andn2_b64 vcc, exec, s[4:5]
	s_mov_b64 s[76:77], 0
	s_cbranch_vccnz .LBB0_1081
	v_readlane_b32 s4, v254, 57
	s_nop 0
	s_lshl_b32 s4, s4, 7
.Lrsp_loop_a:
	s_cmp_lt_i32 s4, 0x8000
	s_cbranch_scc0 .Lrsp_done_a
	v_and_b32_e32 v1, 0x7f, v0
	v_lshrrev_b32_e32 v2, 7, v0
	v_add_u32_e32 v1, s4, v1
	v_lshlrev_b32_e32 v4, 22, v2
	v_lshl_add_u32 v4, v1, 2, v4
	v_add_u32_e32 v4, 0x1e000000, v4
	s_mov_b32 s6, s88
	s_mov_b32 s7, s89
	global_load_dword v10, v4, s[6:7]
	s_add_u32 s6, s6, 0x20000
	s_addc_u32 s7, s7, 0
	global_load_dword v11, v4, s[6:7]
	s_add_u32 s6, s6, 0x20000
	s_addc_u32 s7, s7, 0
	global_load_dword v12, v4, s[6:7]
	s_add_u32 s6, s6, 0x20000
	s_addc_u32 s7, s7, 0
	global_load_dword v13, v4, s[6:7]
	s_add_u32 s6, s6, 0x20000
	s_addc_u32 s7, s7, 0
	global_load_dword v14, v4, s[6:7]
	s_add_u32 s6, s6, 0x20000
	s_addc_u32 s7, s7, 0
	global_load_dword v15, v4, s[6:7]
	s_add_u32 s6, s6, 0x20000
	s_addc_u32 s7, s7, 0
	global_load_dword v16, v4, s[6:7]
	s_add_u32 s6, s6, 0x20000
	s_addc_u32 s7, s7, 0
	global_load_dword v17, v4, s[6:7]
	s_add_u32 s6, s6, 0x20000
	s_addc_u32 s7, s7, 0
	global_load_dword v18, v4, s[6:7]
	s_add_u32 s6, s6, 0x20000
	s_addc_u32 s7, s7, 0
	global_load_dword v19, v4, s[6:7]
	s_add_u32 s6, s6, 0x20000
	s_addc_u32 s7, s7, 0
	global_load_dword v20, v4, s[6:7]
	s_add_u32 s6, s6, 0x20000
	s_addc_u32 s7, s7, 0
	global_load_dword v21, v4, s[6:7]
	s_add_u32 s6, s6, 0x20000
	s_addc_u32 s7, s7, 0
	global_load_dword v22, v4, s[6:7]
	s_add_u32 s6, s6, 0x20000
	s_addc_u32 s7, s7, 0
	global_load_dword v23, v4, s[6:7]
	s_add_u32 s6, s6, 0x20000
	s_addc_u32 s7, s7, 0
	global_load_dword v24, v4, s[6:7]
	s_add_u32 s6, s6, 0x20000
	s_addc_u32 s7, s7, 0
	global_load_dword v25, v4, s[6:7]
	s_add_u32 s6, s6, 0x20000
	s_addc_u32 s7, s7, 0
	global_load_dword v26, v4, s[6:7]
	s_add_u32 s6, s6, 0x20000
	s_addc_u32 s7, s7, 0
	global_load_dword v27, v4, s[6:7]
	s_add_u32 s6, s6, 0x20000
	s_addc_u32 s7, s7, 0
	global_load_dword v28, v4, s[6:7]
	s_add_u32 s6, s6, 0x20000
	s_addc_u32 s7, s7, 0
	global_load_dword v29, v4, s[6:7]
	s_add_u32 s6, s6, 0x20000
	s_addc_u32 s7, s7, 0
	global_load_dword v30, v4, s[6:7]
	s_add_u32 s6, s6, 0x20000
	s_addc_u32 s7, s7, 0
	global_load_dword v31, v4, s[6:7]
	s_add_u32 s6, s6, 0x20000
	s_addc_u32 s7, s7, 0
	global_load_dword v32, v4, s[6:7]
	s_add_u32 s6, s6, 0x20000
	s_addc_u32 s7, s7, 0
	global_load_dword v33, v4, s[6:7]
	s_add_u32 s6, s6, 0x20000
	s_addc_u32 s7, s7, 0
	global_load_dword v34, v4, s[6:7]
	s_add_u32 s6, s6, 0x20000
	s_addc_u32 s7, s7, 0
	global_load_dword v35, v4, s[6:7]
	s_add_u32 s6, s6, 0x20000
	s_addc_u32 s7, s7, 0
	global_load_dword v36, v4, s[6:7]
	s_add_u32 s6, s6, 0x20000
	s_addc_u32 s7, s7, 0
	global_load_dword v37, v4, s[6:7]
	s_add_u32 s6, s6, 0x20000
	s_addc_u32 s7, s7, 0
	global_load_dword v38, v4, s[6:7]
	s_add_u32 s6, s6, 0x20000
	s_addc_u32 s7, s7, 0
	global_load_dword v39, v4, s[6:7]
	s_add_u32 s6, s6, 0x20000
	s_addc_u32 s7, s7, 0
	global_load_dword v40, v4, s[6:7]
	s_add_u32 s6, s6, 0x20000
	s_addc_u32 s7, s7, 0
	global_load_dword v41, v4, s[6:7]
	s_waitcnt vmcnt(0)
	v_add_f32_e32 v10, v10, v11
	v_add_f32_e32 v12, v12, v13
	v_add_f32_e32 v14, v14, v15
	v_add_f32_e32 v16, v16, v17
	v_add_f32_e32 v18, v18, v19
	v_add_f32_e32 v20, v20, v21
	v_add_f32_e32 v22, v22, v23
	v_add_f32_e32 v24, v24, v25
	v_add_f32_e32 v26, v26, v27
	v_add_f32_e32 v28, v28, v29
	v_add_f32_e32 v30, v30, v31
	v_add_f32_e32 v32, v32, v33
	v_add_f32_e32 v34, v34, v35
	v_add_f32_e32 v36, v36, v37
	v_add_f32_e32 v38, v38, v39
	v_add_f32_e32 v40, v40, v41
	v_add_f32_e32 v10, v10, v12
	v_add_f32_e32 v14, v14, v16
	v_add_f32_e32 v18, v18, v20
	v_add_f32_e32 v22, v22, v24
	v_add_f32_e32 v26, v26, v28
	v_add_f32_e32 v30, v30, v32
	v_add_f32_e32 v34, v34, v36
	v_add_f32_e32 v38, v38, v40
	v_add_f32_e32 v10, v10, v14
	v_add_f32_e32 v18, v18, v22
	v_add_f32_e32 v26, v26, v30
	v_add_f32_e32 v34, v34, v38
	v_add_f32_e32 v10, v10, v18
	v_add_f32_e32 v26, v26, v34
	v_add_f32_e32 v10, v10, v26
	v_lshlrev_b32_e32 v5, 2, v0
	ds_write_b32 v5, v10
	s_waitcnt lgkmcnt(0)
	s_barrier
	v_cmp_gt_u32_e32 vcc, 0x80, v0
	s_and_saveexec_b64 s[14:15], vcc
	s_cbranch_execz .Lrsp_skip_a
	ds_read_b32 v11, v5
	ds_read_b32 v12, v5 offset:512
	ds_read_b32 v13, v5 offset:1024
	ds_read_b32 v14, v5 offset:1536
	v_readlane_b32 s18, v252, 14
	v_readlane_b32 s19, v252, 15
	v_mov_b32_e32 v15, 0x358637bd
	v_lshlrev_b32_e32 v6, 2, v1
	s_waitcnt lgkmcnt(0)
	v_add_f32_e32 v11, v11, v12
	v_add_f32_e32 v13, v13, v14
	v_add_f32_e32 v11, v11, v13
	v_fmamk_f32 v11, v11, 0x3a000000, v15
	v_rsq_f32_e32 v11, v11
	s_nop 1
	global_store_dword v6, v11, s[18:19]
.Lrsp_skip_a:
	s_or_b64 exec, exec, s[14:15]
	s_barrier
	s_lshl_b32 s5, s84, 7
	s_add_i32 s4, s4, s5
	s_branch .Lrsp_loop_a
.Lrsp_done_a:
.LBB0_1031:
	v_readlane_b32 s4, v252, 4
	s_add_i32 s2, s73, 5
	v_readlane_b32 s5, v252, 5
	s_cmp_ge_i32 s2, s5
	s_mov_b64 s[76:77], 0
	s_cbranch_scc1 .LBB0_1081
	s_waitcnt vmcnt(0)
	s_waitcnt vmcnt(0) lgkmcnt(0)
	s_barrier
	s_mov_b64 s[4:5], exec
	v_readlane_b32 s6, v255, 24
	v_readlane_b32 s7, v255, 25
	s_and_b64 s[6:7], s[4:5], s[6:7]
	s_mov_b64 exec, s[6:7]
	s_cbranch_execz .LBB0_1080
	v_readlane_b32 s2, v255, 9
	s_waitcnt vmcnt(0) expcnt(0) lgkmcnt(0)
	s_nop 0
	v_mov_b32_e32 v1, s2
	ds_read_b32 v4, v1
	v_readlane_b32 s2, v255, 10
	s_waitcnt lgkmcnt(0)
	v_cmp_ne_u32_e32 vcc, 0, v4
	v_mov_b32_e32 v1, s2
	ds_read_b32 v2, v1
	s_cbranch_vccnz .LBB0_1048
	v_readlane_b32 s14, v252, 8
	v_readlane_b32 s15, v252, 9
	s_load_dwordx2 s[6:7], s[14:15], 0x4
	s_mov_b32 s20, 1
	s_waitcnt lgkmcnt(0)
	s_mul_i32 s2, s6, s84
	s_mul_i32 s2, s2, s7
	s_branch .LBB0_1036

; #define PG8_STAGE(bufoff, gbase, voff) do { _Pragma("unroll") for (int _i = 0; _i < 2; ++_i) \
;         __builtin_amdgcn_global_load_lds((const unsigned*)((const char*)(gbase) + (voff)[_i]), (LAS unsigned*)(lds + (bufoff) + ldsw + _i * 8192), 16, 0, 0); } while (0)
; #define PG8_LDA(dst, b, h) do { _Pragma("unroll") for (int m = 0; m < 4; ++m) _Pragma("unroll") for (int k = 0; k < 2; ++k) dst[m][k] = *(const LAS bf16x8*)(lds + PG8_SA(b, h) + aoff + m * 2048 + k * 1024); } while (0)
; #define PG8_LDB(dst, b, h) do { _Pragma("unroll") for (int n = 0; n < 2; ++n) _Pragma("unroll") for (int k = 0; k < 2; ++k) dst[n][k] = *(const LAS bf16x8*)(lds + PG8_SB(b, h) + boff + n * 2048 + k * 1024); } while (0)
; #define PG8_MMA(ai, bj, At, Bt) do { __builtin_amdgcn_s_setprio(1); _Pragma("unroll") for (int m = 0; m < 4; ++m) _Pragma("unroll") for (int n = 0; n < 2; ++n) _Pragma("unroll") for (int k = 0; k < 2; ++k) \
;         acc[ai][bj][m][n] = __builtin_amdgcn_mfma_f32_16x16x32_bf16(Bt[n][k], At[m][k], acc[ai][bj][m][n], 0, 0, 0); __builtin_amdgcn_s_setprio(0); } while (0)
; #define PG8_WAIT_V(n) asm volatile("s_waitcnt vmcnt(" #n ")" ::: "memory")
; #define PG8_WAIT_L(n) asm volatile("s_waitcnt lgkmcnt(" #n ")" ::: "memory")
; #define PG8_BAR __builtin_amdgcn_s_barrier()
; #define PG8_SCHED __builtin_amdgcn_sched_barrier(0)
; template <class Epi, class Sched>
; __device__ __forceinline__ void gemm_phase(LAS unsigned char* lds, const Gemm g, const Sched& S, const Epi& E) {
;     ...
;             PG8_LDB(B0, 0, 0); PG8_SCHED; PG8_LDA(At, 0, 0); PG8_STAGE(PG8_SA(1, 1), a1 + hstepA, voffA);
;             PG8_WAIT_L(8); PG8_BAR; PG8_WAIT_L(0); PG8_MMA(0, 0, At, B0); PG8_BAR; PG8_SCHED;
;             PG8_LDB(B1, 0, 1); PG8_STAGE(PG8_SB(0, 0), b2, voffB);
;             PG8_BAR; PG8_WAIT_L(0); PG8_MMA(0, 1, At, B1); PG8_BAR;
;             PG8_LDA(At, 0, 1); PG8_STAGE(PG8_SA(0, 0), a2, voffA);
;             PG8_BAR; PG8_WAIT_L(0); PG8_MMA(1, 0, At, B0); PG8_BAR; PG8_SCHED;
;             PG8_STAGE(PG8_SB(0, 1), b2 + hstepB, voffB);
;             PG8_WAIT_V(6); PG8_BAR; PG8_MMA(1, 1, At, B1); PG8_BAR;
.LBB0_1396:
	s_setprio 0
	s_add_u32 s20, s6, 0xfff80080
	s_addc_u32 s21, s7, -1
	s_add_i32 s52, 0, 0x10000
	v_add_u32_e32 v144, s52, v1
	ds_read_b128 v[132:135], v144
	ds_read_b128 v[136:139], v144 offset:1024
	ds_read_b128 v[140:143], v144 offset:2048
	ds_read_b128 v[144:147], v144 offset:3072
	s_cmp_eq_u32 s51, 28
	s_cselect_b32 s25, s15, s21
	s_cselect_b32 s24, s47, s20
	s_cselect_b32 s21, s1, s50
	s_cselect_b32 s20, s48, s49
	ds_read_b128 v[148:151], v224
	ds_read_b128 v[152:155], v224 offset:1024
	ds_read_b128 v[156:159], v224 offset:2048
	ds_read_b128 v[160:163], v224 offset:3072
	ds_read_b128 v[164:167], v224 offset:4096
	ds_read_b128 v[168:171], v224 offset:5120
	ds_read_b128 v[172:175], v224 offset:6144
	ds_read_b128 v[176:179], v224 offset:7168
	s_add_i32 s54, 0, 0x14000
	v_add_u32_e32 v202, s54, v1
	ds_read_b128 v[180:183], v202
	ds_read_b128 v[184:187], v202 offset:1024
	ds_read_b128 v[188:191], v202 offset:2048
	ds_read_b128 v[202:205], v202 offset:3072
	s_add_i32 m0, s31, 0xc000
	s_nop 0
	global_load_lds_dwordx4 v198, s[6:7]
	s_add_i32 m0, s31, 0xe000
	s_nop 0
	global_load_lds_dwordx4 v200, s[6:7]
	s_waitcnt lgkmcnt(0)
	s_setprio 1
	s_barrier
	v_mfma_f32_16x16x32_bf16 v[128:131], v[132:135], v[148:151], v[128:131]
	v_mfma_f32_16x16x32_bf16 v[124:127], v[140:143], v[148:151], v[124:127]
	v_mfma_f32_16x16x32_bf16 v[112:115], v[132:135], v[156:159], v[112:115]
	v_mfma_f32_16x16x32_bf16 v[108:111], v[140:143], v[156:159], v[108:111]
	v_mfma_f32_16x16x32_bf16 v[100:103], v[132:135], v[164:167], v[100:103]
	v_mfma_f32_16x16x32_bf16 v[92:95], v[140:143], v[164:167], v[92:95]
	v_mfma_f32_16x16x32_bf16 v[84:87], v[132:135], v[172:175], v[84:87]
	v_mfma_f32_16x16x32_bf16 v[76:79], v[140:143], v[172:175], v[76:79]
	v_mfma_f32_16x16x32_bf16 v[128:131], v[136:139], v[152:155], v[128:131]
	v_mfma_f32_16x16x32_bf16 v[124:127], v[144:147], v[152:155], v[124:127]
	v_mfma_f32_16x16x32_bf16 v[112:115], v[136:139], v[160:163], v[112:115]
	v_mfma_f32_16x16x32_bf16 v[108:111], v[144:147], v[160:163], v[108:111]
	v_mfma_f32_16x16x32_bf16 v[100:103], v[136:139], v[168:171], v[100:103]
	v_mfma_f32_16x16x32_bf16 v[92:95], v[144:147], v[168:171], v[92:95]
	v_mfma_f32_16x16x32_bf16 v[84:87], v[136:139], v[176:179], v[84:87]
	v_mfma_f32_16x16x32_bf16 v[76:79], v[144:147], v[176:179], v[76:79]
	v_mfma_f32_16x16x32_bf16 v[120:123], v[180:183], v[148:151], v[120:123]
	v_mfma_f32_16x16x32_bf16 v[116:119], v[188:191], v[148:151], v[116:119]
	v_mfma_f32_16x16x32_bf16 v[104:107], v[180:183], v[156:159], v[104:107]
	v_mfma_f32_16x16x32_bf16 v[96:99], v[188:191], v[156:159], v[96:99]
	v_mfma_f32_16x16x32_bf16 v[88:91], v[180:183], v[164:167], v[88:91]
	v_mfma_f32_16x16x32_bf16 v[80:83], v[188:191], v[164:167], v[80:83]
	v_mfma_f32_16x16x32_bf16 v[72:75], v[180:183], v[172:175], v[72:75]
	v_mfma_f32_16x16x32_bf16 v[68:71], v[188:191], v[172:175], v[68:71]
	v_mfma_f32_16x16x32_bf16 v[120:123], v[184:187], v[152:155], v[120:123]
	v_mfma_f32_16x16x32_bf16 v[116:119], v[202:205], v[152:155], v[116:119]
	v_mfma_f32_16x16x32_bf16 v[104:107], v[184:187], v[160:163], v[104:107]
	v_mfma_f32_16x16x32_bf16 v[96:99], v[202:205], v[160:163], v[96:99]
	v_mfma_f32_16x16x32_bf16 v[88:91], v[184:187], v[168:171], v[88:91]
	v_mfma_f32_16x16x32_bf16 v[80:83], v[202:205], v[168:171], v[80:83]
	v_mfma_f32_16x16x32_bf16 v[72:75], v[184:187], v[176:179], v[72:75]
	v_mfma_f32_16x16x32_bf16 v[68:71], v[202:205], v[176:179], v[68:71]
	s_barrier
	s_setprio 0
	ds_read_b128 v[148:151], v224 offset:16384
	ds_read_b128 v[152:155], v224 offset:17408
	ds_read_b128 v[156:159], v224 offset:18432
	ds_read_b128 v[160:163], v224 offset:19456
	ds_read_b128 v[164:167], v224 offset:20480
	ds_read_b128 v[168:171], v224 offset:21504
	ds_read_b128 v[172:175], v224 offset:22528
	ds_read_b128 v[176:179], v224 offset:23552
	s_add_i32 s52, s52, s30
	v_lshl_add_u64 v[206:207], s[20:21], 0, v[2:3]
	s_mov_b32 m0, s52
	s_nop 0
	global_load_lds_dwordx4 v[206:207], off
	v_lshl_add_u64 v[208:209], s[20:21], 0, v[192:193]
	s_add_i32 m0, s52, 0x2000
	s_nop 0
	global_load_lds_dwordx4 v[208:209], off
	s_mov_b32 m0, s31
	v_lshl_add_u64 v[210:211], s[24:25], 0, v[196:197]
	global_load_lds_dwordx4 v[210:211], off
	v_lshl_add_u64 v[212:213], s[24:25], 0, v[194:195]
	s_mov_b32 m0, s35
	s_nop 0
	global_load_lds_dwordx4 v[212:213], off
	s_add_u32 s52, s20, 0x80000
	s_addc_u32 s53, s21, 0
	s_add_i32 s54, s54, s30
	s_mov_b32 m0, s54
	s_nop 0
	global_load_lds_dwordx4 v2, s[52:53]
	s_add_i32 m0, s54, 0x2000
	s_nop 0
	global_load_lds_dwordx4 v192, s[52:53]
	s_waitcnt lgkmcnt(0)
	s_waitcnt vmcnt(6)
	s_setprio 1
	s_barrier
; #define PG8_STAGE(bufoff, gbase, voff) do { _Pragma("unroll") for (int _i = 0; _i < 2; ++_i) \
;         __builtin_amdgcn_global_load_lds((const unsigned*)((const char*)(gbase) + (voff)[_i]), (LAS unsigned*)(lds + (bufoff) + ldsw + _i * 8192), 16, 0, 0); } while (0)
; #define PG8_LDA(dst, b, h) do { _Pragma("unroll") for (int m = 0; m < 4; ++m) _Pragma("unroll") for (int k = 0; k < 2; ++k) dst[m][k] = *(const LAS bf16x8*)(lds + PG8_SA(b, h) + aoff + m * 2048 + k * 1024); } while (0)
; #define PG8_LDB(dst, b, h) do { _Pragma("unroll") for (int n = 0; n < 2; ++n) _Pragma("unroll") for (int k = 0; k < 2; ++k) dst[n][k] = *(const LAS bf16x8*)(lds + PG8_SB(b, h) + boff + n * 2048 + k * 1024); } while (0)
; #define PG8_MMA(ai, bj, At, Bt) do { __builtin_amdgcn_s_setprio(1); _Pragma("unroll") for (int m = 0; m < 4; ++m) _Pragma("unroll") for (int n = 0; n < 2; ++n) _Pragma("unroll") for (int k = 0; k < 2; ++k) \
;         acc[ai][bj][m][n] = __builtin_amdgcn_mfma_f32_16x16x32_bf16(Bt[n][k], At[m][k], acc[ai][bj][m][n], 0, 0, 0); __builtin_amdgcn_s_setprio(0); } while (0)
; #define PG8_WAIT_V(n) asm volatile("s_waitcnt vmcnt(" #n ")" ::: "memory")
; #define PG8_WAIT_L(n) asm volatile("s_waitcnt lgkmcnt(" #n ")" ::: "memory")
; #define PG8_BAR __builtin_amdgcn_s_barrier()
; #define PG8_SCHED __builtin_amdgcn_sched_barrier(0)
; template <class Epi, class Sched>
; __device__ __forceinline__ void gemm_phase(LAS unsigned char* lds, const Gemm g, const Sched& S, const Epi& E) {
;     ...
;             PG8_BAR; PG8_WAIT_L(0); PG8_MMA(1, 0, At, B0); PG8_BAR; PG8_SCHED;
;             PG8_STAGE(PG8_SB(0, 1), b2 + hstepB, voffB);
;             PG8_WAIT_V(6); PG8_BAR; PG8_MMA(1, 1, At, B1); PG8_BAR;
;             PG8_LDB(B0, 1, 0); PG8_SCHED; PG8_LDA(At, 1, 0); PG8_STAGE(PG8_SA(0, 1), a2 + hstepA, voffA);
;             PG8_WAIT_L(8); PG8_BAR; PG8_WAIT_L(0); PG8_MMA(0, 0, At, B0); PG8_BAR; PG8_SCHED;
;             PG8_LDB(B1, 1, 1); PG8_STAGE(PG8_SB(1, 0), b3, voffB);
;             PG8_BAR; PG8_WAIT_L(0); PG8_MMA(0, 1, At, B1); PG8_BAR;
;             PG8_LDA(At, 1, 1); PG8_STAGE(PG8_SA(1, 0), a3, voffA);
;             PG8_BAR; PG8_WAIT_L(0); PG8_MMA(1, 0, At, B0); PG8_BAR; PG8_SCHED;
	v_mfma_f32_16x16x32_bf16 v[64:67], v[132:135], v[148:151], v[64:67]
	v_mfma_f32_16x16x32_bf16 v[60:63], v[140:143], v[148:151], v[60:63]
	v_mfma_f32_16x16x32_bf16 v[52:55], v[132:135], v[156:159], v[52:55]
	v_mfma_f32_16x16x32_bf16 v[44:47], v[140:143], v[156:159], v[44:47]
	v_mfma_f32_16x16x32_bf16 v[36:39], v[132:135], v[164:167], v[36:39]
	v_mfma_f32_16x16x32_bf16 v[28:31], v[140:143], v[164:167], v[28:31]
	v_mfma_f32_16x16x32_bf16 v[20:23], v[132:135], v[172:175], v[20:23]
	v_mfma_f32_16x16x32_bf16 v[12:15], v[140:143], v[172:175], v[12:15]
	v_mfma_f32_16x16x32_bf16 v[64:67], v[136:139], v[152:155], v[64:67]
	v_mfma_f32_16x16x32_bf16 v[60:63], v[144:147], v[152:155], v[60:63]
	v_mfma_f32_16x16x32_bf16 v[52:55], v[136:139], v[160:163], v[52:55]
	v_mfma_f32_16x16x32_bf16 v[44:47], v[144:147], v[160:163], v[44:47]
	v_mfma_f32_16x16x32_bf16 v[36:39], v[136:139], v[168:171], v[36:39]
	v_mfma_f32_16x16x32_bf16 v[28:31], v[144:147], v[168:171], v[28:31]
	v_mfma_f32_16x16x32_bf16 v[20:23], v[136:139], v[176:179], v[20:23]
	v_mfma_f32_16x16x32_bf16 v[12:15], v[144:147], v[176:179], v[12:15]
	v_mfma_f32_16x16x32_bf16 v[56:59], v[180:183], v[148:151], v[56:59]
	v_mfma_f32_16x16x32_bf16 v[48:51], v[188:191], v[148:151], v[48:51]
	v_mfma_f32_16x16x32_bf16 v[40:43], v[180:183], v[156:159], v[40:43]
	v_mfma_f32_16x16x32_bf16 v[32:35], v[188:191], v[156:159], v[32:35]
	v_mfma_f32_16x16x32_bf16 v[24:27], v[180:183], v[164:167], v[24:27]
	v_mfma_f32_16x16x32_bf16 v[16:19], v[188:191], v[164:167], v[16:19]
	v_mfma_f32_16x16x32_bf16 v[8:11], v[180:183], v[172:175], v[8:11]
	v_mfma_f32_16x16x32_bf16 v[4:7], v[188:191], v[172:175], v[4:7]
	v_mfma_f32_16x16x32_bf16 v[56:59], v[184:187], v[152:155], v[56:59]
	v_mfma_f32_16x16x32_bf16 v[48:51], v[202:205], v[152:155], v[48:51]
	v_mfma_f32_16x16x32_bf16 v[40:43], v[184:187], v[160:163], v[40:43]
	v_mfma_f32_16x16x32_bf16 v[32:35], v[202:205], v[160:163], v[32:35]
	v_mfma_f32_16x16x32_bf16 v[24:27], v[184:187], v[168:171], v[24:27]
	v_mfma_f32_16x16x32_bf16 v[16:19], v[202:205], v[168:171], v[16:19]
	v_mfma_f32_16x16x32_bf16 v[8:11], v[184:187], v[176:179], v[8:11]
	v_mfma_f32_16x16x32_bf16 v[4:7], v[202:205], v[176:179], v[4:7]
	s_barrier
	s_setprio 0
	s_add_i32 s52, 0, 0x18000
	v_add_u32_e32 v144, s52, v1
	ds_read_b128 v[132:135], v144
	ds_read_b128 v[136:139], v144 offset:1024
	ds_read_b128 v[140:143], v144 offset:2048
	ds_read_b128 v[144:147], v144 offset:3072
	s_add_u32 s24, s24, 0x80000
	s_addc_u32 s25, s25, 0
	ds_read_b128 v[148:151], v224 offset:32768
	ds_read_b128 v[152:155], v224 offset:33792
	ds_read_b128 v[156:159], v224 offset:34816
	ds_read_b128 v[160:163], v224 offset:35840
	ds_read_b128 v[164:167], v224 offset:36864
	ds_read_b128 v[168:171], v224 offset:37888
	ds_read_b128 v[172:175], v224 offset:38912
	ds_read_b128 v[176:179], v224 offset:39936
	s_mov_b32 m0, s36
	s_nop 0
	global_load_lds_dwordx4 v196, s[24:25]
	s_mov_b32 m0, s37
	s_nop 0
	global_load_lds_dwordx4 v194, s[24:25]
	s_add_i32 s24, 0, 0x1c000
	v_add_u32_e32 v202, s24, v1
	ds_read_b128 v[180:183], v202
	ds_read_b128 v[184:187], v202 offset:1024
	ds_read_b128 v[188:191], v202 offset:2048
	ds_read_b128 v[202:205], v202 offset:3072
	s_waitcnt lgkmcnt(0)
	s_setprio 1
	s_barrier
	v_mfma_f32_16x16x32_bf16 v[128:131], v[132:135], v[148:151], v[128:131]
	v_mfma_f32_16x16x32_bf16 v[124:127], v[140:143], v[148:151], v[124:127]
	v_mfma_f32_16x16x32_bf16 v[112:115], v[132:135], v[156:159], v[112:115]
	v_mfma_f32_16x16x32_bf16 v[108:111], v[140:143], v[156:159], v[108:111]
	v_mfma_f32_16x16x32_bf16 v[100:103], v[132:135], v[164:167], v[100:103]
	v_mfma_f32_16x16x32_bf16 v[92:95], v[140:143], v[164:167], v[92:95]
	v_mfma_f32_16x16x32_bf16 v[84:87], v[132:135], v[172:175], v[84:87]
	v_mfma_f32_16x16x32_bf16 v[76:79], v[140:143], v[172:175], v[76:79]
	v_mfma_f32_16x16x32_bf16 v[128:131], v[136:139], v[152:155], v[128:131]
	v_mfma_f32_16x16x32_bf16 v[124:127], v[144:147], v[152:155], v[124:127]
	v_mfma_f32_16x16x32_bf16 v[112:115], v[136:139], v[160:163], v[112:115]
	v_mfma_f32_16x16x32_bf16 v[108:111], v[144:147], v[160:163], v[108:111]
	v_mfma_f32_16x16x32_bf16 v[100:103], v[136:139], v[168:171], v[100:103]
	v_mfma_f32_16x16x32_bf16 v[92:95], v[144:147], v[168:171], v[92:95]
	v_mfma_f32_16x16x32_bf16 v[84:87], v[136:139], v[176:179], v[84:87]
	v_mfma_f32_16x16x32_bf16 v[76:79], v[144:147], v[176:179], v[76:79]
	v_mfma_f32_16x16x32_bf16 v[120:123], v[180:183], v[148:151], v[120:123]
	v_mfma_f32_16x16x32_bf16 v[116:119], v[188:191], v[148:151], v[116:119]
	v_mfma_f32_16x16x32_bf16 v[104:107], v[180:183], v[156:159], v[104:107]
	v_mfma_f32_16x16x32_bf16 v[96:99], v[188:191], v[156:159], v[96:99]
	v_mfma_f32_16x16x32_bf16 v[88:91], v[180:183], v[164:167], v[88:91]
	v_mfma_f32_16x16x32_bf16 v[80:83], v[188:191], v[164:167], v[80:83]
	v_mfma_f32_16x16x32_bf16 v[72:75], v[180:183], v[172:175], v[72:75]
	v_mfma_f32_16x16x32_bf16 v[68:71], v[188:191], v[172:175], v[68:71]
	v_mfma_f32_16x16x32_bf16 v[120:123], v[184:187], v[152:155], v[120:123]
	v_mfma_f32_16x16x32_bf16 v[116:119], v[202:205], v[152:155], v[116:119]
	v_mfma_f32_16x16x32_bf16 v[104:107], v[184:187], v[160:163], v[104:107]
	v_mfma_f32_16x16x32_bf16 v[96:99], v[202:205], v[160:163], v[96:99]
	v_mfma_f32_16x16x32_bf16 v[88:91], v[184:187], v[168:171], v[88:91]
	v_mfma_f32_16x16x32_bf16 v[80:83], v[202:205], v[168:171], v[80:83]
	v_mfma_f32_16x16x32_bf16 v[72:75], v[184:187], v[176:179], v[72:75]
	v_mfma_f32_16x16x32_bf16 v[68:71], v[202:205], v[176:179], v[68:71]
	s_barrier
; #define PG8_STAGE(bufoff, gbase, voff) do { _Pragma("unroll") for (int _i = 0; _i < 2; ++_i) \
;         __builtin_amdgcn_global_load_lds((const unsigned*)((const char*)(gbase) + (voff)[_i]), (LAS unsigned*)(lds + (bufoff) + ldsw + _i * 8192), 16, 0, 0); } while (0)
; #define PG8_MMA(ai, bj, At, Bt) do { __builtin_amdgcn_s_setprio(1); _Pragma("unroll") for (int m = 0; m < 4; ++m) _Pragma("unroll") for (int n = 0; n < 2; ++n) _Pragma("unroll") for (int k = 0; k < 2; ++k) \
;         acc[ai][bj][m][n] = __builtin_amdgcn_mfma_f32_16x16x32_bf16(Bt[n][k], At[m][k], acc[ai][bj][m][n], 0, 0, 0); __builtin_amdgcn_s_setprio(0); } while (0)
; #define PG8_WAIT_V(n) asm volatile("s_waitcnt vmcnt(" #n ")" ::: "memory")
; #define PG8_WAIT_L(n) asm volatile("s_waitcnt lgkmcnt(" #n ")" ::: "memory")
; #define PG8_BAR __builtin_amdgcn_s_barrier()
; #define PG8_SCHED __builtin_amdgcn_sched_barrier(0)
;     __device__ __forceinline__ void operator()(const f32x4 (&acc)[2][2][4][2], const Unit& u, int wr, int wc, int, int) const {
;     ...
;         u32x4 cin[2][4][2];
; #pragma unroll
;         for (int ai = 0; ai < 2; ++ai)
; #pragma unroll
;             for (int m = 0; m < 4; ++m)
; #pragma unroll
;                 for (int bj = 0; bj < 2; ++bj) cin[ai][m][bj] = *(const u32x4*)(C + (size_t)(row0 + ai * HALF + m * 16) * ldc + col0 + bj * HALF);
; template <class Epi, class Sched>
; __device__ __forceinline__ void gemm_phase(LAS unsigned char* lds, const Gemm g, const Sched& S, const Epi& E) {
;     ...
;             PG8_BAR; PG8_WAIT_L(0); PG8_MMA(1, 0, At, B0); PG8_BAR; PG8_SCHED;
;             PG8_STAGE(PG8_SB(1, 1), b3 + hstepB, voffB);
;             PG8_WAIT_V(6); PG8_BAR; PG8_MMA(1, 1, At, B1); PG8_BAR;
	s_setprio 0
	ds_read_b128 v[148:151], v224 offset:49152
	ds_read_b128 v[152:155], v224 offset:50176
	ds_read_b128 v[156:159], v224 offset:51200
	ds_read_b128 v[160:163], v224 offset:52224
	ds_read_b128 v[164:167], v224 offset:53248
	ds_read_b128 v[168:171], v224 offset:54272
	ds_read_b128 v[172:175], v224 offset:55296
	ds_read_b128 v[176:179], v224 offset:56320
	s_add_i32 s25, s52, s30
	v_lshl_add_u64 v[206:207], v[206:207], 0, s[8:9]
	s_mov_b32 m0, s25
	s_nop 0
	global_load_lds_dwordx4 v[206:207], off
	v_lshl_add_u64 v[206:207], v[208:209], 0, s[8:9]
	s_add_i32 m0, s25, 0x2000
	s_nop 0
	global_load_lds_dwordx4 v[206:207], off
	s_mov_b32 m0, s42
	v_lshl_add_u64 v[206:207], v[210:211], 0, s[8:9]
	global_load_lds_dwordx4 v[206:207], off
	v_lshl_add_u64 v[206:207], v[212:213], 0, s[8:9]
	s_mov_b32 m0, s43
	s_nop 0
	global_load_lds_dwordx4 v[206:207], off
	s_add_u32 s20, s20, 0x80080
	s_addc_u32 s21, s21, 0
	s_add_i32 s24, s24, s30
	s_mov_b32 m0, s24
	s_nop 0
	global_load_lds_dwordx4 v2, s[20:21]
	s_add_i32 m0, s24, 0x2000
	s_nop 0
	global_load_lds_dwordx4 v192, s[20:21]
	s_add_i32 s51, s51, 2
	s_add_u32 s6, s6, 0x100
	s_addc_u32 s7, s7, 0
	s_add_u32 s49, s49, 0x100
	s_addc_u32 s50, s50, 0
	s_cmp_gt_u32 s51, 29
	s_waitcnt lgkmcnt(0)
	s_waitcnt vmcnt(6)
	s_setprio 1
	s_barrier
	v_mfma_f32_16x16x32_bf16 v[64:67], v[132:135], v[148:151], v[64:67]
	v_mfma_f32_16x16x32_bf16 v[60:63], v[140:143], v[148:151], v[60:63]
	v_mfma_f32_16x16x32_bf16 v[52:55], v[132:135], v[156:159], v[52:55]
	v_mfma_f32_16x16x32_bf16 v[44:47], v[140:143], v[156:159], v[44:47]
	v_mfma_f32_16x16x32_bf16 v[36:39], v[132:135], v[164:167], v[36:39]
	v_mfma_f32_16x16x32_bf16 v[28:31], v[140:143], v[164:167], v[28:31]
	v_mfma_f32_16x16x32_bf16 v[20:23], v[132:135], v[172:175], v[20:23]
	v_mfma_f32_16x16x32_bf16 v[12:15], v[140:143], v[172:175], v[12:15]
	v_mfma_f32_16x16x32_bf16 v[64:67], v[136:139], v[152:155], v[64:67]
	v_mfma_f32_16x16x32_bf16 v[60:63], v[144:147], v[152:155], v[60:63]
	v_mfma_f32_16x16x32_bf16 v[52:55], v[136:139], v[160:163], v[52:55]
	v_mfma_f32_16x16x32_bf16 v[44:47], v[144:147], v[160:163], v[44:47]
	v_mfma_f32_16x16x32_bf16 v[36:39], v[136:139], v[168:171], v[36:39]
	v_mfma_f32_16x16x32_bf16 v[28:31], v[144:147], v[168:171], v[28:31]
	v_mfma_f32_16x16x32_bf16 v[20:23], v[136:139], v[176:179], v[20:23]
	v_mfma_f32_16x16x32_bf16 v[12:15], v[144:147], v[176:179], v[12:15]
	v_mfma_f32_16x16x32_bf16 v[56:59], v[180:183], v[148:151], v[56:59]
	v_mfma_f32_16x16x32_bf16 v[48:51], v[188:191], v[148:151], v[48:51]
	v_mfma_f32_16x16x32_bf16 v[40:43], v[180:183], v[156:159], v[40:43]
	v_mfma_f32_16x16x32_bf16 v[32:35], v[188:191], v[156:159], v[32:35]
	v_mfma_f32_16x16x32_bf16 v[24:27], v[180:183], v[164:167], v[24:27]
	v_mfma_f32_16x16x32_bf16 v[16:19], v[188:191], v[164:167], v[16:19]
	v_mfma_f32_16x16x32_bf16 v[8:11], v[180:183], v[172:175], v[8:11]
	v_mfma_f32_16x16x32_bf16 v[4:7], v[188:191], v[172:175], v[4:7]
	v_mfma_f32_16x16x32_bf16 v[56:59], v[184:187], v[152:155], v[56:59]
	v_mfma_f32_16x16x32_bf16 v[48:51], v[202:205], v[152:155], v[48:51]
	v_mfma_f32_16x16x32_bf16 v[40:43], v[184:187], v[160:163], v[40:43]
	v_mfma_f32_16x16x32_bf16 v[32:35], v[202:205], v[160:163], v[32:35]
	v_mfma_f32_16x16x32_bf16 v[24:27], v[184:187], v[168:171], v[24:27]
	v_mfma_f32_16x16x32_bf16 v[16:19], v[202:205], v[168:171], v[16:19]
	v_mfma_f32_16x16x32_bf16 v[8:11], v[184:187], v[176:179], v[8:11]
	v_mfma_f32_16x16x32_bf16 v[4:7], v[202:205], v[176:179], v[4:7]
	s_barrier
	s_cbranch_scc0 .LBB0_1396
	s_setprio 0
	v_mov_b32_e32 v133, v0
	s_lshl_b32 s1, s46, 8
	s_add_i32 s1, s1, s38
	v_and_or_b32 v132, v133, 15, s1
	s_lshl_b32 s1, s45, 8
	v_lshrrev_b32_e32 v133, 1, v133
	v_and_or_b32 v133, v133, 24, s1
	v_or_b32_e32 v134, s39, v133
	v_ashrrev_i32_e32 v135, 31, v134
	v_lshlrev_b64 v[202:203], 1, v[134:135]
	v_ashrrev_i32_e32 v133, 31, v132
	v_lshl_add_u64 v[134:135], s[88:89], 0, v[202:203]
	v_lshlrev_b64 v[216:217], 12, v[132:133]
	v_lshl_add_u64 v[136:137], v[134:135], 0, v[216:217]
	global_load_dwordx4 v[226:229], v[136:137], off
	global_load_dwordx4 v[188:191], v[136:137], off offset:256
	v_or_b32_e32 v136, 16, v132
	v_ashrrev_i32_e32 v137, 31, v136
	v_lshlrev_b64 v[222:223], 12, v[136:137]
	v_lshl_add_u64 v[136:137], v[134:135], 0, v[222:223]
	global_load_dwordx4 v[184:187], v[136:137], off
	global_load_dwordx4 v[180:183], v[136:137], off offset:256
	v_or_b32_e32 v136, 32, v132
	v_ashrrev_i32_e32 v137, 31, v136
	v_lshlrev_b64 v[220:221], 12, v[136:137]
	v_lshl_add_u64 v[136:137], v[134:135], 0, v[220:221]
	global_load_dwordx4 v[176:179], v[136:137], off
	global_load_dwordx4 v[168:171], v[136:137], off offset:256
	v_or_b32_e32 v132, 48, v132
	v_ashrrev_i32_e32 v133, 31, v132
	v_lshlrev_b64 v[212:213], 12, v[132:133]
	v_lshl_add_u64 v[132:133], v[134:135], 0, v[212:213]
	global_load_dwordx4 v[172:175], v[132:133], off
	global_load_dwordx4 v[164:167], v[132:133], off offset:256
	s_mov_b64 s[6:7], 0x80000
	v_lshl_add_u64 v[210:211], v[216:217], 0, s[6:7]
	v_lshl_add_u64 v[132:133], v[134:135], 0, v[210:211]
	global_load_dwordx4 v[160:163], v[132:133], off
	global_load_dwordx4 v[156:159], v[132:133], off offset:256
	s_mov_b64 s[6:7], 0x90000
	v_lshl_add_u64 v[208:209], v[216:217], 0, s[6:7]
	v_lshl_add_u64 v[132:133], v[134:135], 0, v[208:209]
	global_load_dwordx4 v[152:155], v[132:133], off
	global_load_dwordx4 v[148:151], v[132:133], off offset:256
	s_mov_b64 s[6:7], 0xa0000
	v_lshl_add_u64 v[206:207], v[216:217], 0, s[6:7]
	v_lshl_add_u64 v[132:133], v[134:135], 0, v[206:207]
	global_load_dwordx4 v[144:147], v[132:133], off
	global_load_dwordx4 v[140:143], v[132:133], off offset:256
	s_mov_b64 s[6:7], 0xb0000
	v_lshl_add_u64 v[204:205], v[216:217], 0, s[6:7]
	v_lshl_add_u64 v[132:133], v[134:135], 0, v[204:205]
	global_load_dwordx4 v[136:139], v[132:133], off
	s_nop 0
	global_load_dwordx4 v[132:135], v[132:133], off offset:256
	s_and_b64 vcc, exec, s[40:41]
	s_mov_b32 s45, s0
	s_mov_b32 s46, s14
	s_mov_b64 s[20:21], s[18:19]
	s_mov_b64 s[6:7], s[4:5]
	s_waitcnt vmcnt(15)
; __device__ __forceinline__ unsigned cvt_pk_bf16(float lo, float hi) { const f32x2 v = {lo, hi}; const bf16v2_ r = __builtin_convertvector(v, bf16v2_); return __builtin_bit_cast(unsigned, r); }
; __device__ __forceinline__ float bflo(unsigned w) { return __uint_as_float(w << 16); }
; __device__ __forceinline__ float bfhi(unsigned w) { return __uint_as_float(w & 0xffff0000u); }
;     __device__ __forceinline__ void operator()(const f32x4 (&acc)[2][2][4][2], const Unit& u, int wr, int wc, int, int) const {
;     ...
; #pragma unroll
;         for (int ai = 0; ai < 2; ++ai)
; #pragma unroll
;             for (int m = 0; m < 4; ++m)
; #pragma unroll
;                 for (int bj = 0; bj < 2; ++bj) { const u32x4 c = cin[ai][m][bj]; const f32x4 v0 = acc[ai][bj][m][0], v1 = acc[ai][bj][m][1];
;                     u32x4 w; w.x = cvt_pk_bf16(bflo(c.x) + v0[0], bfhi(c.x) + v0[1]); w.y = cvt_pk_bf16(bflo(c.y) + v0[2], bfhi(c.y) + v0[3]);
;                     w.z = cvt_pk_bf16(bflo(c.z) + v1[0], bfhi(c.z) + v1[1]); w.w = cvt_pk_bf16(bflo(c.w) + v1[2], bfhi(c.w) + v1[3]);
;                     *(u32x4*)(C + (size_t)(row0 + ai * HALF + m * 16) * ldc + col0 + bj * HALF) = w; }
	v_lshlrev_b32_e32 v218, 16, v226
	v_and_b32_e32 v219, 0xffff0000, v226
	v_pk_add_f32 v[128:129], v[128:129], v[218:219]
	v_lshlrev_b32_e32 v218, 16, v227
	v_and_b32_e32 v219, 0xffff0000, v227
	v_pk_add_f32 v[130:131], v[130:131], v[218:219]
	v_cvt_pk_bf16_f32 v128, v128, v129
	v_cvt_pk_bf16_f32 v129, v130, v131
	v_lshlrev_b32_e32 v130, 16, v228
	v_and_b32_e32 v131, 0xffff0000, v228
	v_pk_add_f32 v[124:125], v[124:125], v[130:131]
	s_nop 0
	v_cvt_pk_bf16_f32 v130, v124, v125
	v_lshlrev_b32_e32 v124, 16, v229
	v_and_b32_e32 v125, 0xffff0000, v229
	v_pk_add_f32 v[124:125], v[126:127], v[124:125]
	s_waitcnt vmcnt(14)
	v_lshlrev_b32_e32 v126, 16, v188
	v_and_b32_e32 v127, 0xffff0000, v188
	v_pk_add_f32 v[120:121], v[120:121], v[126:127]
	v_lshlrev_b32_e32 v126, 16, v189
	v_and_b32_e32 v127, 0xffff0000, v189
	v_pk_add_f32 v[122:123], v[122:123], v[126:127]
	v_cvt_pk_bf16_f32 v120, v120, v121
	v_cvt_pk_bf16_f32 v121, v122, v123
	v_lshlrev_b32_e32 v122, 16, v190
	v_and_b32_e32 v123, 0xffff0000, v190
	v_pk_add_f32 v[116:117], v[116:117], v[122:123]
	v_cvt_pk_bf16_f32 v131, v124, v125
	v_cvt_pk_bf16_f32 v122, v116, v117
	v_lshlrev_b32_e32 v116, 16, v191
	v_and_b32_e32 v117, 0xffff0000, v191
	v_pk_add_f32 v[116:117], v[118:119], v[116:117]
	v_lshl_add_u64 v[124:125], s[88:89], 0, v[216:217]
	v_cvt_pk_bf16_f32 v123, v116, v117
	s_waitcnt vmcnt(13)
	v_lshlrev_b32_e32 v116, 16, v184
	v_and_b32_e32 v117, 0xffff0000, v184
	v_pk_add_f32 v[112:113], v[112:113], v[116:117]
	v_lshlrev_b32_e32 v116, 16, v185
	v_and_b32_e32 v117, 0xffff0000, v185
	v_pk_add_f32 v[114:115], v[114:115], v[116:117]
	v_cvt_pk_bf16_f32 v112, v112, v113
	v_cvt_pk_bf16_f32 v113, v114, v115
	v_lshlrev_b32_e32 v114, 16, v186
	v_and_b32_e32 v115, 0xffff0000, v186
	v_pk_add_f32 v[108:109], v[108:109], v[114:115]
	v_lshl_add_u64 v[124:125], v[124:125], 0, v[202:203]
	v_cvt_pk_bf16_f32 v114, v108, v109
	v_lshlrev_b32_e32 v108, 16, v187
	v_and_b32_e32 v109, 0xffff0000, v187
	v_pk_add_f32 v[108:109], v[110:111], v[108:109]
	s_waitcnt vmcnt(12)
	v_lshlrev_b32_e32 v110, 16, v180
	v_and_b32_e32 v111, 0xffff0000, v180
	v_pk_add_f32 v[104:105], v[104:105], v[110:111]
	v_lshlrev_b32_e32 v110, 16, v181
	v_and_b32_e32 v111, 0xffff0000, v181
	v_pk_add_f32 v[106:107], v[106:107], v[110:111]
	v_cvt_pk_bf16_f32 v104, v104, v105
	v_cvt_pk_bf16_f32 v105, v106, v107
	v_lshlrev_b32_e32 v106, 16, v182
	v_and_b32_e32 v107, 0xffff0000, v182
	v_pk_add_f32 v[96:97], v[96:97], v[106:107]
	v_cvt_pk_bf16_f32 v115, v108, v109
	v_cvt_pk_bf16_f32 v106, v96, v97
	v_lshlrev_b32_e32 v96, 16, v183
	v_and_b32_e32 v97, 0xffff0000, v183
	v_pk_add_f32 v[96:97], v[98:99], v[96:97]
	s_waitcnt vmcnt(11)
	v_lshlrev_b32_e32 v98, 16, v177
	v_cvt_pk_bf16_f32 v107, v96, v97
	v_lshlrev_b32_e32 v96, 16, v176
	v_and_b32_e32 v97, 0xffff0000, v176
	v_and_b32_e32 v99, 0xffff0000, v177
	v_pk_add_f32 v[96:97], v[100:101], v[96:97]
	v_pk_add_f32 v[98:99], v[102:103], v[98:99]
	v_cvt_pk_bf16_f32 v96, v96, v97
	v_cvt_pk_bf16_f32 v97, v98, v99
	v_lshlrev_b32_e32 v98, 16, v178
	v_and_b32_e32 v99, 0xffff0000, v178
	v_pk_add_f32 v[92:93], v[92:93], v[98:99]
	v_lshl_add_u64 v[108:109], s[88:89], 0, v[222:223]
	v_cvt_pk_bf16_f32 v98, v92, v93
	v_lshlrev_b32_e32 v92, 16, v179
	v_and_b32_e32 v93, 0xffff0000, v179
	v_pk_add_f32 v[92:93], v[94:95], v[92:93]
	s_waitcnt vmcnt(10)
	v_lshlrev_b32_e32 v94, 16, v168
	v_and_b32_e32 v95, 0xffff0000, v168
	v_pk_add_f32 v[88:89], v[88:89], v[94:95]
	v_lshlrev_b32_e32 v94, 16, v169
	v_and_b32_e32 v95, 0xffff0000, v169
	v_pk_add_f32 v[90:91], v[90:91], v[94:95]
	v_cvt_pk_bf16_f32 v88, v88, v89
	v_cvt_pk_bf16_f32 v89, v90, v91
	v_lshlrev_b32_e32 v90, 16, v170
	v_and_b32_e32 v91, 0xffff0000, v170
	v_pk_add_f32 v[80:81], v[80:81], v[90:91]
	v_cvt_pk_bf16_f32 v99, v92, v93
	v_cvt_pk_bf16_f32 v90, v80, v81
	v_lshlrev_b32_e32 v80, 16, v171
	v_and_b32_e32 v81, 0xffff0000, v171
	v_pk_add_f32 v[80:81], v[82:83], v[80:81]
	s_waitcnt vmcnt(9)
	v_lshlrev_b32_e32 v82, 16, v173
	v_cvt_pk_bf16_f32 v91, v80, v81
	v_lshlrev_b32_e32 v80, 16, v172
	v_and_b32_e32 v81, 0xffff0000, v172
	v_and_b32_e32 v83, 0xffff0000, v173
	v_pk_add_f32 v[80:81], v[84:85], v[80:81]
	v_pk_add_f32 v[82:83], v[86:87], v[82:83]
	v_cvt_pk_bf16_f32 v80, v80, v81
	v_cvt_pk_bf16_f32 v81, v82, v83
	v_lshlrev_b32_e32 v82, 16, v174
	v_and_b32_e32 v83, 0xffff0000, v174
	v_pk_add_f32 v[76:77], v[76:77], v[82:83]
	v_lshl_add_u64 v[92:93], s[88:89], 0, v[220:221]
	v_cvt_pk_bf16_f32 v82, v76, v77
	v_lshlrev_b32_e32 v76, 16, v175
	v_and_b32_e32 v77, 0xffff0000, v175
	v_pk_add_f32 v[76:77], v[78:79], v[76:77]
	s_waitcnt vmcnt(8)
	v_lshlrev_b32_e32 v78, 16, v164
	v_and_b32_e32 v79, 0xffff0000, v164
	v_pk_add_f32 v[72:73], v[72:73], v[78:79]
	v_lshlrev_b32_e32 v78, 16, v165
	v_and_b32_e32 v79, 0xffff0000, v165
	v_pk_add_f32 v[74:75], v[74:75], v[78:79]
	v_cvt_pk_bf16_f32 v72, v72, v73
	v_cvt_pk_bf16_f32 v73, v74, v75
	v_lshlrev_b32_e32 v74, 16, v166
	v_and_b32_e32 v75, 0xffff0000, v166
	v_pk_add_f32 v[68:69], v[68:69], v[74:75]
	v_cvt_pk_bf16_f32 v83, v76, v77
	v_cvt_pk_bf16_f32 v74, v68, v69
	v_lshlrev_b32_e32 v68, 16, v167
	v_and_b32_e32 v69, 0xffff0000, v167
	v_pk_add_f32 v[68:69], v[70:71], v[68:69]
	v_lshl_add_u64 v[76:77], s[88:89], 0, v[212:213]
	v_cvt_pk_bf16_f32 v75, v68, v69
	s_waitcnt vmcnt(7)
	v_lshlrev_b32_e32 v68, 16, v160
	v_and_b32_e32 v69, 0xffff0000, v160
	v_pk_add_f32 v[64:65], v[64:65], v[68:69]
	v_lshlrev_b32_e32 v68, 16, v161
	v_and_b32_e32 v69, 0xffff0000, v161
	v_pk_add_f32 v[66:67], v[66:67], v[68:69]
	v_cvt_pk_bf16_f32 v64, v64, v65
	v_cvt_pk_bf16_f32 v65, v66, v67
	v_lshlrev_b32_e32 v66, 16, v162
	v_and_b32_e32 v67, 0xffff0000, v162
	v_pk_add_f32 v[60:61], v[60:61], v[66:67]
	v_lshl_add_u64 v[108:109], v[108:109], 0, v[202:203]
	v_cvt_pk_bf16_f32 v66, v60, v61
	v_lshlrev_b32_e32 v60, 16, v163
	v_and_b32_e32 v61, 0xffff0000, v163
	v_pk_add_f32 v[60:61], v[62:63], v[60:61]
	s_waitcnt vmcnt(6)
; __device__ __forceinline__ unsigned cvt_pk_bf16(float lo, float hi) { const f32x2 v = {lo, hi}; const bf16v2_ r = __builtin_convertvector(v, bf16v2_); return __builtin_bit_cast(unsigned, r); }
; __device__ __forceinline__ float bflo(unsigned w) { return __uint_as_float(w << 16); }
; __device__ __forceinline__ float bfhi(unsigned w) { return __uint_as_float(w & 0xffff0000u); }
;     __device__ __forceinline__ void operator()(const f32x4 (&acc)[2][2][4][2], const Unit& u, int wr, int wc, int, int) const {
;     ...
;                 for (int bj = 0; bj < 2; ++bj) { const u32x4 c = cin[ai][m][bj]; const f32x4 v0 = acc[ai][bj][m][0], v1 = acc[ai][bj][m][1];
;                     u32x4 w; w.x = cvt_pk_bf16(bflo(c.x) + v0[0], bfhi(c.x) + v0[1]); w.y = cvt_pk_bf16(bflo(c.y) + v0[2], bfhi(c.y) + v0[3]);
;                     w.z = cvt_pk_bf16(bflo(c.z) + v1[0], bfhi(c.z) + v1[1]); w.w = cvt_pk_bf16(bflo(c.w) + v1[2], bfhi(c.w) + v1[3]);
;                     *(u32x4*)(C + (size_t)(row0 + ai * HALF + m * 16) * ldc + col0 + bj * HALF) = w; }
	v_lshlrev_b32_e32 v62, 16, v156
	v_and_b32_e32 v63, 0xffff0000, v156
	v_pk_add_f32 v[56:57], v[56:57], v[62:63]
	v_lshlrev_b32_e32 v62, 16, v157
	v_and_b32_e32 v63, 0xffff0000, v157
	v_pk_add_f32 v[58:59], v[58:59], v[62:63]
	v_cvt_pk_bf16_f32 v56, v56, v57
	v_cvt_pk_bf16_f32 v57, v58, v59
	v_lshlrev_b32_e32 v58, 16, v158
	v_and_b32_e32 v59, 0xffff0000, v158
	v_pk_add_f32 v[48:49], v[48:49], v[58:59]
	v_cvt_pk_bf16_f32 v67, v60, v61
	v_cvt_pk_bf16_f32 v58, v48, v49
	v_lshlrev_b32_e32 v48, 16, v159
	v_and_b32_e32 v49, 0xffff0000, v159
	v_pk_add_f32 v[48:49], v[50:51], v[48:49]
	s_waitcnt vmcnt(5)
	v_lshlrev_b32_e32 v50, 16, v153
	v_cvt_pk_bf16_f32 v59, v48, v49
	v_lshlrev_b32_e32 v48, 16, v152
	v_and_b32_e32 v49, 0xffff0000, v152
	v_and_b32_e32 v51, 0xffff0000, v153
	v_pk_add_f32 v[48:49], v[52:53], v[48:49]
	v_pk_add_f32 v[50:51], v[54:55], v[50:51]
	v_cvt_pk_bf16_f32 v48, v48, v49
	v_cvt_pk_bf16_f32 v49, v50, v51
	v_lshlrev_b32_e32 v50, 16, v154
	v_and_b32_e32 v51, 0xffff0000, v154
	v_pk_add_f32 v[44:45], v[44:45], v[50:51]
	v_lshl_add_u64 v[60:61], s[88:89], 0, v[210:211]
	v_cvt_pk_bf16_f32 v50, v44, v45
	v_lshlrev_b32_e32 v44, 16, v155
	v_and_b32_e32 v45, 0xffff0000, v155
	v_pk_add_f32 v[44:45], v[46:47], v[44:45]
	s_waitcnt vmcnt(4)
	v_lshlrev_b32_e32 v46, 16, v148
	v_and_b32_e32 v47, 0xffff0000, v148
	v_pk_add_f32 v[40:41], v[40:41], v[46:47]
	v_lshlrev_b32_e32 v46, 16, v149
	v_and_b32_e32 v47, 0xffff0000, v149
	v_pk_add_f32 v[42:43], v[42:43], v[46:47]
	v_cvt_pk_bf16_f32 v40, v40, v41
	v_cvt_pk_bf16_f32 v41, v42, v43
	v_lshlrev_b32_e32 v42, 16, v150
	v_and_b32_e32 v43, 0xffff0000, v150
	v_pk_add_f32 v[32:33], v[32:33], v[42:43]
	v_cvt_pk_bf16_f32 v51, v44, v45
	v_cvt_pk_bf16_f32 v42, v32, v33
	v_lshlrev_b32_e32 v32, 16, v151
	v_and_b32_e32 v33, 0xffff0000, v151
	v_pk_add_f32 v[32:33], v[34:35], v[32:33]
	s_waitcnt vmcnt(3)
	v_lshlrev_b32_e32 v34, 16, v145
	v_cvt_pk_bf16_f32 v43, v32, v33
	v_lshlrev_b32_e32 v32, 16, v144
	v_and_b32_e32 v33, 0xffff0000, v144
	v_and_b32_e32 v35, 0xffff0000, v145
	v_pk_add_f32 v[32:33], v[36:37], v[32:33]
	v_pk_add_f32 v[34:35], v[38:39], v[34:35]
	v_cvt_pk_bf16_f32 v32, v32, v33
	v_cvt_pk_bf16_f32 v33, v34, v35
	v_lshlrev_b32_e32 v34, 16, v146
	v_and_b32_e32 v35, 0xffff0000, v146
	v_pk_add_f32 v[28:29], v[28:29], v[34:35]
	v_lshl_add_u64 v[44:45], s[88:89], 0, v[208:209]
	v_cvt_pk_bf16_f32 v34, v28, v29
	v_lshlrev_b32_e32 v28, 16, v147
	v_and_b32_e32 v29, 0xffff0000, v147
	v_pk_add_f32 v[28:29], v[30:31], v[28:29]
	s_waitcnt vmcnt(2)
	v_lshlrev_b32_e32 v30, 16, v140
	v_and_b32_e32 v31, 0xffff0000, v140
	v_pk_add_f32 v[24:25], v[24:25], v[30:31]
	v_lshlrev_b32_e32 v30, 16, v141
	v_and_b32_e32 v31, 0xffff0000, v141
	v_pk_add_f32 v[26:27], v[26:27], v[30:31]
	v_cvt_pk_bf16_f32 v24, v24, v25
	v_cvt_pk_bf16_f32 v25, v26, v27
	v_lshlrev_b32_e32 v26, 16, v142
	v_and_b32_e32 v27, 0xffff0000, v142
	v_pk_add_f32 v[16:17], v[16:17], v[26:27]
	v_cvt_pk_bf16_f32 v35, v28, v29
	v_cvt_pk_bf16_f32 v26, v16, v17
	v_lshlrev_b32_e32 v16, 16, v143
	v_and_b32_e32 v17, 0xffff0000, v143
	v_pk_add_f32 v[16:17], v[18:19], v[16:17]
	s_waitcnt vmcnt(1)
	v_lshlrev_b32_e32 v18, 16, v137
	v_cvt_pk_bf16_f32 v27, v16, v17
	v_lshlrev_b32_e32 v16, 16, v136
	v_and_b32_e32 v17, 0xffff0000, v136
	v_and_b32_e32 v19, 0xffff0000, v137
	v_pk_add_f32 v[16:17], v[20:21], v[16:17]
	v_pk_add_f32 v[18:19], v[22:23], v[18:19]
	v_cvt_pk_bf16_f32 v16, v16, v17
	v_cvt_pk_bf16_f32 v17, v18, v19
	v_lshlrev_b32_e32 v18, 16, v138
	v_and_b32_e32 v19, 0xffff0000, v138
	v_pk_add_f32 v[12:13], v[12:13], v[18:19]
	v_lshl_add_u64 v[28:29], s[88:89], 0, v[206:207]
	v_cvt_pk_bf16_f32 v18, v12, v13
	v_lshlrev_b32_e32 v12, 16, v139
	v_and_b32_e32 v13, 0xffff0000, v139
	v_pk_add_f32 v[12:13], v[14:15], v[12:13]
	s_waitcnt vmcnt(0)
	v_lshlrev_b32_e32 v14, 16, v132
	v_and_b32_e32 v15, 0xffff0000, v132
	v_pk_add_f32 v[8:9], v[8:9], v[14:15]
	v_lshlrev_b32_e32 v14, 16, v133
	v_and_b32_e32 v15, 0xffff0000, v133
	v_pk_add_f32 v[10:11], v[10:11], v[14:15]
	v_cvt_pk_bf16_f32 v8, v8, v9
	v_cvt_pk_bf16_f32 v9, v10, v11
	v_lshlrev_b32_e32 v10, 16, v134
	v_and_b32_e32 v11, 0xffff0000, v134
	v_pk_add_f32 v[4:5], v[4:5], v[10:11]
	v_cvt_pk_bf16_f32 v19, v12, v13
	v_cvt_pk_bf16_f32 v10, v4, v5
	v_lshlrev_b32_e32 v4, 16, v135
	v_and_b32_e32 v5, 0xffff0000, v135
	v_lshl_add_u64 v[12:13], s[88:89], 0, v[204:205]
	v_pk_add_f32 v[4:5], v[6:7], v[4:5]
	v_lshl_add_u64 v[92:93], v[92:93], 0, v[202:203]
	v_lshl_add_u64 v[76:77], v[76:77], 0, v[202:203]
	v_lshl_add_u64 v[60:61], v[60:61], 0, v[202:203]
	v_lshl_add_u64 v[44:45], v[44:45], 0, v[202:203]
	v_lshl_add_u64 v[28:29], v[28:29], 0, v[202:203]
	v_lshl_add_u64 v[12:13], v[12:13], 0, v[202:203]
	v_cvt_pk_bf16_f32 v11, v4, v5
	global_store_dwordx4 v[124:125], v[128:131], off
	global_store_dwordx4 v[124:125], v[120:123], off offset:256
	global_store_dwordx4 v[108:109], v[112:115], off
	global_store_dwordx4 v[108:109], v[104:107], off offset:256
	global_store_dwordx4 v[92:93], v[96:99], off
	global_store_dwordx4 v[92:93], v[88:91], off offset:256
	global_store_dwordx4 v[76:77], v[80:83], off
	global_store_dwordx4 v[76:77], v[72:75], off offset:256
	global_store_dwordx4 v[60:61], v[64:67], off
	global_store_dwordx4 v[60:61], v[56:59], off offset:256
	global_store_dwordx4 v[44:45], v[48:51], off
	global_store_dwordx4 v[44:45], v[40:43], off offset:256
	global_store_dwordx4 v[28:29], v[32:35], off
	global_store_dwordx4 v[28:29], v[24:27], off offset:256
	global_store_dwordx4 v[12:13], v[16:19], off
	global_store_dwordx4 v[12:13], v[8:11], off offset:256
	v_subrev_u32_e32 v226, s88, v124
	v_bfe_u32 v227, v226, 4, 8
	v_lshrrev_b32_e32 v226, 12, v226
; __device__ __forceinline__ unsigned cvt_pk_bf16(float lo, float hi) { const f32x2 v = {lo, hi}; const bf16v2_ r = __builtin_convertvector(v, bf16v2_); return __builtin_bit_cast(unsigned, r); }
; __device__ __forceinline__ float bflo(unsigned w) { return __uint_as_float(w << 16); }
; __device__ __forceinline__ float bfhi(unsigned w) { return __uint_as_float(w & 0xffff0000u); }
; __device__ __forceinline__ float wave_sum(float v) { v = row16_sum(v); v += shx(v, 16); v += shx(v, 32); return v; }
;     __device__ __forceinline__ void operator()(const f32x4 (&acc)[2][2][4][2], const Unit& u, int wr, int wc, int, int) const {
;     ...
;                 for (int bj = 0; bj < 2; ++bj) { const u32x4 c = cin[ai][m][bj]; const f32x4 v0 = acc[ai][bj][m][0], v1 = acc[ai][bj][m][1];
;                     u32x4 w; w.x = cvt_pk_bf16(bflo(c.x) + v0[0], bfhi(c.x) + v0[1]); w.y = cvt_pk_bf16(bflo(c.y) + v0[2], bfhi(c.y) + v0[3]);
;                     w.z = cvt_pk_bf16(bflo(c.z) + v1[0], bfhi(c.z) + v1[1]); w.w = cvt_pk_bf16(bflo(c.w) + v1[2], bfhi(c.w) + v1[3]);
;                     *(u32x4*)(C + (size_t)(row0 + ai * HALF + m * 16) * ldc + col0 + bj * HALF) = w; }
; __device__ __forceinline__ void rowstat_phase(const Frame& F, const bf16_t* __restrict__ res, float* __restrict__ rstd_out) {
;     ...
;         for (int r = 0; r < 4; ++r) { ss[r] = 0.f;
; #pragma unroll
;             for (int i = 0; i < 4; ++i) { const u32x4 x = v[r][i];
;                 ss[r] += bflo(x.x) * bflo(x.x) + bfhi(x.x) * bfhi(x.x) + bflo(x.y) * bflo(x.y) + bfhi(x.y) * bfhi(x.y) + bflo(x.z) * bflo(x.z) + bfhi(x.z) * bfhi(x.z) + bflo(x.w) * bflo(x.w) + bfhi(x.w) * bfhi(x.w); }
;             ss[r] = wave_sum(ss[r]); }
	v_and_b32_e32 v228, 15, v227
	v_lshrrev_b32_e32 v227, 5, v227
	v_lshl_or_b32 v227, v227, 4, v228
	v_lshlrev_b32_e32 v227, 17, v227
	v_lshl_add_u32 v226, v226, 2, v227
	v_add_u32_e32 v226, 0x1e000000, v226
	v_lshlrev_b32_e32 v228, 16, v128
	v_and_b32_e32 v229, 0xffff0000, v128
	v_mul_f32_e32 v188, v228, v228
	v_fmac_f32_e32 v188, v229, v229
	v_lshlrev_b32_e32 v228, 16, v129
	v_and_b32_e32 v229, 0xffff0000, v129
	v_fmac_f32_e32 v188, v228, v228
	v_fmac_f32_e32 v188, v229, v229
	v_lshlrev_b32_e32 v228, 16, v130
	v_and_b32_e32 v229, 0xffff0000, v130
	v_fmac_f32_e32 v188, v228, v228
	v_fmac_f32_e32 v188, v229, v229
	v_lshlrev_b32_e32 v228, 16, v131
	v_and_b32_e32 v229, 0xffff0000, v131
	v_fmac_f32_e32 v188, v228, v228
	v_fmac_f32_e32 v188, v229, v229
	v_lshlrev_b32_e32 v228, 16, v120
	v_and_b32_e32 v229, 0xffff0000, v120
	v_fmac_f32_e32 v188, v228, v228
	v_fmac_f32_e32 v188, v229, v229
	v_lshlrev_b32_e32 v228, 16, v121
	v_and_b32_e32 v229, 0xffff0000, v121
	v_fmac_f32_e32 v188, v228, v228
	v_fmac_f32_e32 v188, v229, v229
	v_lshlrev_b32_e32 v228, 16, v122
	v_and_b32_e32 v229, 0xffff0000, v122
	v_fmac_f32_e32 v188, v228, v228
	v_fmac_f32_e32 v188, v229, v229
	v_lshlrev_b32_e32 v228, 16, v123
	v_and_b32_e32 v229, 0xffff0000, v123
	v_fmac_f32_e32 v188, v228, v228
	v_fmac_f32_e32 v188, v229, v229
	global_store_dword v226, v188, s[88:89]
	v_lshlrev_b32_e32 v228, 16, v112
	v_and_b32_e32 v229, 0xffff0000, v112
	v_mul_f32_e32 v189, v228, v228
	v_fmac_f32_e32 v189, v229, v229
	v_lshlrev_b32_e32 v228, 16, v113
	v_and_b32_e32 v229, 0xffff0000, v113
	v_fmac_f32_e32 v189, v228, v228
	v_fmac_f32_e32 v189, v229, v229
	v_lshlrev_b32_e32 v228, 16, v114
	v_and_b32_e32 v229, 0xffff0000, v114
	v_fmac_f32_e32 v189, v228, v228
	v_fmac_f32_e32 v189, v229, v229
	v_lshlrev_b32_e32 v228, 16, v115
	v_and_b32_e32 v229, 0xffff0000, v115
	v_fmac_f32_e32 v189, v228, v228
	v_fmac_f32_e32 v189, v229, v229
	v_lshlrev_b32_e32 v228, 16, v104
	v_and_b32_e32 v229, 0xffff0000, v104
	v_fmac_f32_e32 v189, v228, v228
	v_fmac_f32_e32 v189, v229, v229
	v_lshlrev_b32_e32 v228, 16, v105
	v_and_b32_e32 v229, 0xffff0000, v105
	v_fmac_f32_e32 v189, v228, v228
	v_fmac_f32_e32 v189, v229, v229
	v_lshlrev_b32_e32 v228, 16, v106
	v_and_b32_e32 v229, 0xffff0000, v106
	v_fmac_f32_e32 v189, v228, v228
	v_fmac_f32_e32 v189, v229, v229
	v_lshlrev_b32_e32 v228, 16, v107
	v_and_b32_e32 v229, 0xffff0000, v107
	v_fmac_f32_e32 v189, v228, v228
	v_fmac_f32_e32 v189, v229, v229
	global_store_dword v226, v189, s[88:89] offset:64
	v_lshlrev_b32_e32 v228, 16, v96
	v_and_b32_e32 v229, 0xffff0000, v96
	v_mul_f32_e32 v188, v228, v228
	v_fmac_f32_e32 v188, v229, v229
	v_lshlrev_b32_e32 v228, 16, v97
	v_and_b32_e32 v229, 0xffff0000, v97
	v_fmac_f32_e32 v188, v228, v228
	v_fmac_f32_e32 v188, v229, v229
	v_lshlrev_b32_e32 v228, 16, v98
	v_and_b32_e32 v229, 0xffff0000, v98
	v_fmac_f32_e32 v188, v228, v228
	v_fmac_f32_e32 v188, v229, v229
	v_lshlrev_b32_e32 v228, 16, v99
	v_and_b32_e32 v229, 0xffff0000, v99
	v_fmac_f32_e32 v188, v228, v228
	v_fmac_f32_e32 v188, v229, v229
	v_lshlrev_b32_e32 v228, 16, v88
	v_and_b32_e32 v229, 0xffff0000, v88
	v_fmac_f32_e32 v188, v228, v228
	v_fmac_f32_e32 v188, v229, v229
	v_lshlrev_b32_e32 v228, 16, v89
	v_and_b32_e32 v229, 0xffff0000, v89
	v_fmac_f32_e32 v188, v228, v228
	v_fmac_f32_e32 v188, v229, v229
	v_lshlrev_b32_e32 v228, 16, v90
	v_and_b32_e32 v229, 0xffff0000, v90
	v_fmac_f32_e32 v188, v228, v228
	v_fmac_f32_e32 v188, v229, v229
	v_lshlrev_b32_e32 v228, 16, v91
	v_and_b32_e32 v229, 0xffff0000, v91
	v_fmac_f32_e32 v188, v228, v228
	v_fmac_f32_e32 v188, v229, v229
	global_store_dword v226, v188, s[88:89] offset:128
	v_lshlrev_b32_e32 v228, 16, v80
	v_and_b32_e32 v229, 0xffff0000, v80
	v_mul_f32_e32 v189, v228, v228
	v_fmac_f32_e32 v189, v229, v229
	v_lshlrev_b32_e32 v228, 16, v81
	v_and_b32_e32 v229, 0xffff0000, v81
	v_fmac_f32_e32 v189, v228, v228
	v_fmac_f32_e32 v189, v229, v229
	v_lshlrev_b32_e32 v228, 16, v82
	v_and_b32_e32 v229, 0xffff0000, v82
	v_fmac_f32_e32 v189, v228, v228
	v_fmac_f32_e32 v189, v229, v229
	v_lshlrev_b32_e32 v228, 16, v83
	v_and_b32_e32 v229, 0xffff0000, v83
	v_fmac_f32_e32 v189, v228, v228
	v_fmac_f32_e32 v189, v229, v229
	v_lshlrev_b32_e32 v228, 16, v72
	v_and_b32_e32 v229, 0xffff0000, v72
	v_fmac_f32_e32 v189, v228, v228
	v_fmac_f32_e32 v189, v229, v229
	v_lshlrev_b32_e32 v228, 16, v73
	v_and_b32_e32 v229, 0xffff0000, v73
	v_fmac_f32_e32 v189, v228, v228
	v_fmac_f32_e32 v189, v229, v229
	v_lshlrev_b32_e32 v228, 16, v74
	v_and_b32_e32 v229, 0xffff0000, v74
	v_fmac_f32_e32 v189, v228, v228
	v_fmac_f32_e32 v189, v229, v229
	v_lshlrev_b32_e32 v228, 16, v75
	v_and_b32_e32 v229, 0xffff0000, v75
	v_fmac_f32_e32 v189, v228, v228
	v_fmac_f32_e32 v189, v229, v229
; __device__ __forceinline__ unsigned cvt_pk_bf16(float lo, float hi) { const f32x2 v = {lo, hi}; const bf16v2_ r = __builtin_convertvector(v, bf16v2_); return __builtin_bit_cast(unsigned, r); }
; __device__ __forceinline__ float bflo(unsigned w) { return __uint_as_float(w << 16); }
; __device__ __forceinline__ float bfhi(unsigned w) { return __uint_as_float(w & 0xffff0000u); }
; __device__ __forceinline__ float wave_sum(float v) { v = row16_sum(v); v += shx(v, 16); v += shx(v, 32); return v; }
;     __device__ __forceinline__ void operator()(const f32x4 (&acc)[2][2][4][2], const Unit& u, int wr, int wc, int, int) const {
;     ...
;                 for (int bj = 0; bj < 2; ++bj) { const u32x4 c = cin[ai][m][bj]; const f32x4 v0 = acc[ai][bj][m][0], v1 = acc[ai][bj][m][1];
;                     u32x4 w; w.x = cvt_pk_bf16(bflo(c.x) + v0[0], bfhi(c.x) + v0[1]); w.y = cvt_pk_bf16(bflo(c.y) + v0[2], bfhi(c.y) + v0[3]);
;                     w.z = cvt_pk_bf16(bflo(c.z) + v1[0], bfhi(c.z) + v1[1]); w.w = cvt_pk_bf16(bflo(c.w) + v1[2], bfhi(c.w) + v1[3]);
;                     *(u32x4*)(C + (size_t)(row0 + ai * HALF + m * 16) * ldc + col0 + bj * HALF) = w; }
; __device__ __forceinline__ void rowstat_phase(const Frame& F, const bf16_t* __restrict__ res, float* __restrict__ rstd_out) {
;     ...
;         for (int r = 0; r < 4; ++r) { ss[r] = 0.f;
; #pragma unroll
;             for (int i = 0; i < 4; ++i) { const u32x4 x = v[r][i];
;                 ss[r] += bflo(x.x) * bflo(x.x) + bfhi(x.x) * bfhi(x.x) + bflo(x.y) * bflo(x.y) + bfhi(x.y) * bfhi(x.y) + bflo(x.z) * bflo(x.z) + bfhi(x.z) * bfhi(x.z) + bflo(x.w) * bflo(x.w) + bfhi(x.w) * bfhi(x.w); }
;             ss[r] = wave_sum(ss[r]); }
	global_store_dword v226, v189, s[88:89] offset:192
	v_lshlrev_b32_e32 v228, 16, v64
	v_and_b32_e32 v229, 0xffff0000, v64
	v_mul_f32_e32 v188, v228, v228
	v_fmac_f32_e32 v188, v229, v229
	v_lshlrev_b32_e32 v228, 16, v65
	v_and_b32_e32 v229, 0xffff0000, v65
	v_fmac_f32_e32 v188, v228, v228
	v_fmac_f32_e32 v188, v229, v229
	v_lshlrev_b32_e32 v228, 16, v66
	v_and_b32_e32 v229, 0xffff0000, v66
	v_fmac_f32_e32 v188, v228, v228
	v_fmac_f32_e32 v188, v229, v229
	v_lshlrev_b32_e32 v228, 16, v67
	v_and_b32_e32 v229, 0xffff0000, v67
	v_fmac_f32_e32 v188, v228, v228
	v_fmac_f32_e32 v188, v229, v229
	v_lshlrev_b32_e32 v228, 16, v56
	v_and_b32_e32 v229, 0xffff0000, v56
	v_fmac_f32_e32 v188, v228, v228
	v_fmac_f32_e32 v188, v229, v229
	v_lshlrev_b32_e32 v228, 16, v57
	v_and_b32_e32 v229, 0xffff0000, v57
	v_fmac_f32_e32 v188, v228, v228
	v_fmac_f32_e32 v188, v229, v229
	v_lshlrev_b32_e32 v228, 16, v58
	v_and_b32_e32 v229, 0xffff0000, v58
	v_fmac_f32_e32 v188, v228, v228
	v_fmac_f32_e32 v188, v229, v229
	v_lshlrev_b32_e32 v228, 16, v59
	v_and_b32_e32 v229, 0xffff0000, v59
	v_fmac_f32_e32 v188, v228, v228
	v_fmac_f32_e32 v188, v229, v229
	global_store_dword v226, v188, s[88:89] offset:512
	v_lshlrev_b32_e32 v228, 16, v48
	v_and_b32_e32 v229, 0xffff0000, v48
	v_mul_f32_e32 v189, v228, v228
	v_fmac_f32_e32 v189, v229, v229
	v_lshlrev_b32_e32 v228, 16, v49
	v_and_b32_e32 v229, 0xffff0000, v49
	v_fmac_f32_e32 v189, v228, v228
	v_fmac_f32_e32 v189, v229, v229
	v_lshlrev_b32_e32 v228, 16, v50
	v_and_b32_e32 v229, 0xffff0000, v50
	v_fmac_f32_e32 v189, v228, v228
	v_fmac_f32_e32 v189, v229, v229
	v_lshlrev_b32_e32 v228, 16, v51
	v_and_b32_e32 v229, 0xffff0000, v51
	v_fmac_f32_e32 v189, v228, v228
	v_fmac_f32_e32 v189, v229, v229
	v_lshlrev_b32_e32 v228, 16, v40
	v_and_b32_e32 v229, 0xffff0000, v40
	v_fmac_f32_e32 v189, v228, v228
	v_fmac_f32_e32 v189, v229, v229
	v_lshlrev_b32_e32 v228, 16, v41
	v_and_b32_e32 v229, 0xffff0000, v41
	v_fmac_f32_e32 v189, v228, v228
	v_fmac_f32_e32 v189, v229, v229
	v_lshlrev_b32_e32 v228, 16, v42
	v_and_b32_e32 v229, 0xffff0000, v42
	v_fmac_f32_e32 v189, v228, v228
	v_fmac_f32_e32 v189, v229, v229
	v_lshlrev_b32_e32 v228, 16, v43
	v_and_b32_e32 v229, 0xffff0000, v43
	v_fmac_f32_e32 v189, v228, v228
	v_fmac_f32_e32 v189, v229, v229
	global_store_dword v226, v189, s[88:89] offset:576
	v_lshlrev_b32_e32 v228, 16, v32
	v_and_b32_e32 v229, 0xffff0000, v32
	v_mul_f32_e32 v188, v228, v228
	v_fmac_f32_e32 v188, v229, v229
	v_lshlrev_b32_e32 v228, 16, v33
	v_and_b32_e32 v229, 0xffff0000, v33
	v_fmac_f32_e32 v188, v228, v228
	v_fmac_f32_e32 v188, v229, v229
	v_lshlrev_b32_e32 v228, 16, v34
	v_and_b32_e32 v229, 0xffff0000, v34
	v_fmac_f32_e32 v188, v228, v228
	v_fmac_f32_e32 v188, v229, v229
	v_lshlrev_b32_e32 v228, 16, v35
	v_and_b32_e32 v229, 0xffff0000, v35
	v_fmac_f32_e32 v188, v228, v228
	v_fmac_f32_e32 v188, v229, v229
	v_lshlrev_b32_e32 v228, 16, v24
	v_and_b32_e32 v229, 0xffff0000, v24
	v_fmac_f32_e32 v188, v228, v228
	v_fmac_f32_e32 v188, v229, v229
	v_lshlrev_b32_e32 v228, 16, v25
	v_and_b32_e32 v229, 0xffff0000, v25
	v_fmac_f32_e32 v188, v228, v228
	v_fmac_f32_e32 v188, v229, v229
	v_lshlrev_b32_e32 v228, 16, v26
	v_and_b32_e32 v229, 0xffff0000, v26
	v_fmac_f32_e32 v188, v228, v228
	v_fmac_f32_e32 v188, v229, v229
	v_lshlrev_b32_e32 v228, 16, v27
	v_and_b32_e32 v229, 0xffff0000, v27
	v_fmac_f32_e32 v188, v228, v228
	v_fmac_f32_e32 v188, v229, v229
	global_store_dword v226, v188, s[88:89] offset:640
	v_lshlrev_b32_e32 v228, 16, v16
	v_and_b32_e32 v229, 0xffff0000, v16
	v_mul_f32_e32 v189, v228, v228
	v_fmac_f32_e32 v189, v229, v229
	v_lshlrev_b32_e32 v228, 16, v17
	v_and_b32_e32 v229, 0xffff0000, v17
	v_fmac_f32_e32 v189, v228, v228
	v_fmac_f32_e32 v189, v229, v229
	v_lshlrev_b32_e32 v228, 16, v18
	v_and_b32_e32 v229, 0xffff0000, v18
	v_fmac_f32_e32 v189, v228, v228
	v_fmac_f32_e32 v189, v229, v229
	v_lshlrev_b32_e32 v228, 16, v19
	v_and_b32_e32 v229, 0xffff0000, v19
	v_fmac_f32_e32 v189, v228, v228
	v_fmac_f32_e32 v189, v229, v229
	v_lshlrev_b32_e32 v228, 16, v8
	v_and_b32_e32 v229, 0xffff0000, v8
	v_fmac_f32_e32 v189, v228, v228
	v_fmac_f32_e32 v189, v229, v229
	v_lshlrev_b32_e32 v228, 16, v9
	v_and_b32_e32 v229, 0xffff0000, v9
	v_fmac_f32_e32 v189, v228, v228
	v_fmac_f32_e32 v189, v229, v229
	v_lshlrev_b32_e32 v228, 16, v10
	v_and_b32_e32 v229, 0xffff0000, v10
	v_fmac_f32_e32 v189, v228, v228
	v_fmac_f32_e32 v189, v229, v229
	v_lshlrev_b32_e32 v228, 16, v11
	v_and_b32_e32 v229, 0xffff0000, v11
	v_fmac_f32_e32 v189, v228, v228
	v_fmac_f32_e32 v189, v229, v229
	global_store_dword v226, v189, s[88:89] offset:704
	s_cbranch_vccz .LBB0_1389
	s_waitcnt vmcnt(0)
	s_cmpk_gt_u32 s2, 0xff
	s_cbranch_scc1 .LBB0_1400
	s_barrier

; __device__ __forceinline__ float bflo(unsigned w) { return __uint_as_float(w << 16); }
; __device__ __forceinline__ float bfhi(unsigned w) { return __uint_as_float(w & 0xffff0000u); }
; __device__ __forceinline__ float wave_sum(float v) { v = row16_sum(v); v += shx(v, 16); v += shx(v, 32); return v; }
; #define WAVE (__builtin_amdgcn_readfirstlane(opaque_tid() >> 6))
; __device__ __forceinline__ void rowstat_phase(const Frame& F, const bf16_t* __restrict__ res, float* __restrict__ rstd_out) {
;     for (int row0 = (F.bid * NWAVE + WAVE) * 4; row0 < M; row0 += F.G * NWAVE * 4) {
;         u32x4 v[4][4];
; #pragma unroll
;         for (int r = 0; r < 4; ++r)
; #pragma unroll
;             for (int i = 0; i < 4; ++i) v[r][i] = *(const u32x4*)(res + (size_t)(row0 + r) * D + LANE * 8 + i * 512);
;         float ss[4];
; #pragma unroll
;         for (int r = 0; r < 4; ++r) { ss[r] = 0.f;
; #pragma unroll
;             for (int i = 0; i < 4; ++i) { const u32x4 x = v[r][i];
;                 ss[r] += bflo(x.x) * bflo(x.x) + bfhi(x.x) * bfhi(x.x) + bflo(x.y) * bflo(x.y) + bfhi(x.y) * bfhi(x.y) + bflo(x.z) * bflo(x.z) + bfhi(x.z) * bfhi(x.z) + bflo(x.w) * bflo(x.w) + bfhi(x.w) * bfhi(x.w); }
;             ss[r] = wave_sum(ss[r]); }
;         if (LANE < 4) rstd_out[row0 + LANE] = rsqrtf((LANE == 0 ? ss[0] : LANE == 1 ? ss[1] : LANE == 2 ? ss[2] : ss[3]) * (1.f / D) + EPS);
;     }
; }
.LBB0_1451:
	v_readlane_b32 s4, v252, 4
	v_readlane_b32 s5, v252, 5
	s_cmp_le_i32 s4, s2
	s_cselect_b64 s[0:1], -1, 0
	s_cmp_lt_i32 s2, s5
	s_cselect_b64 s[4:5], -1, 0
	s_and_b64 s[0:1], s[0:1], s[4:5]
	s_andn2_b64 vcc, exec, s[0:1]
	s_cbranch_vccnz .LBB0_1511
	v_readlane_b32 s4, v254, 57
	s_nop 0
	s_lshl_b32 s4, s4, 7

; __device__ __forceinline__ float bflo(unsigned w) { return __uint_as_float(w << 16); }
; __device__ __forceinline__ float bfhi(unsigned w) { return __uint_as_float(w & 0xffff0000u); }
; __device__ __forceinline__ float wave_sum(float v) { v = row16_sum(v); v += shx(v, 16); v += shx(v, 32); return v; }
; #define WAVE (__builtin_amdgcn_readfirstlane(opaque_tid() >> 6))
; __device__ __forceinline__ void xcd_barrier(const XcdBarrier& b) {
;     asm volatile("s_waitcnt vmcnt(0)" ::: "memory");
;     __syncthreads();
;     if (threadIdx.x == 0) {
;         unsigned* bar = b.bar;
;         __builtin_amdgcn_s_waitcnt(0);
;         unsigned nloc = b.st[0], nx = b.st[1];
;         if (nloc == 0u) { xcd_barrier_complete(bar, b.x, nloc, nx); b.st[0] = nloc; b.st[1] = nx; }
; __device__ __forceinline__ void rowstat_phase(const Frame& F, const bf16_t* __restrict__ res, float* __restrict__ rstd_out) {
;     for (int row0 = (F.bid * NWAVE + WAVE) * 4; row0 < M; row0 += F.G * NWAVE * 4) {
;         u32x4 v[4][4];
; #pragma unroll
;         for (int r = 0; r < 4; ++r)
; #pragma unroll
;             for (int i = 0; i < 4; ++i) v[r][i] = *(const u32x4*)(res + (size_t)(row0 + r) * D + LANE * 8 + i * 512);
;         float ss[4];
; #pragma unroll
;         for (int r = 0; r < 4; ++r) { ss[r] = 0.f;
; #pragma unroll
;             for (int i = 0; i < 4; ++i) { const u32x4 x = v[r][i];
;                 ss[r] += bflo(x.x) * bflo(x.x) + bfhi(x.x) * bfhi(x.x) + bflo(x.y) * bflo(x.y) + bfhi(x.y) * bfhi(x.y) + bflo(x.z) * bflo(x.z) + bfhi(x.z) * bfhi(x.z) + bflo(x.w) * bflo(x.w) + bfhi(x.w) * bfhi(x.w); }
;             ss[r] = wave_sum(ss[r]); }
;         if (LANE < 4) rstd_out[row0 + LANE] = rsqrtf((LANE == 0 ? ss[0] : LANE == 1 ? ss[1] : LANE == 2 ? ss[2] : ss[3]) * (1.f / D) + EPS);
;     }
; }
.Lrsp_done_b:
.LBB0_1461:
	v_readlane_b32 s4, v252, 4
	s_add_i32 s0, s73, 5
	v_readlane_b32 s5, v252, 5
	s_cmp_ge_i32 s0, s5
	s_cbranch_scc1 .LBB0_1511
	s_waitcnt vmcnt(0)
	s_waitcnt vmcnt(0) lgkmcnt(0)
	s_barrier
	s_mov_b64 s[0:1], exec
	v_readlane_b32 s4, v255, 24
	v_readlane_b32 s5, v255, 25
	s_and_b64 s[4:5], s[0:1], s[4:5]
	s_mov_b64 exec, s[4:5]
	s_cbranch_execz .LBB0_1510
	v_readlane_b32 s2, v255, 9
	s_waitcnt vmcnt(0) expcnt(0) lgkmcnt(0)
	s_nop 0
	v_mov_b32_e32 v1, s2
	ds_read_b32 v4, v1
	v_readlane_b32 s2, v255, 10
	s_waitcnt lgkmcnt(0)
	v_cmp_ne_u32_e32 vcc, 0, v4
	v_mov_b32_e32 v1, s2
	ds_read_b32 v2, v1
	s_cbranch_vccnz .LBB0_1478
	v_readlane_b32 s6, v252, 8
	v_readlane_b32 s7, v252, 9
	s_load_dwordx2 s[4:5], s[6:7], 0x4
	s_mov_b32 s18, 1
	s_waitcnt lgkmcnt(0)
	s_mul_i32 s2, s4, s84
	s_mul_i32 s2, s2, s5
	s_branch .LBB0_1466

; #define PG8_STAGE(bufoff, gbase, voff) do { _Pragma("unroll") for (int _i = 0; _i < 2; ++_i) \
;         __builtin_amdgcn_global_load_lds((const unsigned*)((const char*)(gbase) + (voff)[_i]), (LAS unsigned*)(lds + (bufoff) + ldsw + _i * 8192), 16, 0, 0); } while (0)
; #define PG8_LDA(dst, b, h) do { _Pragma("unroll") for (int m = 0; m < 4; ++m) _Pragma("unroll") for (int k = 0; k < 2; ++k) dst[m][k] = *(const LAS bf16x8*)(lds + PG8_SA(b, h) + aoff + m * 2048 + k * 1024); } while (0)
; #define PG8_LDB(dst, b, h) do { _Pragma("unroll") for (int n = 0; n < 2; ++n) _Pragma("unroll") for (int k = 0; k < 2; ++k) dst[n][k] = *(const LAS bf16x8*)(lds + PG8_SB(b, h) + boff + n * 2048 + k * 1024); } while (0)
; #define PG8_MMA(ai, bj, At, Bt) do { __builtin_amdgcn_s_setprio(1); _Pragma("unroll") for (int m = 0; m < 4; ++m) _Pragma("unroll") for (int n = 0; n < 2; ++n) _Pragma("unroll") for (int k = 0; k < 2; ++k) \
;         acc[ai][bj][m][n] = __builtin_amdgcn_mfma_f32_16x16x32_bf16(Bt[n][k], At[m][k], acc[ai][bj][m][n], 0, 0, 0); __builtin_amdgcn_s_setprio(0); } while (0)
; #define PG8_WAIT_V(n) asm volatile("s_waitcnt vmcnt(" #n ")" ::: "memory")
; #define PG8_WAIT_L(n) asm volatile("s_waitcnt lgkmcnt(" #n ")" ::: "memory")
; #define PG8_BAR __builtin_amdgcn_s_barrier()
; #define PG8_SCHED __builtin_amdgcn_sched_barrier(0)
; template <class Epi, class Sched>
; __device__ __forceinline__ void gemm_phase(LAS unsigned char* lds, const Gemm g, const Sched& S, const Epi& E) {
;     ...
;             PG8_LDB(B0, 0, 0); PG8_SCHED; PG8_LDA(At, 0, 0); PG8_STAGE(PG8_SA(1, 1), a1 + hstepA, voffA);
;             PG8_WAIT_L(8); PG8_BAR; PG8_WAIT_L(0); PG8_MMA(0, 0, At, B0); PG8_BAR; PG8_SCHED;
;             PG8_LDB(B1, 0, 1); PG8_STAGE(PG8_SB(0, 0), b2, voffB);
;             PG8_BAR; PG8_WAIT_L(0); PG8_MMA(0, 1, At, B1); PG8_BAR;
;             PG8_LDA(At, 0, 1); PG8_STAGE(PG8_SA(0, 0), a2, voffA);
;             PG8_BAR; PG8_WAIT_L(0); PG8_MMA(1, 0, At, B0); PG8_BAR; PG8_SCHED;
;             PG8_STAGE(PG8_SB(0, 1), b2 + hstepB, voffB);
;             PG8_WAIT_V(6); PG8_BAR; PG8_MMA(1, 1, At, B1); PG8_BAR;
.LBB0_1666:
	s_setprio 0
	s_add_u32 s14, s6, 0x100
	s_addc_u32 s15, s7, 0
	s_add_i32 s45, 0, 0x10000
	v_add_u32_e32 v144, s45, v1
	ds_read_b128 v[132:135], v144
	ds_read_b128 v[136:139], v144 offset:1024
	ds_read_b128 v[140:143], v144 offset:2048
	ds_read_b128 v[144:147], v144 offset:3072
	s_cmpk_eq_i32 s44, 0x54
	s_cselect_b32 s21, s1, s15
	s_cselect_b32 s20, s0, s14
	s_cselect_b32 s19, s5, s43
	s_cselect_b32 s18, s4, s42
	ds_read_b128 v[148:151], v224
	ds_read_b128 v[152:155], v224 offset:1024
	ds_read_b128 v[156:159], v224 offset:2048
	ds_read_b128 v[160:163], v224 offset:3072
	ds_read_b128 v[164:167], v224 offset:4096
	ds_read_b128 v[168:171], v224 offset:5120
	ds_read_b128 v[172:175], v224 offset:6144
	ds_read_b128 v[176:179], v224 offset:7168
	s_add_i32 s51, 0, 0x14000
	v_add_u32_e32 v202, s51, v1
	ds_read_b128 v[180:183], v202
	ds_read_b128 v[184:187], v202 offset:1024
	ds_read_b128 v[188:191], v202 offset:2048
	ds_read_b128 v[202:205], v202 offset:3072
	s_add_i32 m0, s29, 0xc000
	s_nop 0
	global_load_lds_dwordx4 v198, s[6:7]
	s_add_i32 m0, s29, 0xe000
	s_nop 0
	global_load_lds_dwordx4 v200, s[6:7]
	s_waitcnt lgkmcnt(0)
	s_setprio 1
	s_barrier
	v_mfma_f32_16x16x32_bf16 v[128:131], v[132:135], v[148:151], v[128:131]
	v_mfma_f32_16x16x32_bf16 v[124:127], v[140:143], v[148:151], v[124:127]
	v_mfma_f32_16x16x32_bf16 v[112:115], v[132:135], v[156:159], v[112:115]
	v_mfma_f32_16x16x32_bf16 v[108:111], v[140:143], v[156:159], v[108:111]
	v_mfma_f32_16x16x32_bf16 v[100:103], v[132:135], v[164:167], v[100:103]
	v_mfma_f32_16x16x32_bf16 v[92:95], v[140:143], v[164:167], v[92:95]
	v_mfma_f32_16x16x32_bf16 v[84:87], v[132:135], v[172:175], v[84:87]
	v_mfma_f32_16x16x32_bf16 v[76:79], v[140:143], v[172:175], v[76:79]
	v_mfma_f32_16x16x32_bf16 v[128:131], v[136:139], v[152:155], v[128:131]
	v_mfma_f32_16x16x32_bf16 v[124:127], v[144:147], v[152:155], v[124:127]
	v_mfma_f32_16x16x32_bf16 v[112:115], v[136:139], v[160:163], v[112:115]
	v_mfma_f32_16x16x32_bf16 v[108:111], v[144:147], v[160:163], v[108:111]
	v_mfma_f32_16x16x32_bf16 v[100:103], v[136:139], v[168:171], v[100:103]
	v_mfma_f32_16x16x32_bf16 v[92:95], v[144:147], v[168:171], v[92:95]
	v_mfma_f32_16x16x32_bf16 v[84:87], v[136:139], v[176:179], v[84:87]
	v_mfma_f32_16x16x32_bf16 v[76:79], v[144:147], v[176:179], v[76:79]
	v_mfma_f32_16x16x32_bf16 v[120:123], v[180:183], v[148:151], v[120:123]
	v_mfma_f32_16x16x32_bf16 v[116:119], v[188:191], v[148:151], v[116:119]
	v_mfma_f32_16x16x32_bf16 v[104:107], v[180:183], v[156:159], v[104:107]
	v_mfma_f32_16x16x32_bf16 v[96:99], v[188:191], v[156:159], v[96:99]
	v_mfma_f32_16x16x32_bf16 v[88:91], v[180:183], v[164:167], v[88:91]
	v_mfma_f32_16x16x32_bf16 v[80:83], v[188:191], v[164:167], v[80:83]
	v_mfma_f32_16x16x32_bf16 v[72:75], v[180:183], v[172:175], v[72:75]
	v_mfma_f32_16x16x32_bf16 v[68:71], v[188:191], v[172:175], v[68:71]
	v_mfma_f32_16x16x32_bf16 v[120:123], v[184:187], v[152:155], v[120:123]
	v_mfma_f32_16x16x32_bf16 v[116:119], v[202:205], v[152:155], v[116:119]
	v_mfma_f32_16x16x32_bf16 v[104:107], v[184:187], v[160:163], v[104:107]
	v_mfma_f32_16x16x32_bf16 v[96:99], v[202:205], v[160:163], v[96:99]
	v_mfma_f32_16x16x32_bf16 v[88:91], v[184:187], v[168:171], v[88:91]
	v_mfma_f32_16x16x32_bf16 v[80:83], v[202:205], v[168:171], v[80:83]
	v_mfma_f32_16x16x32_bf16 v[72:75], v[184:187], v[176:179], v[72:75]
	v_mfma_f32_16x16x32_bf16 v[68:71], v[202:205], v[176:179], v[68:71]
	s_barrier
	s_setprio 0
	ds_read_b128 v[148:151], v224 offset:16384
	ds_read_b128 v[152:155], v224 offset:17408
	ds_read_b128 v[156:159], v224 offset:18432
	ds_read_b128 v[160:163], v224 offset:19456
	ds_read_b128 v[164:167], v224 offset:20480
	ds_read_b128 v[168:171], v224 offset:21504
	ds_read_b128 v[172:175], v224 offset:22528
	ds_read_b128 v[176:179], v224 offset:23552
	s_add_i32 s6, s45, s28
	v_lshl_add_u64 v[206:207], s[18:19], 0, v[2:3]
	s_mov_b32 m0, s6
	s_nop 0
	global_load_lds_dwordx4 v[206:207], off
	v_lshl_add_u64 v[208:209], s[18:19], 0, v[192:193]
	s_add_i32 m0, s6, 0x2000
	s_nop 0
	global_load_lds_dwordx4 v[208:209], off
	s_mov_b32 m0, s29
	v_lshl_add_u64 v[210:211], s[20:21], 0, v[196:197]
	global_load_lds_dwordx4 v[210:211], off
	v_lshl_add_u64 v[212:213], s[20:21], 0, v[194:195]
	s_mov_b32 m0, s30
	s_nop 0
	global_load_lds_dwordx4 v[212:213], off
	s_add_u32 s6, s18, 0x160000
	s_addc_u32 s7, s19, 0
	s_add_i32 s45, s51, s28
	s_mov_b32 m0, s45
	s_nop 0
	global_load_lds_dwordx4 v2, s[6:7]
	s_add_i32 m0, s45, 0x2000
	s_nop 0
	global_load_lds_dwordx4 v192, s[6:7]
	s_waitcnt lgkmcnt(0)
	s_waitcnt vmcnt(6)
	s_setprio 1
	s_barrier
; #define PG8_STAGE(bufoff, gbase, voff) do { _Pragma("unroll") for (int _i = 0; _i < 2; ++_i) \
;         __builtin_amdgcn_global_load_lds((const unsigned*)((const char*)(gbase) + (voff)[_i]), (LAS unsigned*)(lds + (bufoff) + ldsw + _i * 8192), 16, 0, 0); } while (0)
; #define PG8_LDA(dst, b, h) do { _Pragma("unroll") for (int m = 0; m < 4; ++m) _Pragma("unroll") for (int k = 0; k < 2; ++k) dst[m][k] = *(const LAS bf16x8*)(lds + PG8_SA(b, h) + aoff + m * 2048 + k * 1024); } while (0)
; #define PG8_LDB(dst, b, h) do { _Pragma("unroll") for (int n = 0; n < 2; ++n) _Pragma("unroll") for (int k = 0; k < 2; ++k) dst[n][k] = *(const LAS bf16x8*)(lds + PG8_SB(b, h) + boff + n * 2048 + k * 1024); } while (0)
; #define PG8_MMA(ai, bj, At, Bt) do { __builtin_amdgcn_s_setprio(1); _Pragma("unroll") for (int m = 0; m < 4; ++m) _Pragma("unroll") for (int n = 0; n < 2; ++n) _Pragma("unroll") for (int k = 0; k < 2; ++k) \
;         acc[ai][bj][m][n] = __builtin_amdgcn_mfma_f32_16x16x32_bf16(Bt[n][k], At[m][k], acc[ai][bj][m][n], 0, 0, 0); __builtin_amdgcn_s_setprio(0); } while (0)
; #define PG8_WAIT_V(n) asm volatile("s_waitcnt vmcnt(" #n ")" ::: "memory")
; #define PG8_WAIT_L(n) asm volatile("s_waitcnt lgkmcnt(" #n ")" ::: "memory")
; #define PG8_BAR __builtin_amdgcn_s_barrier()
; #define PG8_SCHED __builtin_amdgcn_sched_barrier(0)
; template <class Epi, class Sched>
; __device__ __forceinline__ void gemm_phase(LAS unsigned char* lds, const Gemm g, const Sched& S, const Epi& E) {
;     ...
;             PG8_BAR; PG8_WAIT_L(0); PG8_MMA(1, 0, At, B0); PG8_BAR; PG8_SCHED;
;             PG8_STAGE(PG8_SB(0, 1), b2 + hstepB, voffB);
;             PG8_WAIT_V(6); PG8_BAR; PG8_MMA(1, 1, At, B1); PG8_BAR;
;             PG8_LDB(B0, 1, 0); PG8_SCHED; PG8_LDA(At, 1, 0); PG8_STAGE(PG8_SA(0, 1), a2 + hstepA, voffA);
;             PG8_WAIT_L(8); PG8_BAR; PG8_WAIT_L(0); PG8_MMA(0, 0, At, B0); PG8_BAR; PG8_SCHED;
;             PG8_LDB(B1, 1, 1); PG8_STAGE(PG8_SB(1, 0), b3, voffB);
;             PG8_BAR; PG8_WAIT_L(0); PG8_MMA(0, 1, At, B1); PG8_BAR;
;             PG8_LDA(At, 1, 1); PG8_STAGE(PG8_SA(1, 0), a3, voffA);
;             PG8_BAR; PG8_WAIT_L(0); PG8_MMA(1, 0, At, B0); PG8_BAR; PG8_SCHED;
	v_mfma_f32_16x16x32_bf16 v[64:67], v[132:135], v[148:151], v[64:67]
	v_mfma_f32_16x16x32_bf16 v[60:63], v[140:143], v[148:151], v[60:63]
	v_mfma_f32_16x16x32_bf16 v[52:55], v[132:135], v[156:159], v[52:55]
	v_mfma_f32_16x16x32_bf16 v[44:47], v[140:143], v[156:159], v[44:47]
	v_mfma_f32_16x16x32_bf16 v[36:39], v[132:135], v[164:167], v[36:39]
	v_mfma_f32_16x16x32_bf16 v[28:31], v[140:143], v[164:167], v[28:31]
	v_mfma_f32_16x16x32_bf16 v[20:23], v[132:135], v[172:175], v[20:23]
	v_mfma_f32_16x16x32_bf16 v[12:15], v[140:143], v[172:175], v[12:15]
	v_mfma_f32_16x16x32_bf16 v[64:67], v[136:139], v[152:155], v[64:67]
	v_mfma_f32_16x16x32_bf16 v[60:63], v[144:147], v[152:155], v[60:63]
	v_mfma_f32_16x16x32_bf16 v[52:55], v[136:139], v[160:163], v[52:55]
	v_mfma_f32_16x16x32_bf16 v[44:47], v[144:147], v[160:163], v[44:47]
	v_mfma_f32_16x16x32_bf16 v[36:39], v[136:139], v[168:171], v[36:39]
	v_mfma_f32_16x16x32_bf16 v[28:31], v[144:147], v[168:171], v[28:31]
	v_mfma_f32_16x16x32_bf16 v[20:23], v[136:139], v[176:179], v[20:23]
	v_mfma_f32_16x16x32_bf16 v[12:15], v[144:147], v[176:179], v[12:15]
	v_mfma_f32_16x16x32_bf16 v[56:59], v[180:183], v[148:151], v[56:59]
	v_mfma_f32_16x16x32_bf16 v[48:51], v[188:191], v[148:151], v[48:51]
	v_mfma_f32_16x16x32_bf16 v[40:43], v[180:183], v[156:159], v[40:43]
	v_mfma_f32_16x16x32_bf16 v[32:35], v[188:191], v[156:159], v[32:35]
	v_mfma_f32_16x16x32_bf16 v[24:27], v[180:183], v[164:167], v[24:27]
	v_mfma_f32_16x16x32_bf16 v[16:19], v[188:191], v[164:167], v[16:19]
	v_mfma_f32_16x16x32_bf16 v[8:11], v[180:183], v[172:175], v[8:11]
	v_mfma_f32_16x16x32_bf16 v[4:7], v[188:191], v[172:175], v[4:7]
	v_mfma_f32_16x16x32_bf16 v[56:59], v[184:187], v[152:155], v[56:59]
	v_mfma_f32_16x16x32_bf16 v[48:51], v[202:205], v[152:155], v[48:51]
	v_mfma_f32_16x16x32_bf16 v[40:43], v[184:187], v[160:163], v[40:43]
	v_mfma_f32_16x16x32_bf16 v[32:35], v[202:205], v[160:163], v[32:35]
	v_mfma_f32_16x16x32_bf16 v[24:27], v[184:187], v[168:171], v[24:27]
	v_mfma_f32_16x16x32_bf16 v[16:19], v[202:205], v[168:171], v[16:19]
	v_mfma_f32_16x16x32_bf16 v[8:11], v[184:187], v[176:179], v[8:11]
	v_mfma_f32_16x16x32_bf16 v[4:7], v[202:205], v[176:179], v[4:7]
	s_barrier
	s_setprio 0
	s_add_i32 s45, 0, 0x18000
	v_add_u32_e32 v144, s45, v1
	ds_read_b128 v[132:135], v144
	ds_read_b128 v[136:139], v144 offset:1024
	ds_read_b128 v[140:143], v144 offset:2048
	ds_read_b128 v[144:147], v144 offset:3072
	s_add_u32 s6, s20, 0x160000
	s_addc_u32 s7, s21, 0
	ds_read_b128 v[148:151], v224 offset:32768
	ds_read_b128 v[152:155], v224 offset:33792
	ds_read_b128 v[156:159], v224 offset:34816
	ds_read_b128 v[160:163], v224 offset:35840
	ds_read_b128 v[164:167], v224 offset:36864
	ds_read_b128 v[168:171], v224 offset:37888
	ds_read_b128 v[172:175], v224 offset:38912
	ds_read_b128 v[176:179], v224 offset:39936
	s_mov_b32 m0, s31
	s_nop 0
	global_load_lds_dwordx4 v196, s[6:7]
	s_mov_b32 m0, s35
	s_nop 0
	global_load_lds_dwordx4 v194, s[6:7]
	s_add_i32 s20, 0, 0x1c000
	v_add_u32_e32 v202, s20, v1
	ds_read_b128 v[180:183], v202
	ds_read_b128 v[184:187], v202 offset:1024
	ds_read_b128 v[188:191], v202 offset:2048
	ds_read_b128 v[202:205], v202 offset:3072
	s_waitcnt lgkmcnt(0)
	s_setprio 1
	s_barrier
	v_mfma_f32_16x16x32_bf16 v[128:131], v[132:135], v[148:151], v[128:131]
	v_mfma_f32_16x16x32_bf16 v[124:127], v[140:143], v[148:151], v[124:127]
	v_mfma_f32_16x16x32_bf16 v[112:115], v[132:135], v[156:159], v[112:115]
	v_mfma_f32_16x16x32_bf16 v[108:111], v[140:143], v[156:159], v[108:111]
	v_mfma_f32_16x16x32_bf16 v[100:103], v[132:135], v[164:167], v[100:103]
	v_mfma_f32_16x16x32_bf16 v[92:95], v[140:143], v[164:167], v[92:95]
	v_mfma_f32_16x16x32_bf16 v[84:87], v[132:135], v[172:175], v[84:87]
	v_mfma_f32_16x16x32_bf16 v[76:79], v[140:143], v[172:175], v[76:79]
	v_mfma_f32_16x16x32_bf16 v[128:131], v[136:139], v[152:155], v[128:131]
	v_mfma_f32_16x16x32_bf16 v[124:127], v[144:147], v[152:155], v[124:127]
	v_mfma_f32_16x16x32_bf16 v[112:115], v[136:139], v[160:163], v[112:115]
	v_mfma_f32_16x16x32_bf16 v[108:111], v[144:147], v[160:163], v[108:111]
	v_mfma_f32_16x16x32_bf16 v[100:103], v[136:139], v[168:171], v[100:103]
	v_mfma_f32_16x16x32_bf16 v[92:95], v[144:147], v[168:171], v[92:95]
	v_mfma_f32_16x16x32_bf16 v[84:87], v[136:139], v[176:179], v[84:87]
	v_mfma_f32_16x16x32_bf16 v[76:79], v[144:147], v[176:179], v[76:79]
	v_mfma_f32_16x16x32_bf16 v[120:123], v[180:183], v[148:151], v[120:123]
	v_mfma_f32_16x16x32_bf16 v[116:119], v[188:191], v[148:151], v[116:119]
	v_mfma_f32_16x16x32_bf16 v[104:107], v[180:183], v[156:159], v[104:107]
	v_mfma_f32_16x16x32_bf16 v[96:99], v[188:191], v[156:159], v[96:99]
	v_mfma_f32_16x16x32_bf16 v[88:91], v[180:183], v[164:167], v[88:91]
	v_mfma_f32_16x16x32_bf16 v[80:83], v[188:191], v[164:167], v[80:83]
	v_mfma_f32_16x16x32_bf16 v[72:75], v[180:183], v[172:175], v[72:75]
	v_mfma_f32_16x16x32_bf16 v[68:71], v[188:191], v[172:175], v[68:71]
	v_mfma_f32_16x16x32_bf16 v[120:123], v[184:187], v[152:155], v[120:123]
	v_mfma_f32_16x16x32_bf16 v[116:119], v[202:205], v[152:155], v[116:119]
	v_mfma_f32_16x16x32_bf16 v[104:107], v[184:187], v[160:163], v[104:107]
	v_mfma_f32_16x16x32_bf16 v[96:99], v[202:205], v[160:163], v[96:99]
	v_mfma_f32_16x16x32_bf16 v[88:91], v[184:187], v[168:171], v[88:91]
	v_mfma_f32_16x16x32_bf16 v[80:83], v[202:205], v[168:171], v[80:83]
	v_mfma_f32_16x16x32_bf16 v[72:75], v[184:187], v[176:179], v[72:75]
	v_mfma_f32_16x16x32_bf16 v[68:71], v[202:205], v[176:179], v[68:71]
	s_barrier
; #define PG8_STAGE(bufoff, gbase, voff) do { _Pragma("unroll") for (int _i = 0; _i < 2; ++_i) \
;         __builtin_amdgcn_global_load_lds((const unsigned*)((const char*)(gbase) + (voff)[_i]), (LAS unsigned*)(lds + (bufoff) + ldsw + _i * 8192), 16, 0, 0); } while (0)
; #define PG8_MMA(ai, bj, At, Bt) do { __builtin_amdgcn_s_setprio(1); _Pragma("unroll") for (int m = 0; m < 4; ++m) _Pragma("unroll") for (int n = 0; n < 2; ++n) _Pragma("unroll") for (int k = 0; k < 2; ++k) \
;         acc[ai][bj][m][n] = __builtin_amdgcn_mfma_f32_16x16x32_bf16(Bt[n][k], At[m][k], acc[ai][bj][m][n], 0, 0, 0); __builtin_amdgcn_s_setprio(0); } while (0)
; #define PG8_WAIT_V(n) asm volatile("s_waitcnt vmcnt(" #n ")" ::: "memory")
; #define PG8_WAIT_L(n) asm volatile("s_waitcnt lgkmcnt(" #n ")" ::: "memory")
; #define PG8_BAR __builtin_amdgcn_s_barrier()
; #define PG8_SCHED __builtin_amdgcn_sched_barrier(0)
;     __device__ __forceinline__ void operator()(const f32x4 (&acc)[2][2][4][2], const Unit& u, int wr, int wc, int, int) const {
;     ...
;         u32x4 cin[2][4][2];
; #pragma unroll
;         for (int ai = 0; ai < 2; ++ai)
; #pragma unroll
;             for (int m = 0; m < 4; ++m)
; #pragma unroll
;                 for (int bj = 0; bj < 2; ++bj) cin[ai][m][bj] = *(const u32x4*)(C + (size_t)(row0 + ai * HALF + m * 16) * ldc + col0 + bj * HALF);
; template <class Epi, class Sched>
; __device__ __forceinline__ void gemm_phase(LAS unsigned char* lds, const Gemm g, const Sched& S, const Epi& E) {
;     ...
;             PG8_BAR; PG8_WAIT_L(0); PG8_MMA(1, 0, At, B0); PG8_BAR; PG8_SCHED;
;             PG8_STAGE(PG8_SB(1, 1), b3 + hstepB, voffB);
;             PG8_WAIT_V(6); PG8_BAR; PG8_MMA(1, 1, At, B1); PG8_BAR;
	s_setprio 0
	ds_read_b128 v[148:151], v224 offset:49152
	ds_read_b128 v[152:155], v224 offset:50176
	ds_read_b128 v[156:159], v224 offset:51200
	ds_read_b128 v[160:163], v224 offset:52224
	ds_read_b128 v[164:167], v224 offset:53248
	ds_read_b128 v[168:171], v224 offset:54272
	ds_read_b128 v[172:175], v224 offset:55296
	ds_read_b128 v[176:179], v224 offset:56320
	s_add_i32 s6, s45, s28
	v_lshl_add_u64 v[206:207], v[206:207], 0, s[8:9]
	s_mov_b32 m0, s6
	s_nop 0
	global_load_lds_dwordx4 v[206:207], off
	v_lshl_add_u64 v[206:207], v[208:209], 0, s[8:9]
	s_add_i32 m0, s6, 0x2000
	s_nop 0
	global_load_lds_dwordx4 v[206:207], off
	s_mov_b32 m0, s38
	v_lshl_add_u64 v[206:207], v[210:211], 0, s[8:9]
	global_load_lds_dwordx4 v[206:207], off
	v_lshl_add_u64 v[206:207], v[212:213], 0, s[8:9]
	s_mov_b32 m0, s39
	s_nop 0
	global_load_lds_dwordx4 v[206:207], off
	s_add_u32 s6, s18, 0x160080
	s_addc_u32 s7, s19, 0
	s_add_i32 s18, s20, s28
	s_mov_b32 m0, s18
	s_nop 0
	global_load_lds_dwordx4 v2, s[6:7]
	s_add_i32 m0, s18, 0x2000
	s_nop 0
	global_load_lds_dwordx4 v192, s[6:7]
	s_add_i32 s44, s44, 2
	s_add_u32 s42, s42, 0x100
	s_addc_u32 s43, s43, 0
	s_cmpk_gt_u32 s44, 0x55
	s_mov_b64 s[6:7], s[14:15]
	s_waitcnt lgkmcnt(0)
	s_waitcnt vmcnt(6)
	s_setprio 1
	s_barrier
	v_mfma_f32_16x16x32_bf16 v[64:67], v[132:135], v[148:151], v[64:67]
	v_mfma_f32_16x16x32_bf16 v[60:63], v[140:143], v[148:151], v[60:63]
	v_mfma_f32_16x16x32_bf16 v[52:55], v[132:135], v[156:159], v[52:55]
	v_mfma_f32_16x16x32_bf16 v[44:47], v[140:143], v[156:159], v[44:47]
	v_mfma_f32_16x16x32_bf16 v[36:39], v[132:135], v[164:167], v[36:39]
	v_mfma_f32_16x16x32_bf16 v[28:31], v[140:143], v[164:167], v[28:31]
	v_mfma_f32_16x16x32_bf16 v[20:23], v[132:135], v[172:175], v[20:23]
	v_mfma_f32_16x16x32_bf16 v[12:15], v[140:143], v[172:175], v[12:15]
	v_mfma_f32_16x16x32_bf16 v[64:67], v[136:139], v[152:155], v[64:67]
	v_mfma_f32_16x16x32_bf16 v[60:63], v[144:147], v[152:155], v[60:63]
	v_mfma_f32_16x16x32_bf16 v[52:55], v[136:139], v[160:163], v[52:55]
	v_mfma_f32_16x16x32_bf16 v[44:47], v[144:147], v[160:163], v[44:47]
	v_mfma_f32_16x16x32_bf16 v[36:39], v[136:139], v[168:171], v[36:39]
	v_mfma_f32_16x16x32_bf16 v[28:31], v[144:147], v[168:171], v[28:31]
	v_mfma_f32_16x16x32_bf16 v[20:23], v[136:139], v[176:179], v[20:23]
	v_mfma_f32_16x16x32_bf16 v[12:15], v[144:147], v[176:179], v[12:15]
	v_mfma_f32_16x16x32_bf16 v[56:59], v[180:183], v[148:151], v[56:59]
	v_mfma_f32_16x16x32_bf16 v[48:51], v[188:191], v[148:151], v[48:51]
	v_mfma_f32_16x16x32_bf16 v[40:43], v[180:183], v[156:159], v[40:43]
	v_mfma_f32_16x16x32_bf16 v[32:35], v[188:191], v[156:159], v[32:35]
	v_mfma_f32_16x16x32_bf16 v[24:27], v[180:183], v[164:167], v[24:27]
	v_mfma_f32_16x16x32_bf16 v[16:19], v[188:191], v[164:167], v[16:19]
	v_mfma_f32_16x16x32_bf16 v[8:11], v[180:183], v[172:175], v[8:11]
	v_mfma_f32_16x16x32_bf16 v[4:7], v[188:191], v[172:175], v[4:7]
	v_mfma_f32_16x16x32_bf16 v[56:59], v[184:187], v[152:155], v[56:59]
	v_mfma_f32_16x16x32_bf16 v[48:51], v[202:205], v[152:155], v[48:51]
	v_mfma_f32_16x16x32_bf16 v[40:43], v[184:187], v[160:163], v[40:43]
	v_mfma_f32_16x16x32_bf16 v[32:35], v[202:205], v[160:163], v[32:35]
	v_mfma_f32_16x16x32_bf16 v[24:27], v[184:187], v[168:171], v[24:27]
	v_mfma_f32_16x16x32_bf16 v[16:19], v[202:205], v[168:171], v[16:19]
	v_mfma_f32_16x16x32_bf16 v[8:11], v[184:187], v[176:179], v[8:11]
	v_mfma_f32_16x16x32_bf16 v[4:7], v[202:205], v[176:179], v[4:7]
	s_barrier
	s_cbranch_scc0 .LBB0_1666
	s_setprio 0
	v_mov_b32_e32 v133, v0
	s_lshl_b32 s6, s50, 8
	s_add_i32 s6, s6, s36
	v_and_or_b32 v132, v133, 15, s6
	s_lshl_b32 s6, s49, 8
	v_lshrrev_b32_e32 v133, 1, v133
	v_and_or_b32 v133, v133, 24, s6
	v_or_b32_e32 v134, s37, v133
	v_ashrrev_i32_e32 v135, 31, v134
	v_lshlrev_b64 v[202:203], 1, v[134:135]
	v_ashrrev_i32_e32 v133, 31, v132
	v_lshl_add_u64 v[134:135], s[88:89], 0, v[202:203]
	v_lshlrev_b64 v[226:227], 12, v[132:133]
	v_lshl_add_u64 v[136:137], v[134:135], 0, v[226:227]
	global_load_dwordx4 v[216:219], v[136:137], off
	global_load_dwordx4 v[188:191], v[136:137], off offset:256
	v_or_b32_e32 v136, 16, v132
	v_ashrrev_i32_e32 v137, 31, v136
	v_lshlrev_b64 v[222:223], 12, v[136:137]
	v_lshl_add_u64 v[136:137], v[134:135], 0, v[222:223]
	global_load_dwordx4 v[184:187], v[136:137], off
	global_load_dwordx4 v[180:183], v[136:137], off offset:256
	v_or_b32_e32 v136, 32, v132
	v_ashrrev_i32_e32 v137, 31, v136
	v_lshlrev_b64 v[220:221], 12, v[136:137]
	v_lshl_add_u64 v[136:137], v[134:135], 0, v[220:221]
	global_load_dwordx4 v[176:179], v[136:137], off
	global_load_dwordx4 v[168:171], v[136:137], off offset:256
	v_or_b32_e32 v132, 48, v132
	v_ashrrev_i32_e32 v133, 31, v132
	v_lshlrev_b64 v[212:213], 12, v[132:133]
	v_lshl_add_u64 v[132:133], v[134:135], 0, v[212:213]
	global_load_dwordx4 v[172:175], v[132:133], off
	global_load_dwordx4 v[164:167], v[132:133], off offset:256
	s_mov_b64 s[6:7], 0x80000
	v_lshl_add_u64 v[210:211], v[226:227], 0, s[6:7]
	v_lshl_add_u64 v[132:133], v[134:135], 0, v[210:211]
	global_load_dwordx4 v[160:163], v[132:133], off
	global_load_dwordx4 v[156:159], v[132:133], off offset:256
	s_mov_b64 s[6:7], 0x90000
	v_lshl_add_u64 v[208:209], v[226:227], 0, s[6:7]
	v_lshl_add_u64 v[132:133], v[134:135], 0, v[208:209]
	global_load_dwordx4 v[152:155], v[132:133], off
	global_load_dwordx4 v[148:151], v[132:133], off offset:256
	s_mov_b64 s[6:7], 0xa0000
	v_lshl_add_u64 v[206:207], v[226:227], 0, s[6:7]
	v_lshl_add_u64 v[132:133], v[134:135], 0, v[206:207]
	global_load_dwordx4 v[144:147], v[132:133], off
	global_load_dwordx4 v[140:143], v[132:133], off offset:256
	s_mov_b64 s[6:7], 0xb0000
	v_lshl_add_u64 v[204:205], v[226:227], 0, s[6:7]
	v_lshl_add_u64 v[132:133], v[134:135], 0, v[204:205]
	global_load_dwordx4 v[136:139], v[132:133], off
	s_nop 0
	global_load_dwordx4 v[132:135], v[132:133], off offset:256
	s_and_b64 vcc, exec, s[40:41]
	s_mov_b32 s49, s47
	s_mov_b32 s50, s48
	s_mov_b64 s[14:15], s[4:5]
	s_mov_b64 s[6:7], s[0:1]
	s_waitcnt vmcnt(15)
; __device__ __forceinline__ unsigned cvt_pk_bf16(float lo, float hi) { const f32x2 v = {lo, hi}; const bf16v2_ r = __builtin_convertvector(v, bf16v2_); return __builtin_bit_cast(unsigned, r); }
; __device__ __forceinline__ float bflo(unsigned w) { return __uint_as_float(w << 16); }
; __device__ __forceinline__ float bfhi(unsigned w) { return __uint_as_float(w & 0xffff0000u); }
;     __device__ __forceinline__ void operator()(const f32x4 (&acc)[2][2][4][2], const Unit& u, int wr, int wc, int, int) const {
;     ...
; #pragma unroll
;         for (int ai = 0; ai < 2; ++ai)
; #pragma unroll
;             for (int m = 0; m < 4; ++m)
; #pragma unroll
;                 for (int bj = 0; bj < 2; ++bj) { const u32x4 c = cin[ai][m][bj]; const f32x4 v0 = acc[ai][bj][m][0], v1 = acc[ai][bj][m][1];
;                     u32x4 w; w.x = cvt_pk_bf16(bflo(c.x) + v0[0], bfhi(c.x) + v0[1]); w.y = cvt_pk_bf16(bflo(c.y) + v0[2], bfhi(c.y) + v0[3]);
;                     w.z = cvt_pk_bf16(bflo(c.z) + v1[0], bfhi(c.z) + v1[1]); w.w = cvt_pk_bf16(bflo(c.w) + v1[2], bfhi(c.w) + v1[3]);
;                     *(u32x4*)(C + (size_t)(row0 + ai * HALF + m * 16) * ldc + col0 + bj * HALF) = w; }
	v_lshlrev_b32_e32 v228, 16, v216
	v_and_b32_e32 v229, 0xffff0000, v216
	v_lshlrev_b32_e32 v216, 16, v217
	v_and_b32_e32 v217, 0xffff0000, v217
	v_pk_add_f32 v[128:129], v[128:129], v[228:229]
	v_pk_add_f32 v[130:131], v[130:131], v[216:217]
	v_cvt_pk_bf16_f32 v128, v128, v129
	v_cvt_pk_bf16_f32 v129, v130, v131
	v_lshlrev_b32_e32 v130, 16, v218
	v_and_b32_e32 v131, 0xffff0000, v218
	v_pk_add_f32 v[124:125], v[124:125], v[130:131]
	s_nop 0
	v_cvt_pk_bf16_f32 v130, v124, v125
	v_lshlrev_b32_e32 v124, 16, v219
	v_and_b32_e32 v125, 0xffff0000, v219
	v_pk_add_f32 v[124:125], v[126:127], v[124:125]
	s_waitcnt vmcnt(14)
	v_lshlrev_b32_e32 v126, 16, v188
	v_and_b32_e32 v127, 0xffff0000, v188
	v_pk_add_f32 v[120:121], v[120:121], v[126:127]
	v_lshlrev_b32_e32 v126, 16, v189
	v_and_b32_e32 v127, 0xffff0000, v189
	v_pk_add_f32 v[122:123], v[122:123], v[126:127]
	v_cvt_pk_bf16_f32 v120, v120, v121
	v_cvt_pk_bf16_f32 v121, v122, v123
	v_lshlrev_b32_e32 v122, 16, v190
	v_and_b32_e32 v123, 0xffff0000, v190
	v_pk_add_f32 v[116:117], v[116:117], v[122:123]
	v_cvt_pk_bf16_f32 v131, v124, v125
	v_cvt_pk_bf16_f32 v122, v116, v117
	v_lshlrev_b32_e32 v116, 16, v191
	v_and_b32_e32 v117, 0xffff0000, v191
	v_pk_add_f32 v[116:117], v[118:119], v[116:117]
	v_lshl_add_u64 v[124:125], s[88:89], 0, v[226:227]
	v_cvt_pk_bf16_f32 v123, v116, v117
	s_waitcnt vmcnt(13)
	v_lshlrev_b32_e32 v116, 16, v184
	v_and_b32_e32 v117, 0xffff0000, v184
	v_pk_add_f32 v[112:113], v[112:113], v[116:117]
	v_lshlrev_b32_e32 v116, 16, v185
	v_and_b32_e32 v117, 0xffff0000, v185
	v_pk_add_f32 v[114:115], v[114:115], v[116:117]
	v_cvt_pk_bf16_f32 v112, v112, v113
	v_cvt_pk_bf16_f32 v113, v114, v115
	v_lshlrev_b32_e32 v114, 16, v186
	v_and_b32_e32 v115, 0xffff0000, v186
	v_pk_add_f32 v[108:109], v[108:109], v[114:115]
	v_lshl_add_u64 v[124:125], v[124:125], 0, v[202:203]
	v_cvt_pk_bf16_f32 v114, v108, v109
	v_lshlrev_b32_e32 v108, 16, v187
	v_and_b32_e32 v109, 0xffff0000, v187
	v_pk_add_f32 v[108:109], v[110:111], v[108:109]
	s_waitcnt vmcnt(12)
	v_lshlrev_b32_e32 v110, 16, v180
	v_and_b32_e32 v111, 0xffff0000, v180
	v_pk_add_f32 v[104:105], v[104:105], v[110:111]
	v_lshlrev_b32_e32 v110, 16, v181
	v_and_b32_e32 v111, 0xffff0000, v181
	v_pk_add_f32 v[106:107], v[106:107], v[110:111]
	v_cvt_pk_bf16_f32 v104, v104, v105
	v_cvt_pk_bf16_f32 v105, v106, v107
	v_lshlrev_b32_e32 v106, 16, v182
	v_and_b32_e32 v107, 0xffff0000, v182
	v_pk_add_f32 v[96:97], v[96:97], v[106:107]
	v_cvt_pk_bf16_f32 v115, v108, v109
	v_cvt_pk_bf16_f32 v106, v96, v97
	v_lshlrev_b32_e32 v96, 16, v183
	v_and_b32_e32 v97, 0xffff0000, v183
	v_pk_add_f32 v[96:97], v[98:99], v[96:97]
	s_waitcnt vmcnt(11)
	v_lshlrev_b32_e32 v98, 16, v177
	v_cvt_pk_bf16_f32 v107, v96, v97
	v_lshlrev_b32_e32 v96, 16, v176
	v_and_b32_e32 v97, 0xffff0000, v176
	v_and_b32_e32 v99, 0xffff0000, v177
	v_pk_add_f32 v[96:97], v[100:101], v[96:97]
	v_pk_add_f32 v[98:99], v[102:103], v[98:99]
	v_cvt_pk_bf16_f32 v96, v96, v97
	v_cvt_pk_bf16_f32 v97, v98, v99
	v_lshlrev_b32_e32 v98, 16, v178
	v_and_b32_e32 v99, 0xffff0000, v178
	v_pk_add_f32 v[92:93], v[92:93], v[98:99]
	v_lshl_add_u64 v[108:109], s[88:89], 0, v[222:223]
	v_cvt_pk_bf16_f32 v98, v92, v93
	v_lshlrev_b32_e32 v92, 16, v179
	v_and_b32_e32 v93, 0xffff0000, v179
	v_pk_add_f32 v[92:93], v[94:95], v[92:93]
	s_waitcnt vmcnt(10)
	v_lshlrev_b32_e32 v94, 16, v168
	v_and_b32_e32 v95, 0xffff0000, v168
	v_pk_add_f32 v[88:89], v[88:89], v[94:95]
	v_lshlrev_b32_e32 v94, 16, v169
	v_and_b32_e32 v95, 0xffff0000, v169
	v_pk_add_f32 v[90:91], v[90:91], v[94:95]
	v_cvt_pk_bf16_f32 v88, v88, v89
	v_cvt_pk_bf16_f32 v89, v90, v91
	v_lshlrev_b32_e32 v90, 16, v170
	v_and_b32_e32 v91, 0xffff0000, v170
	v_pk_add_f32 v[80:81], v[80:81], v[90:91]
	v_cvt_pk_bf16_f32 v99, v92, v93
	v_cvt_pk_bf16_f32 v90, v80, v81
	v_lshlrev_b32_e32 v80, 16, v171
	v_and_b32_e32 v81, 0xffff0000, v171
	v_pk_add_f32 v[80:81], v[82:83], v[80:81]
	s_waitcnt vmcnt(9)
	v_lshlrev_b32_e32 v82, 16, v173
	v_cvt_pk_bf16_f32 v91, v80, v81
	v_lshlrev_b32_e32 v80, 16, v172
	v_and_b32_e32 v81, 0xffff0000, v172
	v_and_b32_e32 v83, 0xffff0000, v173
	v_pk_add_f32 v[80:81], v[84:85], v[80:81]
	v_pk_add_f32 v[82:83], v[86:87], v[82:83]
	v_cvt_pk_bf16_f32 v80, v80, v81
	v_cvt_pk_bf16_f32 v81, v82, v83
	v_lshlrev_b32_e32 v82, 16, v174
	v_and_b32_e32 v83, 0xffff0000, v174
	v_pk_add_f32 v[76:77], v[76:77], v[82:83]
	v_lshl_add_u64 v[92:93], s[88:89], 0, v[220:221]
	v_cvt_pk_bf16_f32 v82, v76, v77
	v_lshlrev_b32_e32 v76, 16, v175
	v_and_b32_e32 v77, 0xffff0000, v175
	v_pk_add_f32 v[76:77], v[78:79], v[76:77]
	s_waitcnt vmcnt(8)
	v_lshlrev_b32_e32 v78, 16, v164
	v_and_b32_e32 v79, 0xffff0000, v164
	v_pk_add_f32 v[72:73], v[72:73], v[78:79]
	v_lshlrev_b32_e32 v78, 16, v165
	v_and_b32_e32 v79, 0xffff0000, v165
	v_pk_add_f32 v[74:75], v[74:75], v[78:79]
	v_cvt_pk_bf16_f32 v72, v72, v73
	v_cvt_pk_bf16_f32 v73, v74, v75
	v_lshlrev_b32_e32 v74, 16, v166
	v_and_b32_e32 v75, 0xffff0000, v166
	v_pk_add_f32 v[68:69], v[68:69], v[74:75]
	v_cvt_pk_bf16_f32 v83, v76, v77
	v_cvt_pk_bf16_f32 v74, v68, v69
	v_lshlrev_b32_e32 v68, 16, v167
	v_and_b32_e32 v69, 0xffff0000, v167
	v_pk_add_f32 v[68:69], v[70:71], v[68:69]
	v_lshl_add_u64 v[76:77], s[88:89], 0, v[212:213]
	v_cvt_pk_bf16_f32 v75, v68, v69
	s_waitcnt vmcnt(7)
	v_lshlrev_b32_e32 v68, 16, v160
	v_and_b32_e32 v69, 0xffff0000, v160
	v_pk_add_f32 v[64:65], v[64:65], v[68:69]
	v_lshlrev_b32_e32 v68, 16, v161
	v_and_b32_e32 v69, 0xffff0000, v161
	v_pk_add_f32 v[66:67], v[66:67], v[68:69]
	v_cvt_pk_bf16_f32 v64, v64, v65
	v_cvt_pk_bf16_f32 v65, v66, v67
	v_lshlrev_b32_e32 v66, 16, v162
	v_and_b32_e32 v67, 0xffff0000, v162
	v_pk_add_f32 v[60:61], v[60:61], v[66:67]
	v_lshl_add_u64 v[108:109], v[108:109], 0, v[202:203]
	v_cvt_pk_bf16_f32 v66, v60, v61
	v_lshlrev_b32_e32 v60, 16, v163
	v_and_b32_e32 v61, 0xffff0000, v163
	v_pk_add_f32 v[60:61], v[62:63], v[60:61]
	s_waitcnt vmcnt(6)
; __device__ __forceinline__ unsigned cvt_pk_bf16(float lo, float hi) { const f32x2 v = {lo, hi}; const bf16v2_ r = __builtin_convertvector(v, bf16v2_); return __builtin_bit_cast(unsigned, r); }
; __device__ __forceinline__ float bflo(unsigned w) { return __uint_as_float(w << 16); }
; __device__ __forceinline__ float bfhi(unsigned w) { return __uint_as_float(w & 0xffff0000u); }
;     __device__ __forceinline__ void operator()(const f32x4 (&acc)[2][2][4][2], const Unit& u, int wr, int wc, int, int) const {
;     ...
;                 for (int bj = 0; bj < 2; ++bj) { const u32x4 c = cin[ai][m][bj]; const f32x4 v0 = acc[ai][bj][m][0], v1 = acc[ai][bj][m][1];
;                     u32x4 w; w.x = cvt_pk_bf16(bflo(c.x) + v0[0], bfhi(c.x) + v0[1]); w.y = cvt_pk_bf16(bflo(c.y) + v0[2], bfhi(c.y) + v0[3]);
;                     w.z = cvt_pk_bf16(bflo(c.z) + v1[0], bfhi(c.z) + v1[1]); w.w = cvt_pk_bf16(bflo(c.w) + v1[2], bfhi(c.w) + v1[3]);
;                     *(u32x4*)(C + (size_t)(row0 + ai * HALF + m * 16) * ldc + col0 + bj * HALF) = w; }
	v_lshlrev_b32_e32 v62, 16, v156
	v_and_b32_e32 v63, 0xffff0000, v156
	v_pk_add_f32 v[56:57], v[56:57], v[62:63]
	v_lshlrev_b32_e32 v62, 16, v157
	v_and_b32_e32 v63, 0xffff0000, v157
	v_pk_add_f32 v[58:59], v[58:59], v[62:63]
	v_cvt_pk_bf16_f32 v56, v56, v57
	v_cvt_pk_bf16_f32 v57, v58, v59
	v_lshlrev_b32_e32 v58, 16, v158
	v_and_b32_e32 v59, 0xffff0000, v158
	v_pk_add_f32 v[48:49], v[48:49], v[58:59]
	v_cvt_pk_bf16_f32 v67, v60, v61
	v_cvt_pk_bf16_f32 v58, v48, v49
	v_lshlrev_b32_e32 v48, 16, v159
	v_and_b32_e32 v49, 0xffff0000, v159
	v_pk_add_f32 v[48:49], v[50:51], v[48:49]
	s_waitcnt vmcnt(5)
	v_lshlrev_b32_e32 v50, 16, v153
	v_cvt_pk_bf16_f32 v59, v48, v49
	v_lshlrev_b32_e32 v48, 16, v152
	v_and_b32_e32 v49, 0xffff0000, v152
	v_and_b32_e32 v51, 0xffff0000, v153
	v_pk_add_f32 v[48:49], v[52:53], v[48:49]
	v_pk_add_f32 v[50:51], v[54:55], v[50:51]
	v_cvt_pk_bf16_f32 v48, v48, v49
	v_cvt_pk_bf16_f32 v49, v50, v51
	v_lshlrev_b32_e32 v50, 16, v154
	v_and_b32_e32 v51, 0xffff0000, v154
	v_pk_add_f32 v[44:45], v[44:45], v[50:51]
	v_lshl_add_u64 v[60:61], s[88:89], 0, v[210:211]
	v_cvt_pk_bf16_f32 v50, v44, v45
	v_lshlrev_b32_e32 v44, 16, v155
	v_and_b32_e32 v45, 0xffff0000, v155
	v_pk_add_f32 v[44:45], v[46:47], v[44:45]
	s_waitcnt vmcnt(4)
	v_lshlrev_b32_e32 v46, 16, v148
	v_and_b32_e32 v47, 0xffff0000, v148
	v_pk_add_f32 v[40:41], v[40:41], v[46:47]
	v_lshlrev_b32_e32 v46, 16, v149
	v_and_b32_e32 v47, 0xffff0000, v149
	v_pk_add_f32 v[42:43], v[42:43], v[46:47]
	v_cvt_pk_bf16_f32 v40, v40, v41
	v_cvt_pk_bf16_f32 v41, v42, v43
	v_lshlrev_b32_e32 v42, 16, v150
	v_and_b32_e32 v43, 0xffff0000, v150
	v_pk_add_f32 v[32:33], v[32:33], v[42:43]
	v_cvt_pk_bf16_f32 v51, v44, v45
	v_cvt_pk_bf16_f32 v42, v32, v33
	v_lshlrev_b32_e32 v32, 16, v151
	v_and_b32_e32 v33, 0xffff0000, v151
	v_pk_add_f32 v[32:33], v[34:35], v[32:33]
	s_waitcnt vmcnt(3)
	v_lshlrev_b32_e32 v34, 16, v145
	v_cvt_pk_bf16_f32 v43, v32, v33
	v_lshlrev_b32_e32 v32, 16, v144
	v_and_b32_e32 v33, 0xffff0000, v144
	v_and_b32_e32 v35, 0xffff0000, v145
	v_pk_add_f32 v[32:33], v[36:37], v[32:33]
	v_pk_add_f32 v[34:35], v[38:39], v[34:35]
	v_cvt_pk_bf16_f32 v32, v32, v33
	v_cvt_pk_bf16_f32 v33, v34, v35
	v_lshlrev_b32_e32 v34, 16, v146
	v_and_b32_e32 v35, 0xffff0000, v146
	v_pk_add_f32 v[28:29], v[28:29], v[34:35]
	v_lshl_add_u64 v[44:45], s[88:89], 0, v[208:209]
	v_cvt_pk_bf16_f32 v34, v28, v29
	v_lshlrev_b32_e32 v28, 16, v147
	v_and_b32_e32 v29, 0xffff0000, v147
	v_pk_add_f32 v[28:29], v[30:31], v[28:29]
	s_waitcnt vmcnt(2)
	v_lshlrev_b32_e32 v30, 16, v140
	v_and_b32_e32 v31, 0xffff0000, v140
	v_pk_add_f32 v[24:25], v[24:25], v[30:31]
	v_lshlrev_b32_e32 v30, 16, v141
	v_and_b32_e32 v31, 0xffff0000, v141
	v_pk_add_f32 v[26:27], v[26:27], v[30:31]
	v_cvt_pk_bf16_f32 v24, v24, v25
	v_cvt_pk_bf16_f32 v25, v26, v27
	v_lshlrev_b32_e32 v26, 16, v142
	v_and_b32_e32 v27, 0xffff0000, v142
	v_pk_add_f32 v[16:17], v[16:17], v[26:27]
	v_cvt_pk_bf16_f32 v35, v28, v29
	v_cvt_pk_bf16_f32 v26, v16, v17
	v_lshlrev_b32_e32 v16, 16, v143
	v_and_b32_e32 v17, 0xffff0000, v143
	v_pk_add_f32 v[16:17], v[18:19], v[16:17]
	s_waitcnt vmcnt(1)
	v_lshlrev_b32_e32 v18, 16, v137
	v_cvt_pk_bf16_f32 v27, v16, v17
	v_lshlrev_b32_e32 v16, 16, v136
	v_and_b32_e32 v17, 0xffff0000, v136
	v_and_b32_e32 v19, 0xffff0000, v137
	v_pk_add_f32 v[16:17], v[20:21], v[16:17]
	v_pk_add_f32 v[18:19], v[22:23], v[18:19]
	v_cvt_pk_bf16_f32 v16, v16, v17
	v_cvt_pk_bf16_f32 v17, v18, v19
	v_lshlrev_b32_e32 v18, 16, v138
	v_and_b32_e32 v19, 0xffff0000, v138
	v_pk_add_f32 v[12:13], v[12:13], v[18:19]
	v_lshl_add_u64 v[28:29], s[88:89], 0, v[206:207]
	v_cvt_pk_bf16_f32 v18, v12, v13
	v_lshlrev_b32_e32 v12, 16, v139
	v_and_b32_e32 v13, 0xffff0000, v139
	v_pk_add_f32 v[12:13], v[14:15], v[12:13]
	s_waitcnt vmcnt(0)
	v_lshlrev_b32_e32 v14, 16, v132
	v_and_b32_e32 v15, 0xffff0000, v132
	v_pk_add_f32 v[8:9], v[8:9], v[14:15]
	v_lshlrev_b32_e32 v14, 16, v133
	v_and_b32_e32 v15, 0xffff0000, v133
	v_pk_add_f32 v[10:11], v[10:11], v[14:15]
	v_cvt_pk_bf16_f32 v8, v8, v9
	v_cvt_pk_bf16_f32 v9, v10, v11
	v_lshlrev_b32_e32 v10, 16, v134
	v_and_b32_e32 v11, 0xffff0000, v134
	v_pk_add_f32 v[4:5], v[4:5], v[10:11]
	v_cvt_pk_bf16_f32 v19, v12, v13
	v_cvt_pk_bf16_f32 v10, v4, v5
	v_lshlrev_b32_e32 v4, 16, v135
	v_and_b32_e32 v5, 0xffff0000, v135
	v_lshl_add_u64 v[12:13], s[88:89], 0, v[204:205]
	v_pk_add_f32 v[4:5], v[6:7], v[4:5]
	v_lshl_add_u64 v[92:93], v[92:93], 0, v[202:203]
	v_lshl_add_u64 v[76:77], v[76:77], 0, v[202:203]
	v_lshl_add_u64 v[60:61], v[60:61], 0, v[202:203]
	v_lshl_add_u64 v[44:45], v[44:45], 0, v[202:203]
	v_lshl_add_u64 v[28:29], v[28:29], 0, v[202:203]
	v_lshl_add_u64 v[12:13], v[12:13], 0, v[202:203]
	v_cvt_pk_bf16_f32 v11, v4, v5
	global_store_dwordx4 v[124:125], v[128:131], off
	global_store_dwordx4 v[124:125], v[120:123], off offset:256
	global_store_dwordx4 v[108:109], v[112:115], off
	global_store_dwordx4 v[108:109], v[104:107], off offset:256
	global_store_dwordx4 v[92:93], v[96:99], off
	global_store_dwordx4 v[92:93], v[88:91], off offset:256
	global_store_dwordx4 v[76:77], v[80:83], off
	global_store_dwordx4 v[76:77], v[72:75], off offset:256
	global_store_dwordx4 v[60:61], v[64:67], off
	global_store_dwordx4 v[60:61], v[56:59], off offset:256
	global_store_dwordx4 v[44:45], v[48:51], off
	global_store_dwordx4 v[44:45], v[40:43], off offset:256
	global_store_dwordx4 v[28:29], v[32:35], off
	global_store_dwordx4 v[28:29], v[24:27], off offset:256
	global_store_dwordx4 v[12:13], v[16:19], off
	global_store_dwordx4 v[12:13], v[8:11], off offset:256
	v_subrev_u32_e32 v216, s88, v124
	v_bfe_u32 v217, v216, 4, 8
	v_lshrrev_b32_e32 v216, 12, v216
; __device__ __forceinline__ unsigned cvt_pk_bf16(float lo, float hi) { const f32x2 v = {lo, hi}; const bf16v2_ r = __builtin_convertvector(v, bf16v2_); return __builtin_bit_cast(unsigned, r); }
; __device__ __forceinline__ float bflo(unsigned w) { return __uint_as_float(w << 16); }
; __device__ __forceinline__ float bfhi(unsigned w) { return __uint_as_float(w & 0xffff0000u); }
; __device__ __forceinline__ float wave_sum(float v) { v = row16_sum(v); v += shx(v, 16); v += shx(v, 32); return v; }
;     __device__ __forceinline__ void operator()(const f32x4 (&acc)[2][2][4][2], const Unit& u, int wr, int wc, int, int) const {
;     ...
;                 for (int bj = 0; bj < 2; ++bj) { const u32x4 c = cin[ai][m][bj]; const f32x4 v0 = acc[ai][bj][m][0], v1 = acc[ai][bj][m][1];
;                     u32x4 w; w.x = cvt_pk_bf16(bflo(c.x) + v0[0], bfhi(c.x) + v0[1]); w.y = cvt_pk_bf16(bflo(c.y) + v0[2], bfhi(c.y) + v0[3]);
;                     w.z = cvt_pk_bf16(bflo(c.z) + v1[0], bfhi(c.z) + v1[1]); w.w = cvt_pk_bf16(bflo(c.w) + v1[2], bfhi(c.w) + v1[3]);
;                     *(u32x4*)(C + (size_t)(row0 + ai * HALF + m * 16) * ldc + col0 + bj * HALF) = w; }
; __device__ __forceinline__ void rowstat_phase(const Frame& F, const bf16_t* __restrict__ res, float* __restrict__ rstd_out) {
;     ...
;         for (int r = 0; r < 4; ++r) { ss[r] = 0.f;
; #pragma unroll
;             for (int i = 0; i < 4; ++i) { const u32x4 x = v[r][i];
;                 ss[r] += bflo(x.x) * bflo(x.x) + bfhi(x.x) * bfhi(x.x) + bflo(x.y) * bflo(x.y) + bfhi(x.y) * bfhi(x.y) + bflo(x.z) * bflo(x.z) + bfhi(x.z) * bfhi(x.z) + bflo(x.w) * bflo(x.w) + bfhi(x.w) * bfhi(x.w); }
;             ss[r] = wave_sum(ss[r]); }
	v_and_b32_e32 v218, 15, v217
	v_lshrrev_b32_e32 v217, 5, v217
	v_lshl_or_b32 v217, v217, 4, v218
	v_lshlrev_b32_e32 v217, 17, v217
	v_lshl_add_u32 v216, v216, 2, v217
	v_add_u32_e32 v216, 0x1e000000, v216
	v_lshlrev_b32_e32 v218, 16, v128
	v_and_b32_e32 v219, 0xffff0000, v128
	v_mul_f32_e32 v188, v218, v218
	v_fmac_f32_e32 v188, v219, v219
	v_lshlrev_b32_e32 v218, 16, v129
	v_and_b32_e32 v219, 0xffff0000, v129
	v_fmac_f32_e32 v188, v218, v218
	v_fmac_f32_e32 v188, v219, v219
	v_lshlrev_b32_e32 v218, 16, v130
	v_and_b32_e32 v219, 0xffff0000, v130
	v_fmac_f32_e32 v188, v218, v218
	v_fmac_f32_e32 v188, v219, v219
	v_lshlrev_b32_e32 v218, 16, v131
	v_and_b32_e32 v219, 0xffff0000, v131
	v_fmac_f32_e32 v188, v218, v218
	v_fmac_f32_e32 v188, v219, v219
	v_lshlrev_b32_e32 v218, 16, v120
	v_and_b32_e32 v219, 0xffff0000, v120
	v_fmac_f32_e32 v188, v218, v218
	v_fmac_f32_e32 v188, v219, v219
	v_lshlrev_b32_e32 v218, 16, v121
	v_and_b32_e32 v219, 0xffff0000, v121
	v_fmac_f32_e32 v188, v218, v218
	v_fmac_f32_e32 v188, v219, v219
	v_lshlrev_b32_e32 v218, 16, v122
	v_and_b32_e32 v219, 0xffff0000, v122
	v_fmac_f32_e32 v188, v218, v218
	v_fmac_f32_e32 v188, v219, v219
	v_lshlrev_b32_e32 v218, 16, v123
	v_and_b32_e32 v219, 0xffff0000, v123
	v_fmac_f32_e32 v188, v218, v218
	v_fmac_f32_e32 v188, v219, v219
	global_store_dword v216, v188, s[88:89]
	v_lshlrev_b32_e32 v218, 16, v112
	v_and_b32_e32 v219, 0xffff0000, v112
	v_mul_f32_e32 v189, v218, v218
	v_fmac_f32_e32 v189, v219, v219
	v_lshlrev_b32_e32 v218, 16, v113
	v_and_b32_e32 v219, 0xffff0000, v113
	v_fmac_f32_e32 v189, v218, v218
	v_fmac_f32_e32 v189, v219, v219
	v_lshlrev_b32_e32 v218, 16, v114
	v_and_b32_e32 v219, 0xffff0000, v114
	v_fmac_f32_e32 v189, v218, v218
	v_fmac_f32_e32 v189, v219, v219
	v_lshlrev_b32_e32 v218, 16, v115
	v_and_b32_e32 v219, 0xffff0000, v115
	v_fmac_f32_e32 v189, v218, v218
	v_fmac_f32_e32 v189, v219, v219
	v_lshlrev_b32_e32 v218, 16, v104
	v_and_b32_e32 v219, 0xffff0000, v104
	v_fmac_f32_e32 v189, v218, v218
	v_fmac_f32_e32 v189, v219, v219
	v_lshlrev_b32_e32 v218, 16, v105
	v_and_b32_e32 v219, 0xffff0000, v105
	v_fmac_f32_e32 v189, v218, v218
	v_fmac_f32_e32 v189, v219, v219
	v_lshlrev_b32_e32 v218, 16, v106
	v_and_b32_e32 v219, 0xffff0000, v106
	v_fmac_f32_e32 v189, v218, v218
	v_fmac_f32_e32 v189, v219, v219
	v_lshlrev_b32_e32 v218, 16, v107
	v_and_b32_e32 v219, 0xffff0000, v107
	v_fmac_f32_e32 v189, v218, v218
	v_fmac_f32_e32 v189, v219, v219
	global_store_dword v216, v189, s[88:89] offset:64
	v_lshlrev_b32_e32 v218, 16, v96
	v_and_b32_e32 v219, 0xffff0000, v96
	v_mul_f32_e32 v188, v218, v218
	v_fmac_f32_e32 v188, v219, v219
	v_lshlrev_b32_e32 v218, 16, v97
	v_and_b32_e32 v219, 0xffff0000, v97
	v_fmac_f32_e32 v188, v218, v218
	v_fmac_f32_e32 v188, v219, v219
	v_lshlrev_b32_e32 v218, 16, v98
	v_and_b32_e32 v219, 0xffff0000, v98
	v_fmac_f32_e32 v188, v218, v218
	v_fmac_f32_e32 v188, v219, v219
	v_lshlrev_b32_e32 v218, 16, v99
	v_and_b32_e32 v219, 0xffff0000, v99
	v_fmac_f32_e32 v188, v218, v218
	v_fmac_f32_e32 v188, v219, v219
	v_lshlrev_b32_e32 v218, 16, v88
	v_and_b32_e32 v219, 0xffff0000, v88
	v_fmac_f32_e32 v188, v218, v218
	v_fmac_f32_e32 v188, v219, v219
	v_lshlrev_b32_e32 v218, 16, v89
	v_and_b32_e32 v219, 0xffff0000, v89
	v_fmac_f32_e32 v188, v218, v218
	v_fmac_f32_e32 v188, v219, v219
	v_lshlrev_b32_e32 v218, 16, v90
	v_and_b32_e32 v219, 0xffff0000, v90
	v_fmac_f32_e32 v188, v218, v218
	v_fmac_f32_e32 v188, v219, v219
	v_lshlrev_b32_e32 v218, 16, v91
	v_and_b32_e32 v219, 0xffff0000, v91
	v_fmac_f32_e32 v188, v218, v218
	v_fmac_f32_e32 v188, v219, v219
	global_store_dword v216, v188, s[88:89] offset:128
	v_lshlrev_b32_e32 v218, 16, v80
	v_and_b32_e32 v219, 0xffff0000, v80
	v_mul_f32_e32 v189, v218, v218
	v_fmac_f32_e32 v189, v219, v219
	v_lshlrev_b32_e32 v218, 16, v81
	v_and_b32_e32 v219, 0xffff0000, v81
	v_fmac_f32_e32 v189, v218, v218
	v_fmac_f32_e32 v189, v219, v219
	v_lshlrev_b32_e32 v218, 16, v82
	v_and_b32_e32 v219, 0xffff0000, v82
	v_fmac_f32_e32 v189, v218, v218
	v_fmac_f32_e32 v189, v219, v219
	v_lshlrev_b32_e32 v218, 16, v83
	v_and_b32_e32 v219, 0xffff0000, v83
	v_fmac_f32_e32 v189, v218, v218
	v_fmac_f32_e32 v189, v219, v219
	v_lshlrev_b32_e32 v218, 16, v72
	v_and_b32_e32 v219, 0xffff0000, v72
	v_fmac_f32_e32 v189, v218, v218
	v_fmac_f32_e32 v189, v219, v219
	v_lshlrev_b32_e32 v218, 16, v73
	v_and_b32_e32 v219, 0xffff0000, v73
	v_fmac_f32_e32 v189, v218, v218
	v_fmac_f32_e32 v189, v219, v219
	v_lshlrev_b32_e32 v218, 16, v74
	v_and_b32_e32 v219, 0xffff0000, v74
	v_fmac_f32_e32 v189, v218, v218
	v_fmac_f32_e32 v189, v219, v219
	v_lshlrev_b32_e32 v218, 16, v75
	v_and_b32_e32 v219, 0xffff0000, v75
	v_fmac_f32_e32 v189, v218, v218
	v_fmac_f32_e32 v189, v219, v219
; __device__ __forceinline__ unsigned cvt_pk_bf16(float lo, float hi) { const f32x2 v = {lo, hi}; const bf16v2_ r = __builtin_convertvector(v, bf16v2_); return __builtin_bit_cast(unsigned, r); }
; __device__ __forceinline__ float bflo(unsigned w) { return __uint_as_float(w << 16); }
; __device__ __forceinline__ float bfhi(unsigned w) { return __uint_as_float(w & 0xffff0000u); }
; __device__ __forceinline__ float wave_sum(float v) { v = row16_sum(v); v += shx(v, 16); v += shx(v, 32); return v; }
;     __device__ __forceinline__ void operator()(const f32x4 (&acc)[2][2][4][2], const Unit& u, int wr, int wc, int, int) const {
;     ...
;                 for (int bj = 0; bj < 2; ++bj) { const u32x4 c = cin[ai][m][bj]; const f32x4 v0 = acc[ai][bj][m][0], v1 = acc[ai][bj][m][1];
;                     u32x4 w; w.x = cvt_pk_bf16(bflo(c.x) + v0[0], bfhi(c.x) + v0[1]); w.y = cvt_pk_bf16(bflo(c.y) + v0[2], bfhi(c.y) + v0[3]);
;                     w.z = cvt_pk_bf16(bflo(c.z) + v1[0], bfhi(c.z) + v1[1]); w.w = cvt_pk_bf16(bflo(c.w) + v1[2], bfhi(c.w) + v1[3]);
;                     *(u32x4*)(C + (size_t)(row0 + ai * HALF + m * 16) * ldc + col0 + bj * HALF) = w; }
; __device__ __forceinline__ void rowstat_phase(const Frame& F, const bf16_t* __restrict__ res, float* __restrict__ rstd_out) {
;     ...
;         for (int r = 0; r < 4; ++r) { ss[r] = 0.f;
; #pragma unroll
;             for (int i = 0; i < 4; ++i) { const u32x4 x = v[r][i];
;                 ss[r] += bflo(x.x) * bflo(x.x) + bfhi(x.x) * bfhi(x.x) + bflo(x.y) * bflo(x.y) + bfhi(x.y) * bfhi(x.y) + bflo(x.z) * bflo(x.z) + bfhi(x.z) * bfhi(x.z) + bflo(x.w) * bflo(x.w) + bfhi(x.w) * bfhi(x.w); }
;             ss[r] = wave_sum(ss[r]); }
	global_store_dword v216, v189, s[88:89] offset:192
	v_lshlrev_b32_e32 v218, 16, v64
	v_and_b32_e32 v219, 0xffff0000, v64
	v_mul_f32_e32 v188, v218, v218
	v_fmac_f32_e32 v188, v219, v219
	v_lshlrev_b32_e32 v218, 16, v65
	v_and_b32_e32 v219, 0xffff0000, v65
	v_fmac_f32_e32 v188, v218, v218
	v_fmac_f32_e32 v188, v219, v219
	v_lshlrev_b32_e32 v218, 16, v66
	v_and_b32_e32 v219, 0xffff0000, v66
	v_fmac_f32_e32 v188, v218, v218
	v_fmac_f32_e32 v188, v219, v219
	v_lshlrev_b32_e32 v218, 16, v67
	v_and_b32_e32 v219, 0xffff0000, v67
	v_fmac_f32_e32 v188, v218, v218
	v_fmac_f32_e32 v188, v219, v219
	v_lshlrev_b32_e32 v218, 16, v56
	v_and_b32_e32 v219, 0xffff0000, v56
	v_fmac_f32_e32 v188, v218, v218
	v_fmac_f32_e32 v188, v219, v219
	v_lshlrev_b32_e32 v218, 16, v57
	v_and_b32_e32 v219, 0xffff0000, v57
	v_fmac_f32_e32 v188, v218, v218
	v_fmac_f32_e32 v188, v219, v219
	v_lshlrev_b32_e32 v218, 16, v58
	v_and_b32_e32 v219, 0xffff0000, v58
	v_fmac_f32_e32 v188, v218, v218
	v_fmac_f32_e32 v188, v219, v219
	v_lshlrev_b32_e32 v218, 16, v59
	v_and_b32_e32 v219, 0xffff0000, v59
	v_fmac_f32_e32 v188, v218, v218
	v_fmac_f32_e32 v188, v219, v219
	global_store_dword v216, v188, s[88:89] offset:512
	v_lshlrev_b32_e32 v218, 16, v48
	v_and_b32_e32 v219, 0xffff0000, v48
	v_mul_f32_e32 v189, v218, v218
	v_fmac_f32_e32 v189, v219, v219
	v_lshlrev_b32_e32 v218, 16, v49
	v_and_b32_e32 v219, 0xffff0000, v49
	v_fmac_f32_e32 v189, v218, v218
	v_fmac_f32_e32 v189, v219, v219
	v_lshlrev_b32_e32 v218, 16, v50
	v_and_b32_e32 v219, 0xffff0000, v50
	v_fmac_f32_e32 v189, v218, v218
	v_fmac_f32_e32 v189, v219, v219
	v_lshlrev_b32_e32 v218, 16, v51
	v_and_b32_e32 v219, 0xffff0000, v51
	v_fmac_f32_e32 v189, v218, v218
	v_fmac_f32_e32 v189, v219, v219
	v_lshlrev_b32_e32 v218, 16, v40
	v_and_b32_e32 v219, 0xffff0000, v40
	v_fmac_f32_e32 v189, v218, v218
	v_fmac_f32_e32 v189, v219, v219
	v_lshlrev_b32_e32 v218, 16, v41
	v_and_b32_e32 v219, 0xffff0000, v41
	v_fmac_f32_e32 v189, v218, v218
	v_fmac_f32_e32 v189, v219, v219
	v_lshlrev_b32_e32 v218, 16, v42
	v_and_b32_e32 v219, 0xffff0000, v42
	v_fmac_f32_e32 v189, v218, v218
	v_fmac_f32_e32 v189, v219, v219
	v_lshlrev_b32_e32 v218, 16, v43
	v_and_b32_e32 v219, 0xffff0000, v43
	v_fmac_f32_e32 v189, v218, v218
	v_fmac_f32_e32 v189, v219, v219
	global_store_dword v216, v189, s[88:89] offset:576
	v_lshlrev_b32_e32 v218, 16, v32
	v_and_b32_e32 v219, 0xffff0000, v32
	v_mul_f32_e32 v188, v218, v218
	v_fmac_f32_e32 v188, v219, v219
	v_lshlrev_b32_e32 v218, 16, v33
	v_and_b32_e32 v219, 0xffff0000, v33
	v_fmac_f32_e32 v188, v218, v218
	v_fmac_f32_e32 v188, v219, v219
	v_lshlrev_b32_e32 v218, 16, v34
	v_and_b32_e32 v219, 0xffff0000, v34
	v_fmac_f32_e32 v188, v218, v218
	v_fmac_f32_e32 v188, v219, v219
	v_lshlrev_b32_e32 v218, 16, v35
	v_and_b32_e32 v219, 0xffff0000, v35
	v_fmac_f32_e32 v188, v218, v218
	v_fmac_f32_e32 v188, v219, v219
	v_lshlrev_b32_e32 v218, 16, v24
	v_and_b32_e32 v219, 0xffff0000, v24
	v_fmac_f32_e32 v188, v218, v218
	v_fmac_f32_e32 v188, v219, v219
	v_lshlrev_b32_e32 v218, 16, v25
	v_and_b32_e32 v219, 0xffff0000, v25
	v_fmac_f32_e32 v188, v218, v218
	v_fmac_f32_e32 v188, v219, v219
	v_lshlrev_b32_e32 v218, 16, v26
	v_and_b32_e32 v219, 0xffff0000, v26
	v_fmac_f32_e32 v188, v218, v218
	v_fmac_f32_e32 v188, v219, v219
	v_lshlrev_b32_e32 v218, 16, v27
	v_and_b32_e32 v219, 0xffff0000, v27
	v_fmac_f32_e32 v188, v218, v218
	v_fmac_f32_e32 v188, v219, v219
	global_store_dword v216, v188, s[88:89] offset:640
	v_lshlrev_b32_e32 v218, 16, v16
	v_and_b32_e32 v219, 0xffff0000, v16
	v_mul_f32_e32 v189, v218, v218
	v_fmac_f32_e32 v189, v219, v219
	v_lshlrev_b32_e32 v218, 16, v17
	v_and_b32_e32 v219, 0xffff0000, v17
	v_fmac_f32_e32 v189, v218, v218
	v_fmac_f32_e32 v189, v219, v219
	v_lshlrev_b32_e32 v218, 16, v18
	v_and_b32_e32 v219, 0xffff0000, v18
	v_fmac_f32_e32 v189, v218, v218
	v_fmac_f32_e32 v189, v219, v219
	v_lshlrev_b32_e32 v218, 16, v19
	v_and_b32_e32 v219, 0xffff0000, v19
	v_fmac_f32_e32 v189, v218, v218
	v_fmac_f32_e32 v189, v219, v219
	v_lshlrev_b32_e32 v218, 16, v8
	v_and_b32_e32 v219, 0xffff0000, v8
	v_fmac_f32_e32 v189, v218, v218
	v_fmac_f32_e32 v189, v219, v219
	v_lshlrev_b32_e32 v218, 16, v9
	v_and_b32_e32 v219, 0xffff0000, v9
	v_fmac_f32_e32 v189, v218, v218
	v_fmac_f32_e32 v189, v219, v219
	v_lshlrev_b32_e32 v218, 16, v10
	v_and_b32_e32 v219, 0xffff0000, v10
	v_fmac_f32_e32 v189, v218, v218
	v_fmac_f32_e32 v189, v219, v219
	v_lshlrev_b32_e32 v218, 16, v11
	v_and_b32_e32 v219, 0xffff0000, v11
	v_fmac_f32_e32 v189, v218, v218
	v_fmac_f32_e32 v189, v219, v219
	global_store_dword v216, v189, s[88:89] offset:704
	s_cbranch_vccz .LBB0_1655
	s_waitcnt vmcnt(0)
	s_cmpk_gt_u32 s2, 0xff
	s_cbranch_scc1 .LBB0_1670
	s_barrier

; __device__ __forceinline__ float bflo(unsigned w) { return __uint_as_float(w << 16); }
; __device__ __forceinline__ float bfhi(unsigned w) { return __uint_as_float(w & 0xffff0000u); }
; __device__ __forceinline__ float wave_sum(float v) { v = row16_sum(v); v += shx(v, 16); v += shx(v, 32); return v; }
; #define WAVE (__builtin_amdgcn_readfirstlane(opaque_tid() >> 6))
; __device__ __forceinline__ void rowstat_phase(const Frame& F, const bf16_t* __restrict__ res, float* __restrict__ rstd_out) {
;     for (int row0 = (F.bid * NWAVE + WAVE) * 4; row0 < M; row0 += F.G * NWAVE * 4) {
;         u32x4 v[4][4];
; #pragma unroll
;         for (int r = 0; r < 4; ++r)
; #pragma unroll
;             for (int i = 0; i < 4; ++i) v[r][i] = *(const u32x4*)(res + (size_t)(row0 + r) * D + LANE * 8 + i * 512);
;         float ss[4];
; #pragma unroll
;         for (int r = 0; r < 4; ++r) { ss[r] = 0.f;
; #pragma unroll
;             for (int i = 0; i < 4; ++i) { const u32x4 x = v[r][i];
;                 ss[r] += bflo(x.x) * bflo(x.x) + bfhi(x.x) * bfhi(x.x) + bflo(x.y) * bflo(x.y) + bfhi(x.y) * bfhi(x.y) + bflo(x.z) * bflo(x.z) + bfhi(x.z) * bfhi(x.z) + bflo(x.w) * bflo(x.w) + bfhi(x.w) * bfhi(x.w); }
;             ss[r] = wave_sum(ss[r]); }
;         if (LANE < 4) rstd_out[row0 + LANE] = rsqrtf((LANE == 0 ? ss[0] : LANE == 1 ? ss[1] : LANE == 2 ? ss[2] : ss[3]) * (1.f / D) + EPS);
;     }
; }
.LBB0_1781:
	s_and_b64 vcc, exec, s[0:1]
	s_cbranch_vccz .LBB0_1841
	v_readlane_b32 s4, v254, 57
	s_nop 0
	s_lshl_b32 s4, s4, 7

; __device__ __forceinline__ float bflo(unsigned w) { return __uint_as_float(w << 16); }
; __device__ __forceinline__ float bfhi(unsigned w) { return __uint_as_float(w & 0xffff0000u); }
; __device__ __forceinline__ float wave_sum(float v) { v = row16_sum(v); v += shx(v, 16); v += shx(v, 32); return v; }
; #define WAVE (__builtin_amdgcn_readfirstlane(opaque_tid() >> 6))
; __device__ __forceinline__ void xcd_barrier(const XcdBarrier& b) {
;     asm volatile("s_waitcnt vmcnt(0)" ::: "memory");
;     __syncthreads();
;     if (threadIdx.x == 0) {
;         unsigned* bar = b.bar;
;         __builtin_amdgcn_s_waitcnt(0);
;         unsigned nloc = b.st[0], nx = b.st[1];
;         if (nloc == 0u) { xcd_barrier_complete(bar, b.x, nloc, nx); b.st[0] = nloc; b.st[1] = nx; }
; __device__ __forceinline__ void rowstat_phase(const Frame& F, const bf16_t* __restrict__ res, float* __restrict__ rstd_out) {
;     for (int row0 = (F.bid * NWAVE + WAVE) * 4; row0 < M; row0 += F.G * NWAVE * 4) {
;         u32x4 v[4][4];
; #pragma unroll
;         for (int r = 0; r < 4; ++r)
; #pragma unroll
;             for (int i = 0; i < 4; ++i) v[r][i] = *(const u32x4*)(res + (size_t)(row0 + r) * D + LANE * 8 + i * 512);
;         float ss[4];
; #pragma unroll
;         for (int r = 0; r < 4; ++r) { ss[r] = 0.f;
; #pragma unroll
;             for (int i = 0; i < 4; ++i) { const u32x4 x = v[r][i];
;                 ss[r] += bflo(x.x) * bflo(x.x) + bfhi(x.x) * bfhi(x.x) + bflo(x.y) * bflo(x.y) + bfhi(x.y) * bfhi(x.y) + bflo(x.z) * bflo(x.z) + bfhi(x.z) * bfhi(x.z) + bflo(x.w) * bflo(x.w) + bfhi(x.w) * bfhi(x.w); }
;             ss[r] = wave_sum(ss[r]); }
;         if (LANE < 4) rstd_out[row0 + LANE] = rsqrtf((LANE == 0 ? ss[0] : LANE == 1 ? ss[1] : LANE == 2 ? ss[2] : ss[3]) * (1.f / D) + EPS);
;     }
; }
.Lrsp_done_c:
.LBB0_1791:
	v_readlane_b32 s4, v252, 4
	s_add_i32 s2, s73, 9
	v_readlane_b32 s5, v252, 5
	s_cmp_ge_i32 s2, s5
	s_cbranch_scc1 .LBB0_1841
	s_waitcnt vmcnt(0)
	s_waitcnt vmcnt(0) lgkmcnt(0)
	s_barrier
	s_mov_b64 s[4:5], exec
	v_readlane_b32 s6, v255, 24
	v_readlane_b32 s7, v255, 25
	s_and_b64 s[6:7], s[4:5], s[6:7]
	s_mov_b64 exec, s[6:7]
	s_cbranch_execz .LBB0_1840
	v_readlane_b32 s2, v255, 9
	s_waitcnt vmcnt(0) expcnt(0) lgkmcnt(0)
	s_nop 0
	v_mov_b32_e32 v1, s2
	ds_read_b32 v4, v1
	v_readlane_b32 s2, v255, 10
	s_waitcnt lgkmcnt(0)
	v_cmp_ne_u32_e32 vcc, 0, v4
	v_mov_b32_e32 v1, s2
	ds_read_b32 v2, v1
	s_cbranch_vccnz .LBB0_1808
	v_readlane_b32 s14, v252, 8
	v_readlane_b32 s15, v252, 9
	s_load_dwordx2 s[6:7], s[14:15], 0x4
	s_mov_b32 s20, 1
	s_waitcnt lgkmcnt(0)
	s_mul_i32 s2, s6, s84
	s_mul_i32 s2, s2, s7
	s_branch .LBB0_1796
